# GEMM K-loops: remaining DMA address adds moved to SALU (+0x80 bases in spare SGPR pairs), all LDS-DMA loads SGPR-base form
# speedup vs baseline: 1.0051x; 1.0051x over previous
.LBB0_297:
	s_add_u32 s22, s20, 0xfffc0080
	s_addc_u32 s23, s21, -1
	s_add_i32 s49, 0, 0x10000
	v_add_u32_e32 v145, s49, v142
	ds_read_b128 v[146:149], v145
	ds_read_b128 v[150:153], v145 offset:1024
	ds_read_b128 v[154:157], v145 offset:2048
	ds_read_b128 v[158:161], v145 offset:3072
	s_cmp_eq_u32 s48, 12
	s_cselect_b32 s25, s9, s23
	s_cselect_b32 s24, s44, s22
	s_cselect_b32 s23, s7, s47
	s_cselect_b32 s22, s45, s46
	s_add_i32 m0, s19, 0xc000
	ds_read_b128 v[162:165], v144
	ds_read_b128 v[166:169], v144 offset:1024
	ds_read_b128 v[170:173], v144 offset:2048
	ds_read_b128 v[174:177], v144 offset:3072
	ds_read_b128 v[190:193], v144 offset:4096
	ds_read_b128 v[194:197], v144 offset:5120
	ds_read_b128 v[198:201], v144 offset:6144
	ds_read_b128 v[202:205], v144 offset:7168
	global_load_lds_dwordx4 v138, s[20:21]
	s_add_i32 m0, s19, 0xe000
	s_nop 0
	global_load_lds_dwordx4 v140, s[20:21]
	s_waitcnt lgkmcnt(8)
	s_barrier
	s_waitcnt lgkmcnt(0)
	s_waitcnt lgkmcnt(0)
	v_mfma_f32_16x16x32_bf16 v[126:129], v[146:149], v[162:165], v[126:129]
	v_mfma_f32_16x16x32_bf16 v[118:121], v[154:157], v[162:165], v[118:121]
	v_mfma_f32_16x16x32_bf16 v[110:113], v[146:149], v[170:173], v[110:113]
	v_mfma_f32_16x16x32_bf16 v[102:105], v[154:157], v[170:173], v[102:105]
	v_mfma_f32_16x16x32_bf16 v[94:97], v[146:149], v[190:193], v[94:97]
	v_mfma_f32_16x16x32_bf16 v[86:89], v[154:157], v[190:193], v[86:89]
	v_mfma_f32_16x16x32_bf16 v[78:81], v[146:149], v[198:201], v[78:81]
	v_mfma_f32_16x16x32_bf16 v[70:73], v[154:157], v[198:201], v[70:73]
	v_mfma_f32_16x16x32_bf16 v[126:129], v[150:153], v[166:169], v[126:129]
	v_mfma_f32_16x16x32_bf16 v[118:121], v[158:161], v[166:169], v[118:121]
	v_mfma_f32_16x16x32_bf16 v[110:113], v[150:153], v[174:177], v[110:113]
	v_mfma_f32_16x16x32_bf16 v[102:105], v[158:161], v[174:177], v[102:105]
	v_mfma_f32_16x16x32_bf16 v[94:97], v[150:153], v[194:197], v[94:97]
	v_mfma_f32_16x16x32_bf16 v[86:89], v[158:161], v[194:197], v[86:89]
	v_mfma_f32_16x16x32_bf16 v[78:81], v[150:153], v[202:205], v[78:81]
	v_mfma_f32_16x16x32_bf16 v[70:73], v[158:161], v[202:205], v[70:73]
	s_barrier
	s_add_i32 s54, 0, 0x14000
	s_add_i32 s49, s49, s35
	v_add_u32_e32 v145, s54, v142
	s_add_u32 s64, s22, 0x80
	s_addc_u32 s65, s23, 0
	s_mov_b32 m0, s49
	ds_read_b128 v[206:209], v145
	ds_read_b128 v[210:213], v145 offset:1024
	ds_read_b128 v[214:217], v145 offset:2048
	ds_read_b128 v[218:221], v145 offset:3072
	global_load_lds_dwordx4 v134, s[22:23]
	s_add_i32 m0, s49, 0x2000
	s_nop 0
	global_load_lds_dwordx4 v130, s[22:23]
	s_barrier
	s_waitcnt lgkmcnt(0)
	s_waitcnt lgkmcnt(0)
	v_mfma_f32_16x16x32_bf16 v[122:125], v[206:209], v[162:165], v[122:125]
	v_mfma_f32_16x16x32_bf16 v[114:117], v[214:217], v[162:165], v[114:117]
	v_mfma_f32_16x16x32_bf16 v[106:109], v[206:209], v[170:173], v[106:109]
	v_mfma_f32_16x16x32_bf16 v[98:101], v[214:217], v[170:173], v[98:101]
	v_mfma_f32_16x16x32_bf16 v[90:93], v[206:209], v[190:193], v[90:93]
	v_mfma_f32_16x16x32_bf16 v[82:85], v[214:217], v[190:193], v[82:85]
	v_mfma_f32_16x16x32_bf16 v[74:77], v[206:209], v[198:201], v[74:77]
	v_mfma_f32_16x16x32_bf16 v[66:69], v[214:217], v[198:201], v[66:69]
	v_mfma_f32_16x16x32_bf16 v[122:125], v[210:213], v[166:169], v[122:125]
	v_mfma_f32_16x16x32_bf16 v[114:117], v[218:221], v[166:169], v[114:117]
	v_mfma_f32_16x16x32_bf16 v[106:109], v[210:213], v[174:177], v[106:109]
	v_mfma_f32_16x16x32_bf16 v[98:101], v[218:221], v[174:177], v[98:101]
	v_mfma_f32_16x16x32_bf16 v[90:93], v[210:213], v[194:197], v[90:93]
	v_mfma_f32_16x16x32_bf16 v[82:85], v[218:221], v[194:197], v[82:85]
	v_mfma_f32_16x16x32_bf16 v[74:77], v[210:213], v[202:205], v[74:77]
	v_mfma_f32_16x16x32_bf16 v[66:69], v[218:221], v[202:205], v[66:69]
	s_mov_b32 m0, s19
	s_add_u32 s62, s24, 0x80
	s_addc_u32 s63, s25, 0
	s_barrier
	ds_read_b128 v[162:165], v144 offset:16384
	ds_read_b128 v[166:169], v144 offset:17408
	ds_read_b128 v[170:173], v144 offset:18432
	ds_read_b128 v[174:177], v144 offset:19456
	ds_read_b128 v[190:193], v144 offset:20480
	ds_read_b128 v[194:197], v144 offset:21504
	ds_read_b128 v[198:201], v144 offset:22528
	ds_read_b128 v[202:205], v144 offset:23552
	global_load_lds_dwordx4 v136, s[24:25]
	s_mov_b32 m0, s36
	s_nop 0
	global_load_lds_dwordx4 v132, s[24:25]
	s_barrier
	s_waitcnt lgkmcnt(0)
	s_waitcnt lgkmcnt(0)
	v_mfma_f32_16x16x32_bf16 v[62:65], v[146:149], v[162:165], v[62:65]
	v_mfma_f32_16x16x32_bf16 v[54:57], v[154:157], v[162:165], v[54:57]
	v_mfma_f32_16x16x32_bf16 v[46:49], v[146:149], v[170:173], v[46:49]
	v_mfma_f32_16x16x32_bf16 v[38:41], v[154:157], v[170:173], v[38:41]
	v_mfma_f32_16x16x32_bf16 v[30:33], v[146:149], v[190:193], v[30:33]
	v_mfma_f32_16x16x32_bf16 v[22:25], v[154:157], v[190:193], v[22:25]
	v_mfma_f32_16x16x32_bf16 v[14:17], v[146:149], v[198:201], v[14:17]
	v_mfma_f32_16x16x32_bf16 v[6:9], v[154:157], v[198:201], v[6:9]
	v_mfma_f32_16x16x32_bf16 v[62:65], v[150:153], v[166:169], v[62:65]
	v_mfma_f32_16x16x32_bf16 v[54:57], v[158:161], v[166:169], v[54:57]
	v_mfma_f32_16x16x32_bf16 v[46:49], v[150:153], v[174:177], v[46:49]
	v_mfma_f32_16x16x32_bf16 v[38:41], v[158:161], v[174:177], v[38:41]
	v_mfma_f32_16x16x32_bf16 v[30:33], v[150:153], v[194:197], v[30:33]
	v_mfma_f32_16x16x32_bf16 v[22:25], v[158:161], v[194:197], v[22:25]
	v_mfma_f32_16x16x32_bf16 v[14:17], v[150:153], v[202:205], v[14:17]
	v_mfma_f32_16x16x32_bf16 v[6:9], v[158:161], v[202:205], v[6:9]
	s_barrier
	s_add_u32 s50, s22, 0x40000
	s_addc_u32 s51, s23, 0
	s_add_i32 s49, s54, s35
	s_mov_b32 m0, s49
	s_nop 0
	global_load_lds_dwordx4 v134, s[50:51]
	s_add_i32 m0, s49, 0x2000
	s_nop 0
	global_load_lds_dwordx4 v130, s[50:51]
	s_waitcnt vmcnt(6)
	s_barrier
	v_mfma_f32_16x16x32_bf16 v[58:61], v[206:209], v[162:165], v[58:61]
	v_mfma_f32_16x16x32_bf16 v[50:53], v[214:217], v[162:165], v[50:53]
	v_mfma_f32_16x16x32_bf16 v[42:45], v[206:209], v[170:173], v[42:45]
	v_mfma_f32_16x16x32_bf16 v[34:37], v[214:217], v[170:173], v[34:37]
	v_mfma_f32_16x16x32_bf16 v[26:29], v[206:209], v[190:193], v[26:29]
	v_mfma_f32_16x16x32_bf16 v[18:21], v[214:217], v[190:193], v[18:21]
	v_mfma_f32_16x16x32_bf16 v[10:13], v[206:209], v[198:201], v[10:13]
	v_mfma_f32_16x16x32_bf16 v[2:5], v[214:217], v[198:201], v[2:5]
	v_mfma_f32_16x16x32_bf16 v[58:61], v[210:213], v[166:169], v[58:61]
	v_mfma_f32_16x16x32_bf16 v[50:53], v[218:221], v[166:169], v[50:53]
	v_mfma_f32_16x16x32_bf16 v[42:45], v[210:213], v[174:177], v[42:45]
	v_mfma_f32_16x16x32_bf16 v[34:37], v[218:221], v[174:177], v[34:37]
	v_mfma_f32_16x16x32_bf16 v[26:29], v[210:213], v[194:197], v[26:29]
	v_mfma_f32_16x16x32_bf16 v[18:21], v[218:221], v[194:197], v[18:21]
	v_mfma_f32_16x16x32_bf16 v[10:13], v[210:213], v[202:205], v[10:13]
	v_mfma_f32_16x16x32_bf16 v[2:5], v[218:221], v[202:205], v[2:5]
	s_add_i32 s49, 0, 0x18000
	v_add_u32_e32 v145, s49, v142
	s_barrier
	ds_read_b128 v[146:149], v145
	ds_read_b128 v[150:153], v145 offset:1024
	ds_read_b128 v[154:157], v145 offset:2048
	ds_read_b128 v[158:161], v145 offset:3072
	s_add_u32 s24, s24, 0x40000
	s_addc_u32 s25, s25, 0
	s_mov_b32 m0, s37
	ds_read_b128 v[162:165], v144 offset:32768
	ds_read_b128 v[166:169], v144 offset:33792
	ds_read_b128 v[170:173], v144 offset:34816
	ds_read_b128 v[174:177], v144 offset:35840
	ds_read_b128 v[190:193], v144 offset:36864
	ds_read_b128 v[194:197], v144 offset:37888
	ds_read_b128 v[198:201], v144 offset:38912
	ds_read_b128 v[202:205], v144 offset:39936
	global_load_lds_dwordx4 v136, s[24:25]
	s_mov_b32 m0, s38
	s_nop 0
	global_load_lds_dwordx4 v132, s[24:25]
	s_waitcnt lgkmcnt(8)
	s_barrier
	s_waitcnt lgkmcnt(0)
	s_waitcnt lgkmcnt(0)
	v_mfma_f32_16x16x32_bf16 v[126:129], v[146:149], v[162:165], v[126:129]
	v_mfma_f32_16x16x32_bf16 v[118:121], v[154:157], v[162:165], v[118:121]
	v_mfma_f32_16x16x32_bf16 v[110:113], v[146:149], v[170:173], v[110:113]
	v_mfma_f32_16x16x32_bf16 v[102:105], v[154:157], v[170:173], v[102:105]
	v_mfma_f32_16x16x32_bf16 v[94:97], v[146:149], v[190:193], v[94:97]
	v_mfma_f32_16x16x32_bf16 v[86:89], v[154:157], v[190:193], v[86:89]
	v_mfma_f32_16x16x32_bf16 v[78:81], v[146:149], v[198:201], v[78:81]
	v_mfma_f32_16x16x32_bf16 v[70:73], v[154:157], v[198:201], v[70:73]
	v_mfma_f32_16x16x32_bf16 v[126:129], v[150:153], v[166:169], v[126:129]
	v_mfma_f32_16x16x32_bf16 v[118:121], v[158:161], v[166:169], v[118:121]
	v_mfma_f32_16x16x32_bf16 v[110:113], v[150:153], v[174:177], v[110:113]
	v_mfma_f32_16x16x32_bf16 v[102:105], v[158:161], v[174:177], v[102:105]
	v_mfma_f32_16x16x32_bf16 v[94:97], v[150:153], v[194:197], v[94:97]
	v_mfma_f32_16x16x32_bf16 v[86:89], v[158:161], v[194:197], v[86:89]
	v_mfma_f32_16x16x32_bf16 v[78:81], v[150:153], v[202:205], v[78:81]
	v_mfma_f32_16x16x32_bf16 v[70:73], v[158:161], v[202:205], v[70:73]
	s_barrier
	s_add_i32 s24, 0, 0x1c000
	s_add_i32 s25, s49, s35
	v_add_u32_e32 v145, s24, v142
	s_mov_b32 m0, s25
	ds_read_b128 v[206:209], v145
	ds_read_b128 v[210:213], v145 offset:1024
	ds_read_b128 v[214:217], v145 offset:2048
	ds_read_b128 v[218:221], v145 offset:3072
	global_load_lds_dwordx4 v134, s[64:65]
	s_add_i32 m0, s25, 0x2000
	s_nop 0
	global_load_lds_dwordx4 v130, s[64:65]
	s_barrier
	s_waitcnt lgkmcnt(0)
	s_waitcnt lgkmcnt(0)
	v_mfma_f32_16x16x32_bf16 v[122:125], v[206:209], v[162:165], v[122:125]
	v_mfma_f32_16x16x32_bf16 v[114:117], v[214:217], v[162:165], v[114:117]
	v_mfma_f32_16x16x32_bf16 v[106:109], v[206:209], v[170:173], v[106:109]
	v_mfma_f32_16x16x32_bf16 v[98:101], v[214:217], v[170:173], v[98:101]
	v_mfma_f32_16x16x32_bf16 v[90:93], v[206:209], v[190:193], v[90:93]
	v_mfma_f32_16x16x32_bf16 v[82:85], v[214:217], v[190:193], v[82:85]
	v_mfma_f32_16x16x32_bf16 v[74:77], v[206:209], v[198:201], v[74:77]
	v_mfma_f32_16x16x32_bf16 v[66:69], v[214:217], v[198:201], v[66:69]
	v_mfma_f32_16x16x32_bf16 v[122:125], v[210:213], v[166:169], v[122:125]
	v_mfma_f32_16x16x32_bf16 v[114:117], v[218:221], v[166:169], v[114:117]
	v_mfma_f32_16x16x32_bf16 v[106:109], v[210:213], v[174:177], v[106:109]
	v_mfma_f32_16x16x32_bf16 v[98:101], v[218:221], v[174:177], v[98:101]
	v_mfma_f32_16x16x32_bf16 v[90:93], v[210:213], v[194:197], v[90:93]
	v_mfma_f32_16x16x32_bf16 v[82:85], v[218:221], v[194:197], v[82:85]
	v_mfma_f32_16x16x32_bf16 v[74:77], v[210:213], v[202:205], v[74:77]
	v_mfma_f32_16x16x32_bf16 v[66:69], v[218:221], v[202:205], v[66:69]
	s_mov_b32 m0, s39
	s_barrier
	ds_read_b128 v[162:165], v144 offset:49152
	ds_read_b128 v[166:169], v144 offset:50176
	ds_read_b128 v[170:173], v144 offset:51200
	ds_read_b128 v[174:177], v144 offset:52224
	ds_read_b128 v[190:193], v144 offset:53248
	ds_read_b128 v[194:197], v144 offset:54272
	ds_read_b128 v[198:201], v144 offset:55296
	ds_read_b128 v[202:205], v144 offset:56320
	global_load_lds_dwordx4 v136, s[62:63]
	s_mov_b32 m0, s40
	s_nop 0
	global_load_lds_dwordx4 v132, s[62:63]
	s_barrier
	s_waitcnt lgkmcnt(0)
	s_waitcnt lgkmcnt(0)
	v_mfma_f32_16x16x32_bf16 v[62:65], v[146:149], v[162:165], v[62:65]
	v_mfma_f32_16x16x32_bf16 v[54:57], v[154:157], v[162:165], v[54:57]
	v_mfma_f32_16x16x32_bf16 v[46:49], v[146:149], v[170:173], v[46:49]
	v_mfma_f32_16x16x32_bf16 v[38:41], v[154:157], v[170:173], v[38:41]
	v_mfma_f32_16x16x32_bf16 v[30:33], v[146:149], v[190:193], v[30:33]
	v_mfma_f32_16x16x32_bf16 v[22:25], v[154:157], v[190:193], v[22:25]
	v_mfma_f32_16x16x32_bf16 v[14:17], v[146:149], v[198:201], v[14:17]
	v_mfma_f32_16x16x32_bf16 v[6:9], v[154:157], v[198:201], v[6:9]
	v_mfma_f32_16x16x32_bf16 v[62:65], v[150:153], v[166:169], v[62:65]
	v_mfma_f32_16x16x32_bf16 v[54:57], v[158:161], v[166:169], v[54:57]
	v_mfma_f32_16x16x32_bf16 v[46:49], v[150:153], v[174:177], v[46:49]
	v_mfma_f32_16x16x32_bf16 v[38:41], v[158:161], v[174:177], v[38:41]
	v_mfma_f32_16x16x32_bf16 v[30:33], v[150:153], v[194:197], v[30:33]
	v_mfma_f32_16x16x32_bf16 v[22:25], v[158:161], v[194:197], v[22:25]
	v_mfma_f32_16x16x32_bf16 v[14:17], v[150:153], v[202:205], v[14:17]
	v_mfma_f32_16x16x32_bf16 v[6:9], v[158:161], v[202:205], v[6:9]
	s_barrier
	s_add_u32 s22, s22, 0x40080
	s_addc_u32 s23, s23, 0
	s_add_i32 s24, s24, s35
	s_mov_b32 m0, s24
	s_nop 0
	global_load_lds_dwordx4 v134, s[22:23]
	s_add_i32 m0, s24, 0x2000
	s_nop 0
	global_load_lds_dwordx4 v130, s[22:23]
	s_waitcnt vmcnt(6)
	s_barrier
	v_mfma_f32_16x16x32_bf16 v[58:61], v[206:209], v[162:165], v[58:61]
	v_mfma_f32_16x16x32_bf16 v[50:53], v[214:217], v[162:165], v[50:53]
	v_mfma_f32_16x16x32_bf16 v[42:45], v[206:209], v[170:173], v[42:45]
	v_mfma_f32_16x16x32_bf16 v[34:37], v[214:217], v[170:173], v[34:37]
	v_mfma_f32_16x16x32_bf16 v[26:29], v[206:209], v[190:193], v[26:29]
	v_mfma_f32_16x16x32_bf16 v[18:21], v[214:217], v[190:193], v[18:21]
	v_mfma_f32_16x16x32_bf16 v[10:13], v[206:209], v[198:201], v[10:13]
	v_mfma_f32_16x16x32_bf16 v[2:5], v[214:217], v[198:201], v[2:5]
	v_mfma_f32_16x16x32_bf16 v[58:61], v[210:213], v[166:169], v[58:61]
	v_mfma_f32_16x16x32_bf16 v[50:53], v[218:221], v[166:169], v[50:53]
	v_mfma_f32_16x16x32_bf16 v[42:45], v[210:213], v[174:177], v[42:45]
	v_mfma_f32_16x16x32_bf16 v[34:37], v[218:221], v[174:177], v[34:37]
	v_mfma_f32_16x16x32_bf16 v[26:29], v[210:213], v[194:197], v[26:29]
	v_mfma_f32_16x16x32_bf16 v[18:21], v[218:221], v[194:197], v[18:21]
	v_mfma_f32_16x16x32_bf16 v[10:13], v[210:213], v[202:205], v[10:13]
	v_mfma_f32_16x16x32_bf16 v[2:5], v[218:221], v[202:205], v[2:5]
	s_add_i32 s48, s48, 2
	s_add_u32 s20, s20, 0x100
	s_addc_u32 s21, s21, 0
	s_add_u32 s46, s46, 0x100
	s_addc_u32 s47, s47, 0
	s_cmp_gt_u32 s48, 13
	s_barrier
	s_cbranch_scc0 .LBB0_297
	v_mul_f32_e32 v148, 0xbfb8aa3b, v126
	v_mul_f32_e32 v149, 0xbfb8aa3b, v127
	v_exp_f32_e32 v148, v148
	v_exp_f32_e32 v149, v149
	v_lshl_or_b32 v146, s43, 7, v143
	v_lshl_add_u32 v145, s18, 8, v1
	v_add_f32_e32 v148, 1.0, v148
	v_add_f32_e32 v149, 1.0, v149
	v_rcp_f32_e32 v148, v148
	v_rcp_f32_e32 v149, v149
	v_ashrrev_i32_e32 v147, 31, v146
	s_movk_i32 s7, 0x1700
	s_and_b64 vcc, exec, s[4:5]
	v_pk_mul_f32 v[126:127], v[126:127], v[148:149]
	s_mov_b32 s43, s6
	v_pk_mul_f32 v[122:123], v[126:127], v[122:123]
	v_mul_f32_e32 v126, 0xbfb8aa3b, v128
	v_mul_f32_e32 v127, 0xbfb8aa3b, v129
	v_exp_f32_e32 v126, v126
	v_exp_f32_e32 v127, v127
	s_mov_b32 s18, s8
	s_mov_b64 s[22:23], s[14:15]
	v_add_f32_e32 v126, 1.0, v126
	v_add_f32_e32 v127, 1.0, v127
	v_rcp_f32_e32 v126, v126
	v_rcp_f32_e32 v127, v127
	s_nop 0
	v_pk_mul_f32 v[126:127], v[128:129], v[126:127]
	s_nop 0
	v_pk_mul_f32 v[124:125], v[126:127], v[124:125]
	v_mul_f32_e32 v126, 0xbfb8aa3b, v118
	v_mul_f32_e32 v127, 0xbfb8aa3b, v119
	v_exp_f32_e32 v126, v126
	v_exp_f32_e32 v127, v127
	v_add_f32_e32 v126, 1.0, v126
	v_add_f32_e32 v127, 1.0, v127
	v_rcp_f32_e32 v126, v126
	v_rcp_f32_e32 v127, v127
	s_nop 0
	v_pk_mul_f32 v[118:119], v[118:119], v[126:127]
	s_nop 0
	v_pk_mul_f32 v[114:115], v[118:119], v[114:115]
	v_mul_f32_e32 v118, 0xbfb8aa3b, v120
	v_mul_f32_e32 v119, 0xbfb8aa3b, v121
	v_exp_f32_e32 v118, v118
	v_exp_f32_e32 v119, v119
	v_add_f32_e32 v118, 1.0, v118
	v_add_f32_e32 v119, 1.0, v119
	v_rcp_f32_e32 v118, v118
	v_rcp_f32_e32 v119, v119
	s_nop 0
	v_pk_mul_f32 v[118:119], v[120:121], v[118:119]
	s_nop 0
	v_pk_mul_f32 v[116:117], v[118:119], v[116:117]
	v_cvt_pk_bf16_f32 v120, v114, v115
	v_mov_b64_e32 v[114:115], s[2:3]
	v_cvt_pk_bf16_f32 v118, v122, v123
	v_cvt_pk_bf16_f32 v121, v116, v117
	v_mad_i64_i32 v[122:123], s[20:21], v145, s7, v[114:115]
	v_lshlrev_b64 v[116:117], 1, v[146:147]
	v_cvt_pk_bf16_f32 v119, v124, v125
	v_lshl_add_u64 v[122:123], v[122:123], 0, v[116:117]
	global_store_dwordx4 v[122:123], v[118:121], off
	s_nop 1
	v_mul_f32_e32 v118, 0xbfb8aa3b, v110
	v_mul_f32_e32 v119, 0xbfb8aa3b, v111
	v_exp_f32_e32 v118, v118
	v_exp_f32_e32 v119, v119
	v_add_f32_e32 v118, 1.0, v118
	v_add_f32_e32 v119, 1.0, v119
	v_rcp_f32_e32 v118, v118
	v_rcp_f32_e32 v119, v119
	s_nop 0
	v_pk_mul_f32 v[110:111], v[110:111], v[118:119]
	s_nop 0
	v_pk_mul_f32 v[106:107], v[110:111], v[106:107]
	v_mul_f32_e32 v110, 0xbfb8aa3b, v112
	v_mul_f32_e32 v111, 0xbfb8aa3b, v113
	v_exp_f32_e32 v110, v110
	v_exp_f32_e32 v111, v111
	v_add_f32_e32 v110, 1.0, v110
	v_add_f32_e32 v111, 1.0, v111
	v_rcp_f32_e32 v110, v110
	v_rcp_f32_e32 v111, v111
	s_nop 0
	v_pk_mul_f32 v[110:111], v[112:113], v[110:111]
	s_nop 0
	v_pk_mul_f32 v[108:109], v[110:111], v[108:109]
	v_mul_f32_e32 v110, 0xbfb8aa3b, v102
	v_mul_f32_e32 v111, 0xbfb8aa3b, v103
	v_exp_f32_e32 v110, v110
	v_exp_f32_e32 v111, v111
	v_add_f32_e32 v110, 1.0, v110
	v_add_f32_e32 v111, 1.0, v111
	v_rcp_f32_e32 v110, v110
	v_rcp_f32_e32 v111, v111
	s_nop 0
	v_pk_mul_f32 v[102:103], v[102:103], v[110:111]
	s_nop 0
	v_pk_mul_f32 v[102:103], v[102:103], v[98:99]
	v_mul_f32_e32 v98, 0xbfb8aa3b, v104
	v_mul_f32_e32 v99, 0xbfb8aa3b, v105
	v_exp_f32_e32 v98, v98
	v_exp_f32_e32 v99, v99
	v_add_f32_e32 v98, 1.0, v98
	v_add_f32_e32 v99, 1.0, v99
	v_rcp_f32_e32 v98, v98
	v_rcp_f32_e32 v99, v99
	s_nop 0
	v_pk_mul_f32 v[98:99], v[104:105], v[98:99]
	s_nop 0
	v_pk_mul_f32 v[104:105], v[98:99], v[100:101]
	v_cvt_pk_bf16_f32 v100, v102, v103
	v_or_b32_e32 v102, 16, v145
	v_mad_i64_i32 v[102:103], s[20:21], v102, s7, v[114:115]
	v_cvt_pk_bf16_f32 v98, v106, v107
	v_cvt_pk_bf16_f32 v99, v108, v109
	v_cvt_pk_bf16_f32 v101, v104, v105
	v_lshl_add_u64 v[102:103], v[102:103], 0, v[116:117]
	global_store_dwordx4 v[102:103], v[98:101], off
	s_nop 1
	v_mul_f32_e32 v98, 0xbfb8aa3b, v94
	v_mul_f32_e32 v99, 0xbfb8aa3b, v95
	v_exp_f32_e32 v98, v98
	v_exp_f32_e32 v99, v99
	v_add_f32_e32 v98, 1.0, v98
	v_add_f32_e32 v99, 1.0, v99
	v_rcp_f32_e32 v98, v98
	v_rcp_f32_e32 v99, v99
	s_nop 0
	v_pk_mul_f32 v[94:95], v[94:95], v[98:99]
	s_nop 0
	v_pk_mul_f32 v[90:91], v[94:95], v[90:91]
	v_mul_f32_e32 v94, 0xbfb8aa3b, v96
	v_mul_f32_e32 v95, 0xbfb8aa3b, v97
	v_exp_f32_e32 v94, v94
	v_exp_f32_e32 v95, v95
	v_add_f32_e32 v94, 1.0, v94
	v_add_f32_e32 v95, 1.0, v95
	v_rcp_f32_e32 v94, v94
	v_rcp_f32_e32 v95, v95
	s_nop 0
	v_pk_mul_f32 v[94:95], v[96:97], v[94:95]
	s_nop 0
	v_pk_mul_f32 v[92:93], v[94:95], v[92:93]
	v_mul_f32_e32 v94, 0xbfb8aa3b, v86
	v_mul_f32_e32 v95, 0xbfb8aa3b, v87
	v_exp_f32_e32 v94, v94
	v_exp_f32_e32 v95, v95
	v_add_f32_e32 v94, 1.0, v94
	v_add_f32_e32 v95, 1.0, v95
	v_rcp_f32_e32 v94, v94
	v_rcp_f32_e32 v95, v95
	s_nop 0
	v_pk_mul_f32 v[86:87], v[86:87], v[94:95]
	s_nop 0
	v_pk_mul_f32 v[86:87], v[86:87], v[82:83]
	v_mul_f32_e32 v82, 0xbfb8aa3b, v88
	v_mul_f32_e32 v83, 0xbfb8aa3b, v89
	v_exp_f32_e32 v82, v82
	v_exp_f32_e32 v83, v83
	v_add_f32_e32 v82, 1.0, v82
	v_add_f32_e32 v83, 1.0, v83
	v_rcp_f32_e32 v82, v82
	v_rcp_f32_e32 v83, v83
	s_nop 0
	v_pk_mul_f32 v[82:83], v[88:89], v[82:83]
	s_nop 0
	v_pk_mul_f32 v[88:89], v[82:83], v[84:85]
	v_cvt_pk_bf16_f32 v84, v86, v87
	v_or_b32_e32 v86, 32, v145
	v_mad_i64_i32 v[86:87], s[20:21], v86, s7, v[114:115]
	v_cvt_pk_bf16_f32 v82, v90, v91
	v_cvt_pk_bf16_f32 v83, v92, v93
	v_cvt_pk_bf16_f32 v85, v88, v89
	v_lshl_add_u64 v[86:87], v[86:87], 0, v[116:117]
	global_store_dwordx4 v[86:87], v[82:85], off
	s_nop 1
	v_mul_f32_e32 v82, 0xbfb8aa3b, v78
	v_mul_f32_e32 v83, 0xbfb8aa3b, v79
	v_exp_f32_e32 v82, v82
	v_exp_f32_e32 v83, v83
	v_add_f32_e32 v82, 1.0, v82
	v_add_f32_e32 v83, 1.0, v83
	v_rcp_f32_e32 v82, v82
	v_rcp_f32_e32 v83, v83
	s_nop 0
	v_pk_mul_f32 v[78:79], v[78:79], v[82:83]
	s_nop 0
	v_pk_mul_f32 v[74:75], v[78:79], v[74:75]
	v_mul_f32_e32 v78, 0xbfb8aa3b, v80
	v_mul_f32_e32 v79, 0xbfb8aa3b, v81
	v_exp_f32_e32 v78, v78
	v_exp_f32_e32 v79, v79
	v_add_f32_e32 v78, 1.0, v78
	v_add_f32_e32 v79, 1.0, v79
	v_rcp_f32_e32 v78, v78
	v_rcp_f32_e32 v79, v79
	s_nop 0
	v_pk_mul_f32 v[78:79], v[80:81], v[78:79]
	s_nop 0
	v_pk_mul_f32 v[76:77], v[78:79], v[76:77]
	v_mul_f32_e32 v78, 0xbfb8aa3b, v70
	v_mul_f32_e32 v79, 0xbfb8aa3b, v71
	v_exp_f32_e32 v78, v78
	v_exp_f32_e32 v79, v79
	v_add_f32_e32 v78, 1.0, v78
	v_add_f32_e32 v79, 1.0, v79
	v_rcp_f32_e32 v78, v78
	v_rcp_f32_e32 v79, v79
	s_nop 0
	v_pk_mul_f32 v[70:71], v[70:71], v[78:79]
	s_nop 0
	v_pk_mul_f32 v[70:71], v[70:71], v[66:67]
	v_mul_f32_e32 v66, 0xbfb8aa3b, v72
	v_mul_f32_e32 v67, 0xbfb8aa3b, v73
	v_exp_f32_e32 v66, v66
	v_exp_f32_e32 v67, v67
	v_add_f32_e32 v66, 1.0, v66
	v_add_f32_e32 v67, 1.0, v67
	v_rcp_f32_e32 v66, v66
	v_rcp_f32_e32 v67, v67
	s_nop 0
	v_pk_mul_f32 v[66:67], v[72:73], v[66:67]
	s_nop 0
	v_pk_mul_f32 v[72:73], v[66:67], v[68:69]
	v_cvt_pk_bf16_f32 v68, v70, v71
	v_or_b32_e32 v70, 48, v145
	v_mad_i64_i32 v[70:71], s[20:21], v70, s7, v[114:115]
	v_cvt_pk_bf16_f32 v66, v74, v75
	v_cvt_pk_bf16_f32 v67, v76, v77
	v_cvt_pk_bf16_f32 v69, v72, v73
	v_lshl_add_u64 v[70:71], v[70:71], 0, v[116:117]
	global_store_dwordx4 v[70:71], v[66:69], off
	s_nop 1
	v_mul_f32_e32 v66, 0xbfb8aa3b, v62
	v_mul_f32_e32 v67, 0xbfb8aa3b, v63
	v_exp_f32_e32 v66, v66
	v_exp_f32_e32 v67, v67
	v_add_u32_e32 v68, 0x80, v145
	v_add_f32_e32 v66, 1.0, v66
	v_add_f32_e32 v67, 1.0, v67
	v_rcp_f32_e32 v66, v66
	v_rcp_f32_e32 v67, v67
	s_nop 0
	v_pk_mul_f32 v[62:63], v[62:63], v[66:67]
	s_nop 0
	v_pk_mul_f32 v[58:59], v[62:63], v[58:59]
	v_mul_f32_e32 v62, 0xbfb8aa3b, v64
	v_mul_f32_e32 v63, 0xbfb8aa3b, v65
	v_exp_f32_e32 v62, v62
	v_exp_f32_e32 v63, v63
	v_add_f32_e32 v62, 1.0, v62
	v_add_f32_e32 v63, 1.0, v63
	v_rcp_f32_e32 v62, v62
	v_rcp_f32_e32 v63, v63
	s_nop 0
	v_pk_mul_f32 v[62:63], v[64:65], v[62:63]
	s_nop 0
	v_pk_mul_f32 v[60:61], v[62:63], v[60:61]
	v_mul_f32_e32 v62, 0xbfb8aa3b, v54
	v_mul_f32_e32 v63, 0xbfb8aa3b, v55
	v_exp_f32_e32 v62, v62
	v_exp_f32_e32 v63, v63
	v_add_f32_e32 v62, 1.0, v62
	v_add_f32_e32 v63, 1.0, v63
	v_rcp_f32_e32 v62, v62
	v_rcp_f32_e32 v63, v63
	s_nop 0
	v_pk_mul_f32 v[54:55], v[54:55], v[62:63]
	s_nop 0
	v_pk_mul_f32 v[54:55], v[54:55], v[50:51]
	v_mul_f32_e32 v50, 0xbfb8aa3b, v56
	v_mul_f32_e32 v51, 0xbfb8aa3b, v57
	v_exp_f32_e32 v50, v50
	v_exp_f32_e32 v51, v51
	v_add_f32_e32 v50, 1.0, v50
	v_add_f32_e32 v51, 1.0, v51
	v_rcp_f32_e32 v50, v50
	v_rcp_f32_e32 v51, v51
	s_nop 0
	v_pk_mul_f32 v[50:51], v[56:57], v[50:51]
	s_nop 0
	v_pk_mul_f32 v[56:57], v[50:51], v[52:53]
	v_cvt_pk_bf16_f32 v52, v54, v55
	v_mad_i64_i32 v[54:55], s[20:21], v68, s7, v[114:115]
	v_cvt_pk_bf16_f32 v50, v58, v59
	v_cvt_pk_bf16_f32 v51, v60, v61
	v_cvt_pk_bf16_f32 v53, v56, v57
	v_lshl_add_u64 v[54:55], v[54:55], 0, v[116:117]
	global_store_dwordx4 v[54:55], v[50:53], off
	s_nop 1
	v_mul_f32_e32 v50, 0xbfb8aa3b, v46
	v_mul_f32_e32 v51, 0xbfb8aa3b, v47
	v_exp_f32_e32 v50, v50
	v_exp_f32_e32 v51, v51
	v_add_f32_e32 v50, 1.0, v50
	v_add_f32_e32 v51, 1.0, v51
	v_rcp_f32_e32 v50, v50
	v_rcp_f32_e32 v51, v51
	s_nop 0
	v_pk_mul_f32 v[46:47], v[46:47], v[50:51]
	s_nop 0
	v_pk_mul_f32 v[42:43], v[46:47], v[42:43]
	v_mul_f32_e32 v46, 0xbfb8aa3b, v48
	v_mul_f32_e32 v47, 0xbfb8aa3b, v49
	v_exp_f32_e32 v46, v46
	v_exp_f32_e32 v47, v47
	v_add_f32_e32 v46, 1.0, v46
	v_add_f32_e32 v47, 1.0, v47
	v_rcp_f32_e32 v46, v46
	v_rcp_f32_e32 v47, v47
	s_nop 0
	v_pk_mul_f32 v[46:47], v[48:49], v[46:47]
	s_nop 0
	v_pk_mul_f32 v[44:45], v[46:47], v[44:45]
	v_mul_f32_e32 v46, 0xbfb8aa3b, v38
	v_mul_f32_e32 v47, 0xbfb8aa3b, v39
	v_exp_f32_e32 v46, v46
	v_exp_f32_e32 v47, v47
	v_add_f32_e32 v46, 1.0, v46
	v_add_f32_e32 v47, 1.0, v47
	v_rcp_f32_e32 v46, v46
	v_rcp_f32_e32 v47, v47
	s_nop 0
	v_pk_mul_f32 v[38:39], v[38:39], v[46:47]
	s_nop 0
	v_pk_mul_f32 v[38:39], v[38:39], v[34:35]
	v_mul_f32_e32 v34, 0xbfb8aa3b, v40
	v_mul_f32_e32 v35, 0xbfb8aa3b, v41
	v_exp_f32_e32 v34, v34
	v_exp_f32_e32 v35, v35
	v_add_f32_e32 v34, 1.0, v34
	v_add_f32_e32 v35, 1.0, v35
	v_rcp_f32_e32 v34, v34
	v_rcp_f32_e32 v35, v35
	s_nop 0
	v_pk_mul_f32 v[34:35], v[40:41], v[34:35]
	s_nop 0
	v_pk_mul_f32 v[40:41], v[34:35], v[36:37]
	v_cvt_pk_bf16_f32 v36, v38, v39
	v_add_u32_e32 v38, 0x90, v145
	v_mad_i64_i32 v[38:39], s[20:21], v38, s7, v[114:115]
	v_cvt_pk_bf16_f32 v34, v42, v43
	v_cvt_pk_bf16_f32 v35, v44, v45
	v_cvt_pk_bf16_f32 v37, v40, v41
	v_lshl_add_u64 v[38:39], v[38:39], 0, v[116:117]
	global_store_dwordx4 v[38:39], v[34:37], off
	s_nop 1
	v_mul_f32_e32 v34, 0xbfb8aa3b, v30
	v_mul_f32_e32 v35, 0xbfb8aa3b, v31
	v_exp_f32_e32 v34, v34
	v_exp_f32_e32 v35, v35
	v_add_f32_e32 v34, 1.0, v34
	v_add_f32_e32 v35, 1.0, v35
	v_rcp_f32_e32 v34, v34
	v_rcp_f32_e32 v35, v35
	s_nop 0
	v_pk_mul_f32 v[30:31], v[30:31], v[34:35]
	s_nop 0
	v_pk_mul_f32 v[26:27], v[30:31], v[26:27]
	v_mul_f32_e32 v30, 0xbfb8aa3b, v32
	v_mul_f32_e32 v31, 0xbfb8aa3b, v33
	v_exp_f32_e32 v30, v30
	v_exp_f32_e32 v31, v31
	v_add_f32_e32 v30, 1.0, v30
	v_add_f32_e32 v31, 1.0, v31
	v_rcp_f32_e32 v30, v30
	v_rcp_f32_e32 v31, v31
	s_nop 0
	v_pk_mul_f32 v[30:31], v[32:33], v[30:31]
	s_nop 0
	v_pk_mul_f32 v[28:29], v[30:31], v[28:29]
	v_mul_f32_e32 v30, 0xbfb8aa3b, v22
	v_mul_f32_e32 v31, 0xbfb8aa3b, v23
	v_exp_f32_e32 v30, v30
	v_exp_f32_e32 v31, v31
	v_add_f32_e32 v30, 1.0, v30
	v_add_f32_e32 v31, 1.0, v31
	v_rcp_f32_e32 v30, v30
	v_rcp_f32_e32 v31, v31
	s_nop 0
	v_pk_mul_f32 v[22:23], v[22:23], v[30:31]
	s_nop 0
	v_pk_mul_f32 v[22:23], v[22:23], v[18:19]
	v_mul_f32_e32 v18, 0xbfb8aa3b, v24
	v_mul_f32_e32 v19, 0xbfb8aa3b, v25
	v_exp_f32_e32 v18, v18
	v_exp_f32_e32 v19, v19
	v_add_f32_e32 v18, 1.0, v18
	v_add_f32_e32 v19, 1.0, v19
	v_rcp_f32_e32 v18, v18
	v_rcp_f32_e32 v19, v19
	s_nop 0
	v_pk_mul_f32 v[18:19], v[24:25], v[18:19]
	s_nop 0
	v_pk_mul_f32 v[24:25], v[18:19], v[20:21]
	v_cvt_pk_bf16_f32 v20, v22, v23
	v_add_u32_e32 v22, 0xa0, v145
	v_mad_i64_i32 v[22:23], s[20:21], v22, s7, v[114:115]
	v_cvt_pk_bf16_f32 v18, v26, v27
	v_cvt_pk_bf16_f32 v19, v28, v29
	v_cvt_pk_bf16_f32 v21, v24, v25
	v_lshl_add_u64 v[22:23], v[22:23], 0, v[116:117]
	global_store_dwordx4 v[22:23], v[18:21], off
	s_nop 1
	v_mul_f32_e32 v18, 0xbfb8aa3b, v14
	v_mul_f32_e32 v19, 0xbfb8aa3b, v15
	v_exp_f32_e32 v18, v18
	v_exp_f32_e32 v19, v19
	v_add_f32_e32 v18, 1.0, v18
	v_add_f32_e32 v19, 1.0, v19
	v_rcp_f32_e32 v18, v18
	v_rcp_f32_e32 v19, v19
	s_nop 0
	v_pk_mul_f32 v[14:15], v[14:15], v[18:19]
	s_nop 0
	v_pk_mul_f32 v[10:11], v[14:15], v[10:11]
	v_mul_f32_e32 v14, 0xbfb8aa3b, v16
	v_mul_f32_e32 v15, 0xbfb8aa3b, v17
	v_exp_f32_e32 v14, v14
	v_exp_f32_e32 v15, v15
	v_add_f32_e32 v14, 1.0, v14
	v_add_f32_e32 v15, 1.0, v15
	v_rcp_f32_e32 v14, v14
	v_rcp_f32_e32 v15, v15
	s_nop 0
	v_pk_mul_f32 v[14:15], v[16:17], v[14:15]
	s_nop 0
	v_pk_mul_f32 v[12:13], v[14:15], v[12:13]
	v_mul_f32_e32 v14, 0xbfb8aa3b, v6
	v_mul_f32_e32 v15, 0xbfb8aa3b, v7
	v_exp_f32_e32 v14, v14
	v_exp_f32_e32 v15, v15
	v_add_f32_e32 v14, 1.0, v14
	v_add_f32_e32 v15, 1.0, v15
	v_rcp_f32_e32 v14, v14
	v_rcp_f32_e32 v15, v15
	s_nop 0
	v_pk_mul_f32 v[6:7], v[6:7], v[14:15]
	s_nop 0
	v_pk_mul_f32 v[6:7], v[6:7], v[2:3]
	v_mul_f32_e32 v2, 0xbfb8aa3b, v8
	v_mul_f32_e32 v3, 0xbfb8aa3b, v9
	v_exp_f32_e32 v2, v2
	v_exp_f32_e32 v3, v3
	v_add_f32_e32 v2, 1.0, v2
	v_add_f32_e32 v3, 1.0, v3
	v_rcp_f32_e32 v2, v2
	v_rcp_f32_e32 v3, v3
	s_nop 0
	v_pk_mul_f32 v[2:3], v[8:9], v[2:3]
	s_nop 0
	v_pk_mul_f32 v[8:9], v[2:3], v[4:5]
	v_cvt_pk_bf16_f32 v4, v6, v7
	v_add_u32_e32 v6, 0xb0, v145
	v_mad_i64_i32 v[6:7], s[20:21], v6, s7, v[114:115]
	v_cvt_pk_bf16_f32 v2, v10, v11
	v_cvt_pk_bf16_f32 v3, v12, v13
	v_cvt_pk_bf16_f32 v5, v8, v9
	v_lshl_add_u64 v[6:7], v[6:7], 0, v[116:117]
	s_mov_b64 s[20:21], s[12:13]
	global_store_dwordx4 v[6:7], v[2:5], off
	s_cbranch_vccz .LBB0_294
	s_waitcnt vmcnt(0)
	s_cmpk_gt_u32 s28, 0xff
	s_cbranch_scc1 .LBB0_301
	s_barrier

.LBB0_374:
	s_add_u32 s16, s14, 0x100
	s_addc_u32 s17, s15, 0
	s_add_i32 s49, 0, 0x10000
	v_add_u32_e32 v154, s49, v164
	ds_read_b128 v[142:145], v154
	ds_read_b128 v[146:149], v154 offset:1024
	ds_read_b128 v[150:153], v154 offset:2048
	ds_read_b128 v[154:157], v154 offset:3072
	s_cmp_eq_u32 s48, 40
	s_cselect_b32 s21, s7, s17
	s_cselect_b32 s20, s6, s16
	s_cselect_b32 s19, s9, s47
	s_cselect_b32 s18, s8, s46
	v_lshl_add_u64 v[162:163], s[14:15], 0, v[138:139]
	s_add_i32 m0, s35, 0xc000
	ds_read_b128 v[158:161], v166
	ds_read_b128 v[168:171], v166 offset:1024
	ds_read_b128 v[172:175], v166 offset:2048
	ds_read_b128 v[190:193], v166 offset:3072
	ds_read_b128 v[194:197], v166 offset:4096
	ds_read_b128 v[198:201], v166 offset:5120
	ds_read_b128 v[202:205], v166 offset:6144
	ds_read_b128 v[206:209], v166 offset:7168
	global_load_lds_dwordx4 v[162:163], off
	v_lshl_add_u64 v[162:163], s[14:15], 0, v[140:141]
	s_add_i32 m0, s35, 0xe000
	s_nop 0
	global_load_lds_dwordx4 v[162:163], off
	s_waitcnt lgkmcnt(8)
	s_barrier
	s_waitcnt lgkmcnt(0)
	s_waitcnt lgkmcnt(0)
	v_mfma_f32_16x16x32_bf16 v[126:129], v[142:145], v[158:161], v[126:129]
	v_mfma_f32_16x16x32_bf16 v[122:125], v[150:153], v[158:161], v[122:125]
	v_mfma_f32_16x16x32_bf16 v[110:113], v[142:145], v[172:175], v[110:113]
	v_mfma_f32_16x16x32_bf16 v[106:109], v[150:153], v[172:175], v[106:109]
	v_mfma_f32_16x16x32_bf16 v[94:97], v[142:145], v[194:197], v[94:97]
	v_mfma_f32_16x16x32_bf16 v[90:93], v[150:153], v[194:197], v[90:93]
	v_mfma_f32_16x16x32_bf16 v[78:81], v[142:145], v[202:205], v[78:81]
	v_mfma_f32_16x16x32_bf16 v[74:77], v[150:153], v[202:205], v[74:77]
	v_mfma_f32_16x16x32_bf16 v[126:129], v[146:149], v[168:171], v[126:129]
	v_mfma_f32_16x16x32_bf16 v[122:125], v[154:157], v[168:171], v[122:125]
	v_mfma_f32_16x16x32_bf16 v[110:113], v[146:149], v[190:193], v[110:113]
	v_mfma_f32_16x16x32_bf16 v[106:109], v[154:157], v[190:193], v[106:109]
	v_mfma_f32_16x16x32_bf16 v[94:97], v[146:149], v[198:201], v[94:97]
	v_mfma_f32_16x16x32_bf16 v[90:93], v[154:157], v[198:201], v[90:93]
	v_mfma_f32_16x16x32_bf16 v[78:81], v[146:149], v[206:209], v[78:81]
	v_mfma_f32_16x16x32_bf16 v[74:77], v[154:157], v[206:209], v[74:77]
	s_barrier
	s_add_i32 s50, 0, 0x14000
	v_add_u32_e32 v162, s50, v164
	s_add_i32 s14, s49, s34
	ds_read_b128 v[210:213], v162
	ds_read_b128 v[214:217], v162 offset:1024
	ds_read_b128 v[218:221], v162 offset:2048
	ds_read_b128 v[222:225], v162 offset:3072
	s_add_u32 s64, s18, 0x80
	s_addc_u32 s65, s19, 0
	s_mov_b32 m0, s14
	s_nop 0
	global_load_lds_dwordx4 v132, s[18:19]
	s_add_i32 m0, s14, 0x2000
	s_nop 0
	global_load_lds_dwordx4 v136, s[18:19]
	s_barrier
	s_waitcnt lgkmcnt(0)
	s_waitcnt lgkmcnt(0)
	v_mfma_f32_16x16x32_bf16 v[118:121], v[210:213], v[158:161], v[118:121]
	v_mfma_f32_16x16x32_bf16 v[114:117], v[218:221], v[158:161], v[114:117]
	v_mfma_f32_16x16x32_bf16 v[102:105], v[210:213], v[172:175], v[102:105]
	v_mfma_f32_16x16x32_bf16 v[98:101], v[218:221], v[172:175], v[98:101]
	v_mfma_f32_16x16x32_bf16 v[86:89], v[210:213], v[194:197], v[86:89]
	v_mfma_f32_16x16x32_bf16 v[82:85], v[218:221], v[194:197], v[82:85]
	v_mfma_f32_16x16x32_bf16 v[70:73], v[210:213], v[202:205], v[70:73]
	v_mfma_f32_16x16x32_bf16 v[66:69], v[218:221], v[202:205], v[66:69]
	v_mfma_f32_16x16x32_bf16 v[118:121], v[214:217], v[168:171], v[118:121]
	v_mfma_f32_16x16x32_bf16 v[114:117], v[222:225], v[168:171], v[114:117]
	v_mfma_f32_16x16x32_bf16 v[102:105], v[214:217], v[190:193], v[102:105]
	v_mfma_f32_16x16x32_bf16 v[98:101], v[222:225], v[190:193], v[98:101]
	v_mfma_f32_16x16x32_bf16 v[86:89], v[214:217], v[198:201], v[86:89]
	v_mfma_f32_16x16x32_bf16 v[82:85], v[222:225], v[198:201], v[82:85]
	v_mfma_f32_16x16x32_bf16 v[70:73], v[214:217], v[206:209], v[70:73]
	v_mfma_f32_16x16x32_bf16 v[66:69], v[222:225], v[206:209], v[66:69]
	s_mov_b32 m0, s35
	s_add_u32 s62, s20, 0x80
	s_addc_u32 s63, s21, 0
	s_barrier
	ds_read_b128 v[158:161], v166 offset:16384
	ds_read_b128 v[168:171], v166 offset:17408
	ds_read_b128 v[172:175], v166 offset:18432
	ds_read_b128 v[190:193], v166 offset:19456
	ds_read_b128 v[194:197], v166 offset:20480
	ds_read_b128 v[198:201], v166 offset:21504
	ds_read_b128 v[202:205], v166 offset:22528
	ds_read_b128 v[206:209], v166 offset:23552
	global_load_lds_dwordx4 v130, s[20:21]
	s_mov_b32 m0, s36
	s_nop 0
	global_load_lds_dwordx4 v134, s[20:21]
	s_barrier
	s_waitcnt lgkmcnt(0)
	s_waitcnt lgkmcnt(0)
	v_mfma_f32_16x16x32_bf16 v[62:65], v[142:145], v[158:161], v[62:65]
	v_mfma_f32_16x16x32_bf16 v[58:61], v[150:153], v[158:161], v[58:61]
	v_mfma_f32_16x16x32_bf16 v[46:49], v[142:145], v[172:175], v[46:49]
	v_mfma_f32_16x16x32_bf16 v[42:45], v[150:153], v[172:175], v[42:45]
	v_mfma_f32_16x16x32_bf16 v[30:33], v[142:145], v[194:197], v[30:33]
	v_mfma_f32_16x16x32_bf16 v[26:29], v[150:153], v[194:197], v[26:29]
	v_mfma_f32_16x16x32_bf16 v[14:17], v[142:145], v[202:205], v[14:17]
	v_mfma_f32_16x16x32_bf16 v[10:13], v[150:153], v[202:205], v[10:13]
	v_mfma_f32_16x16x32_bf16 v[62:65], v[146:149], v[168:171], v[62:65]
	v_mfma_f32_16x16x32_bf16 v[58:61], v[154:157], v[168:171], v[58:61]
	v_mfma_f32_16x16x32_bf16 v[46:49], v[146:149], v[190:193], v[46:49]
	v_mfma_f32_16x16x32_bf16 v[42:45], v[154:157], v[190:193], v[42:45]
	v_mfma_f32_16x16x32_bf16 v[30:33], v[146:149], v[198:201], v[30:33]
	v_mfma_f32_16x16x32_bf16 v[26:29], v[154:157], v[198:201], v[26:29]
	v_mfma_f32_16x16x32_bf16 v[14:17], v[146:149], v[206:209], v[14:17]
	v_mfma_f32_16x16x32_bf16 v[10:13], v[154:157], v[206:209], v[10:13]
	s_barrier
	s_add_u32 s14, s18, 0xb0000
	s_addc_u32 s15, s19, 0
	s_add_i32 s49, s50, s34
	s_mov_b32 m0, s49
	s_nop 0
	global_load_lds_dwordx4 v132, s[14:15]
	s_add_i32 m0, s49, 0x2000
	s_nop 0
	global_load_lds_dwordx4 v136, s[14:15]
	s_waitcnt vmcnt(6)
	s_barrier
	v_mfma_f32_16x16x32_bf16 v[54:57], v[210:213], v[158:161], v[54:57]
	v_mfma_f32_16x16x32_bf16 v[50:53], v[218:221], v[158:161], v[50:53]
	v_mfma_f32_16x16x32_bf16 v[38:41], v[210:213], v[172:175], v[38:41]
	v_mfma_f32_16x16x32_bf16 v[34:37], v[218:221], v[172:175], v[34:37]
	v_mfma_f32_16x16x32_bf16 v[22:25], v[210:213], v[194:197], v[22:25]
	v_mfma_f32_16x16x32_bf16 v[18:21], v[218:221], v[194:197], v[18:21]
	v_mfma_f32_16x16x32_bf16 v[6:9], v[210:213], v[202:205], v[6:9]
	v_mfma_f32_16x16x32_bf16 v[2:5], v[218:221], v[202:205], v[2:5]
	v_mfma_f32_16x16x32_bf16 v[54:57], v[214:217], v[168:171], v[54:57]
	v_mfma_f32_16x16x32_bf16 v[50:53], v[222:225], v[168:171], v[50:53]
	v_mfma_f32_16x16x32_bf16 v[38:41], v[214:217], v[190:193], v[38:41]
	v_mfma_f32_16x16x32_bf16 v[34:37], v[222:225], v[190:193], v[34:37]
	v_mfma_f32_16x16x32_bf16 v[22:25], v[214:217], v[198:201], v[22:25]
	v_mfma_f32_16x16x32_bf16 v[18:21], v[222:225], v[198:201], v[18:21]
	v_mfma_f32_16x16x32_bf16 v[6:9], v[214:217], v[206:209], v[6:9]
	v_mfma_f32_16x16x32_bf16 v[2:5], v[222:225], v[206:209], v[2:5]
	s_add_i32 s49, 0, 0x18000
	v_add_u32_e32 v154, s49, v164
	s_barrier
	ds_read_b128 v[142:145], v154
	ds_read_b128 v[146:149], v154 offset:1024
	ds_read_b128 v[150:153], v154 offset:2048
	ds_read_b128 v[154:157], v154 offset:3072
	s_add_u32 s14, s20, 0xb8000
	s_addc_u32 s15, s21, 0
	s_mov_b32 m0, s37
	ds_read_b128 v[158:161], v166 offset:32768
	ds_read_b128 v[168:171], v166 offset:33792
	ds_read_b128 v[172:175], v166 offset:34816
	ds_read_b128 v[190:193], v166 offset:35840
	ds_read_b128 v[194:197], v166 offset:36864
	ds_read_b128 v[198:201], v166 offset:37888
	ds_read_b128 v[202:205], v166 offset:38912
	ds_read_b128 v[206:209], v166 offset:39936
	global_load_lds_dwordx4 v130, s[14:15]
	s_mov_b32 m0, s38
	s_nop 0
	global_load_lds_dwordx4 v134, s[14:15]
	s_waitcnt lgkmcnt(8)
	s_barrier
	s_waitcnt lgkmcnt(0)
	s_waitcnt lgkmcnt(0)
	v_mfma_f32_16x16x32_bf16 v[126:129], v[142:145], v[158:161], v[126:129]
	v_mfma_f32_16x16x32_bf16 v[122:125], v[150:153], v[158:161], v[122:125]
	v_mfma_f32_16x16x32_bf16 v[110:113], v[142:145], v[172:175], v[110:113]
	v_mfma_f32_16x16x32_bf16 v[106:109], v[150:153], v[172:175], v[106:109]
	v_mfma_f32_16x16x32_bf16 v[94:97], v[142:145], v[194:197], v[94:97]
	v_mfma_f32_16x16x32_bf16 v[90:93], v[150:153], v[194:197], v[90:93]
	v_mfma_f32_16x16x32_bf16 v[78:81], v[142:145], v[202:205], v[78:81]
	v_mfma_f32_16x16x32_bf16 v[74:77], v[150:153], v[202:205], v[74:77]
	v_mfma_f32_16x16x32_bf16 v[126:129], v[146:149], v[168:171], v[126:129]
	v_mfma_f32_16x16x32_bf16 v[122:125], v[154:157], v[168:171], v[122:125]
	v_mfma_f32_16x16x32_bf16 v[110:113], v[146:149], v[190:193], v[110:113]
	v_mfma_f32_16x16x32_bf16 v[106:109], v[154:157], v[190:193], v[106:109]
	v_mfma_f32_16x16x32_bf16 v[94:97], v[146:149], v[198:201], v[94:97]
	v_mfma_f32_16x16x32_bf16 v[90:93], v[154:157], v[198:201], v[90:93]
	v_mfma_f32_16x16x32_bf16 v[78:81], v[146:149], v[206:209], v[78:81]
	v_mfma_f32_16x16x32_bf16 v[74:77], v[154:157], v[206:209], v[74:77]
	s_barrier
	s_add_i32 s20, 0, 0x1c000
	s_add_i32 s14, s49, s34
	v_add_u32_e32 v167, s20, v164
	s_mov_b32 m0, s14
	ds_read_b128 v[210:213], v167
	ds_read_b128 v[214:217], v167 offset:1024
	ds_read_b128 v[218:221], v167 offset:2048
	ds_read_b128 v[222:225], v167 offset:3072
	global_load_lds_dwordx4 v132, s[64:65]
	s_add_i32 m0, s14, 0x2000
	s_nop 0
	global_load_lds_dwordx4 v136, s[64:65]
	s_barrier
	s_waitcnt lgkmcnt(0)
	s_waitcnt lgkmcnt(0)
	v_mfma_f32_16x16x32_bf16 v[118:121], v[210:213], v[158:161], v[118:121]
	v_mfma_f32_16x16x32_bf16 v[114:117], v[218:221], v[158:161], v[114:117]
	v_mfma_f32_16x16x32_bf16 v[102:105], v[210:213], v[172:175], v[102:105]
	v_mfma_f32_16x16x32_bf16 v[98:101], v[218:221], v[172:175], v[98:101]
	v_mfma_f32_16x16x32_bf16 v[86:89], v[210:213], v[194:197], v[86:89]
	v_mfma_f32_16x16x32_bf16 v[82:85], v[218:221], v[194:197], v[82:85]
	v_mfma_f32_16x16x32_bf16 v[70:73], v[210:213], v[202:205], v[70:73]
	v_mfma_f32_16x16x32_bf16 v[66:69], v[218:221], v[202:205], v[66:69]
	v_mfma_f32_16x16x32_bf16 v[118:121], v[214:217], v[168:171], v[118:121]
	v_mfma_f32_16x16x32_bf16 v[114:117], v[222:225], v[168:171], v[114:117]
	v_mfma_f32_16x16x32_bf16 v[102:105], v[214:217], v[190:193], v[102:105]
	v_mfma_f32_16x16x32_bf16 v[98:101], v[222:225], v[190:193], v[98:101]
	v_mfma_f32_16x16x32_bf16 v[86:89], v[214:217], v[198:201], v[86:89]
	v_mfma_f32_16x16x32_bf16 v[82:85], v[222:225], v[198:201], v[82:85]
	v_mfma_f32_16x16x32_bf16 v[70:73], v[214:217], v[206:209], v[70:73]
	v_mfma_f32_16x16x32_bf16 v[66:69], v[222:225], v[206:209], v[66:69]
	s_mov_b32 m0, s39
	s_barrier
	ds_read_b128 v[158:161], v166 offset:49152
	ds_read_b128 v[168:171], v166 offset:50176
	ds_read_b128 v[172:175], v166 offset:51200
	ds_read_b128 v[190:193], v166 offset:52224
	ds_read_b128 v[194:197], v166 offset:53248
	ds_read_b128 v[198:201], v166 offset:54272
	ds_read_b128 v[202:205], v166 offset:55296
	ds_read_b128 v[206:209], v166 offset:56320
	global_load_lds_dwordx4 v130, s[62:63]
	s_mov_b32 m0, s40
	s_nop 0
	global_load_lds_dwordx4 v134, s[62:63]
	s_barrier
	s_waitcnt lgkmcnt(0)
	s_waitcnt lgkmcnt(0)
	v_mfma_f32_16x16x32_bf16 v[62:65], v[142:145], v[158:161], v[62:65]
	v_mfma_f32_16x16x32_bf16 v[58:61], v[150:153], v[158:161], v[58:61]
	v_mfma_f32_16x16x32_bf16 v[46:49], v[142:145], v[172:175], v[46:49]
	v_mfma_f32_16x16x32_bf16 v[42:45], v[150:153], v[172:175], v[42:45]
	v_mfma_f32_16x16x32_bf16 v[30:33], v[142:145], v[194:197], v[30:33]
	v_mfma_f32_16x16x32_bf16 v[26:29], v[150:153], v[194:197], v[26:29]
	v_mfma_f32_16x16x32_bf16 v[14:17], v[142:145], v[202:205], v[14:17]
	v_mfma_f32_16x16x32_bf16 v[10:13], v[150:153], v[202:205], v[10:13]
	v_mfma_f32_16x16x32_bf16 v[62:65], v[146:149], v[168:171], v[62:65]
	v_mfma_f32_16x16x32_bf16 v[58:61], v[154:157], v[168:171], v[58:61]
	v_mfma_f32_16x16x32_bf16 v[46:49], v[146:149], v[190:193], v[46:49]
	v_mfma_f32_16x16x32_bf16 v[42:45], v[154:157], v[190:193], v[42:45]
	v_mfma_f32_16x16x32_bf16 v[30:33], v[146:149], v[198:201], v[30:33]
	v_mfma_f32_16x16x32_bf16 v[26:29], v[154:157], v[198:201], v[26:29]
	v_mfma_f32_16x16x32_bf16 v[14:17], v[146:149], v[206:209], v[14:17]
	v_mfma_f32_16x16x32_bf16 v[10:13], v[154:157], v[206:209], v[10:13]
	s_barrier
	s_add_u32 s14, s18, 0xb0080
	s_addc_u32 s15, s19, 0
	s_add_i32 s18, s20, s34
	s_mov_b32 m0, s18
	s_nop 0
	global_load_lds_dwordx4 v132, s[14:15]
	s_add_i32 m0, s18, 0x2000
	s_nop 0
	global_load_lds_dwordx4 v136, s[14:15]
	s_waitcnt vmcnt(6)
	s_barrier
	v_mfma_f32_16x16x32_bf16 v[54:57], v[210:213], v[158:161], v[54:57]
	v_mfma_f32_16x16x32_bf16 v[50:53], v[218:221], v[158:161], v[50:53]
	v_mfma_f32_16x16x32_bf16 v[38:41], v[210:213], v[172:175], v[38:41]
	v_mfma_f32_16x16x32_bf16 v[34:37], v[218:221], v[172:175], v[34:37]
	v_mfma_f32_16x16x32_bf16 v[22:25], v[210:213], v[194:197], v[22:25]
	v_mfma_f32_16x16x32_bf16 v[18:21], v[218:221], v[194:197], v[18:21]
	v_mfma_f32_16x16x32_bf16 v[6:9], v[210:213], v[202:205], v[6:9]
	v_mfma_f32_16x16x32_bf16 v[2:5], v[218:221], v[202:205], v[2:5]
	v_mfma_f32_16x16x32_bf16 v[54:57], v[214:217], v[168:171], v[54:57]
	v_mfma_f32_16x16x32_bf16 v[50:53], v[222:225], v[168:171], v[50:53]
	v_mfma_f32_16x16x32_bf16 v[38:41], v[214:217], v[190:193], v[38:41]
	v_mfma_f32_16x16x32_bf16 v[34:37], v[222:225], v[190:193], v[34:37]
	v_mfma_f32_16x16x32_bf16 v[22:25], v[214:217], v[198:201], v[22:25]
	v_mfma_f32_16x16x32_bf16 v[18:21], v[222:225], v[198:201], v[18:21]
	v_mfma_f32_16x16x32_bf16 v[6:9], v[214:217], v[206:209], v[6:9]
	v_mfma_f32_16x16x32_bf16 v[2:5], v[222:225], v[206:209], v[2:5]
	s_add_i32 s48, s48, 2
	s_add_u32 s46, s46, 0x100
	s_addc_u32 s47, s47, 0
	s_cmp_gt_u32 s48, 41
	s_mov_b64 s[14:15], s[16:17]
	s_barrier
	s_cbranch_scc0 .LBB0_374
	s_ashr_i32 s14, s33, 5
	s_mul_hi_i32 s15, s14, 0x9000
	s_mul_i32 s14, s14, 0x9000
	v_lshl_or_b32 v158, s45, 8, v165
	s_add_u32 s14, s26, s14
	s_addc_u32 s15, s27, s15
	v_ashrrev_i32_e32 v159, 31, v158
	v_lshl_add_u64 v[160:161], v[158:159], 2, s[14:15]
	global_load_dwordx4 v[142:145], v[160:161], off offset:16
	global_load_dwordx4 v[146:149], v[160:161], off
	v_lshl_add_u32 v162, s33, 8, v1
	v_ashrrev_i32_e32 v163, 31, v162
	s_mov_b64 s[14:15], 0x80000
	s_and_b64 vcc, exec, s[4:5]
	s_mov_b32 s45, s43
	s_mov_b32 s33, s44
	s_mov_b64 s[16:17], s[8:9]
	s_waitcnt vmcnt(0)
	v_pk_add_f32 v[144:145], v[144:145], 1.0 op_sel_hi:[1,0]
	v_pk_add_f32 v[148:149], v[148:149], 1.0 op_sel_hi:[1,0]
	v_pk_add_f32 v[146:147], v[146:147], 1.0 op_sel_hi:[1,0]
	v_pk_add_f32 v[142:143], v[142:143], 1.0 op_sel_hi:[1,0]
	v_pk_mul_f32 v[152:153], v[148:149], 0.5 op_sel_hi:[1,0]
	v_pk_mul_f32 v[156:157], v[146:147], 0.5 op_sel_hi:[1,0]
	v_pk_mul_f32 v[150:151], v[144:145], 0.5 op_sel_hi:[1,0]
	v_pk_mul_f32 v[154:155], v[142:143], 0.5 op_sel_hi:[1,0]
	global_load_dwordx4 v[142:145], v[160:161], off offset:528
	global_load_dwordx4 v[146:149], v[160:161], off offset:512
	s_waitcnt vmcnt(0)
	v_pk_add_f32 v[144:145], v[144:145], 1.0 op_sel_hi:[1,0]
	v_pk_add_f32 v[148:149], v[148:149], 1.0 op_sel_hi:[1,0]
	v_pk_add_f32 v[160:161], v[146:147], 1.0 op_sel_hi:[1,0]
	v_pk_mul_f32 v[146:147], v[148:149], 0.5 op_sel_hi:[1,0]
	v_pk_mul_f32 v[148:149], v[160:161], 0.5 op_sel_hi:[1,0]
	v_pk_add_f32 v[160:161], v[142:143], 1.0 op_sel_hi:[1,0]
	v_pk_mul_f32 v[142:143], v[144:145], 0.5 op_sel_hi:[1,0]
	v_pk_mul_f32 v[144:145], v[160:161], 0.5 op_sel_hi:[1,0]
	v_lshlrev_b64 v[160:161], 12, v[162:163]
	v_lshl_add_u64 v[168:169], s[12:13], 0, v[160:161]
	v_lshlrev_b64 v[160:161], 1, v[158:159]
	v_lshl_add_u64 v[158:159], v[168:169], 0, v[160:161]
	global_load_dwordx4 v[168:171], v[158:159], off offset:2048
	s_waitcnt vmcnt(0)
	v_lshlrev_b32_e32 v172, 16, v168
	v_and_b32_e32 v173, 0xffff0000, v168
	v_lshlrev_b32_e32 v168, 16, v169
	v_and_b32_e32 v169, 0xffff0000, v169
	v_pk_fma_f32 v[128:129], v[128:129], v[152:153], v[168:169]
	v_lshlrev_b32_e32 v168, 16, v170
	v_and_b32_e32 v169, 0xffff0000, v170
	v_pk_fma_f32 v[168:169], v[122:123], v[154:155], v[168:169]
	v_lshlrev_b32_e32 v122, 16, v171
	v_and_b32_e32 v123, 0xffff0000, v171
	v_pk_fma_f32 v[126:127], v[126:127], v[156:157], v[172:173]
	v_pk_fma_f32 v[170:171], v[124:125], v[150:151], v[122:123]
	v_cvt_pk_bf16_f32 v122, v126, v127
	v_cvt_pk_bf16_f32 v123, v128, v129
	v_cvt_pk_bf16_f32 v124, v168, v169
	v_cvt_pk_bf16_f32 v125, v170, v171
	global_store_dwordx4 v[158:159], v[122:125], off offset:2048
	global_load_dwordx4 v[122:125], v[158:159], off offset:2304
	s_waitcnt vmcnt(0)
	v_lshlrev_b32_e32 v126, 16, v122
	v_and_b32_e32 v127, 0xffff0000, v122
	v_lshlrev_b32_e32 v122, 16, v123
	v_and_b32_e32 v123, 0xffff0000, v123
	v_pk_fma_f32 v[120:121], v[120:121], v[146:147], v[122:123]
	v_lshlrev_b32_e32 v122, 16, v124
	v_and_b32_e32 v123, 0xffff0000, v124
	v_pk_fma_f32 v[122:123], v[114:115], v[144:145], v[122:123]
	v_lshlrev_b32_e32 v114, 16, v125
	v_and_b32_e32 v115, 0xffff0000, v125
	v_pk_fma_f32 v[118:119], v[118:119], v[148:149], v[126:127]
	v_pk_fma_f32 v[124:125], v[116:117], v[142:143], v[114:115]
	v_cvt_pk_bf16_f32 v114, v118, v119
	v_cvt_pk_bf16_f32 v115, v120, v121
	v_cvt_pk_bf16_f32 v116, v122, v123
	v_cvt_pk_bf16_f32 v117, v124, v125
	global_store_dwordx4 v[158:159], v[114:117], off offset:2304
	s_nop 1
	v_or_b32_e32 v114, 16, v162
	v_ashrrev_i32_e32 v115, 31, v114
	v_lshlrev_b64 v[114:115], 12, v[114:115]
	v_lshl_add_u64 v[114:115], s[12:13], 0, v[114:115]
	v_lshl_add_u64 v[118:119], v[114:115], 0, v[160:161]
	global_load_dwordx4 v[114:117], v[118:119], off offset:2048
	s_waitcnt vmcnt(0)
	v_lshlrev_b32_e32 v120, 16, v114
	v_and_b32_e32 v121, 0xffff0000, v114
	v_lshlrev_b32_e32 v114, 16, v115
	v_and_b32_e32 v115, 0xffff0000, v115
	v_pk_fma_f32 v[112:113], v[112:113], v[152:153], v[114:115]
	v_lshlrev_b32_e32 v114, 16, v116
	v_and_b32_e32 v115, 0xffff0000, v116
	v_pk_fma_f32 v[114:115], v[106:107], v[154:155], v[114:115]
	v_lshlrev_b32_e32 v106, 16, v117
	v_and_b32_e32 v107, 0xffff0000, v117
	v_pk_fma_f32 v[110:111], v[110:111], v[156:157], v[120:121]
	v_pk_fma_f32 v[116:117], v[108:109], v[150:151], v[106:107]
	v_cvt_pk_bf16_f32 v106, v110, v111
	v_cvt_pk_bf16_f32 v107, v112, v113
	v_cvt_pk_bf16_f32 v108, v114, v115
	v_cvt_pk_bf16_f32 v109, v116, v117
	global_store_dwordx4 v[118:119], v[106:109], off offset:2048
	global_load_dwordx4 v[106:109], v[118:119], off offset:2304
	s_waitcnt vmcnt(0)
	v_lshlrev_b32_e32 v110, 16, v106
	v_and_b32_e32 v111, 0xffff0000, v106
	v_lshlrev_b32_e32 v106, 16, v107
	v_and_b32_e32 v107, 0xffff0000, v107
	v_pk_fma_f32 v[104:105], v[104:105], v[146:147], v[106:107]
	v_lshlrev_b32_e32 v106, 16, v108
	v_and_b32_e32 v107, 0xffff0000, v108
	v_pk_fma_f32 v[106:107], v[98:99], v[144:145], v[106:107]
	v_lshlrev_b32_e32 v98, 16, v109
	v_and_b32_e32 v99, 0xffff0000, v109
	v_pk_fma_f32 v[102:103], v[102:103], v[148:149], v[110:111]
	v_pk_fma_f32 v[108:109], v[100:101], v[142:143], v[98:99]
	v_cvt_pk_bf16_f32 v98, v102, v103
	v_cvt_pk_bf16_f32 v99, v104, v105
	v_cvt_pk_bf16_f32 v100, v106, v107
	v_cvt_pk_bf16_f32 v101, v108, v109
	global_store_dwordx4 v[118:119], v[98:101], off offset:2304
	s_nop 1
	v_or_b32_e32 v98, 32, v162
	v_ashrrev_i32_e32 v99, 31, v98
	v_lshlrev_b64 v[98:99], 12, v[98:99]
	v_lshl_add_u64 v[98:99], s[12:13], 0, v[98:99]
	v_lshl_add_u64 v[102:103], v[98:99], 0, v[160:161]
	global_load_dwordx4 v[98:101], v[102:103], off offset:2048
	s_waitcnt vmcnt(0)
	v_lshlrev_b32_e32 v104, 16, v98
	v_and_b32_e32 v105, 0xffff0000, v98
	v_lshlrev_b32_e32 v98, 16, v99
	v_and_b32_e32 v99, 0xffff0000, v99
	v_pk_fma_f32 v[96:97], v[96:97], v[152:153], v[98:99]
	v_lshlrev_b32_e32 v98, 16, v100
	v_and_b32_e32 v99, 0xffff0000, v100
	v_pk_fma_f32 v[98:99], v[90:91], v[154:155], v[98:99]
	v_lshlrev_b32_e32 v90, 16, v101
	v_and_b32_e32 v91, 0xffff0000, v101
	v_pk_fma_f32 v[94:95], v[94:95], v[156:157], v[104:105]
	v_pk_fma_f32 v[100:101], v[92:93], v[150:151], v[90:91]
	v_cvt_pk_bf16_f32 v90, v94, v95
	v_cvt_pk_bf16_f32 v91, v96, v97
	v_cvt_pk_bf16_f32 v92, v98, v99
	v_cvt_pk_bf16_f32 v93, v100, v101
	global_store_dwordx4 v[102:103], v[90:93], off offset:2048
	global_load_dwordx4 v[90:93], v[102:103], off offset:2304
	s_waitcnt vmcnt(0)
	v_lshlrev_b32_e32 v94, 16, v90
	v_and_b32_e32 v95, 0xffff0000, v90
	v_lshlrev_b32_e32 v90, 16, v91
	v_and_b32_e32 v91, 0xffff0000, v91
	v_pk_fma_f32 v[88:89], v[88:89], v[146:147], v[90:91]
	v_lshlrev_b32_e32 v90, 16, v92
	v_and_b32_e32 v91, 0xffff0000, v92
	v_pk_fma_f32 v[90:91], v[82:83], v[144:145], v[90:91]
	v_lshlrev_b32_e32 v82, 16, v93
	v_and_b32_e32 v83, 0xffff0000, v93
	v_pk_fma_f32 v[86:87], v[86:87], v[148:149], v[94:95]
	v_pk_fma_f32 v[92:93], v[84:85], v[142:143], v[82:83]
	v_cvt_pk_bf16_f32 v82, v86, v87
	v_cvt_pk_bf16_f32 v83, v88, v89
	v_cvt_pk_bf16_f32 v84, v90, v91
	v_cvt_pk_bf16_f32 v85, v92, v93
	global_store_dwordx4 v[102:103], v[82:85], off offset:2304
	s_nop 1
	v_or_b32_e32 v82, 48, v162
	v_ashrrev_i32_e32 v83, 31, v82
	v_lshlrev_b64 v[82:83], 12, v[82:83]
	v_lshl_add_u64 v[82:83], s[12:13], 0, v[82:83]
	v_lshl_add_u64 v[82:83], v[82:83], 0, v[160:161]
	global_load_dwordx4 v[84:87], v[82:83], off offset:2048
	s_waitcnt vmcnt(0)
	v_lshlrev_b32_e32 v88, 16, v84
	v_and_b32_e32 v89, 0xffff0000, v84
	v_lshlrev_b32_e32 v84, 16, v85
	v_and_b32_e32 v85, 0xffff0000, v85
	v_pk_fma_f32 v[80:81], v[80:81], v[152:153], v[84:85]
	v_lshlrev_b32_e32 v84, 16, v86
	v_and_b32_e32 v85, 0xffff0000, v86
	v_pk_fma_f32 v[84:85], v[74:75], v[154:155], v[84:85]
	v_lshlrev_b32_e32 v74, 16, v87
	v_and_b32_e32 v75, 0xffff0000, v87
	v_pk_fma_f32 v[78:79], v[78:79], v[156:157], v[88:89]
	v_pk_fma_f32 v[86:87], v[76:77], v[150:151], v[74:75]
	v_cvt_pk_bf16_f32 v74, v78, v79
	v_cvt_pk_bf16_f32 v75, v80, v81
	v_cvt_pk_bf16_f32 v76, v84, v85
	v_cvt_pk_bf16_f32 v77, v86, v87
	global_store_dwordx4 v[82:83], v[74:77], off offset:2048
	global_load_dwordx4 v[74:77], v[82:83], off offset:2304
	s_waitcnt vmcnt(0)
	v_lshlrev_b32_e32 v78, 16, v74
	v_and_b32_e32 v79, 0xffff0000, v74
	v_lshlrev_b32_e32 v74, 16, v75
	v_and_b32_e32 v75, 0xffff0000, v75
	v_pk_fma_f32 v[72:73], v[72:73], v[146:147], v[74:75]
	v_lshlrev_b32_e32 v74, 16, v76
	v_and_b32_e32 v75, 0xffff0000, v76
	v_pk_fma_f32 v[74:75], v[66:67], v[144:145], v[74:75]
	v_lshlrev_b32_e32 v66, 16, v77
	v_and_b32_e32 v67, 0xffff0000, v77
	v_pk_fma_f32 v[70:71], v[70:71], v[148:149], v[78:79]
	v_pk_fma_f32 v[76:77], v[68:69], v[142:143], v[66:67]
	v_cvt_pk_bf16_f32 v66, v70, v71
	v_cvt_pk_bf16_f32 v67, v72, v73
	v_cvt_pk_bf16_f32 v68, v74, v75
	v_cvt_pk_bf16_f32 v69, v76, v77
	v_lshl_add_u64 v[70:71], v[158:159], 0, s[14:15]
	global_store_dwordx4 v[82:83], v[66:69], off offset:2304
	global_load_dwordx4 v[66:69], v[70:71], off offset:2048
	s_mov_b64 s[14:15], 0x90000
	s_waitcnt vmcnt(0)
	v_lshlrev_b32_e32 v72, 16, v66
	v_and_b32_e32 v73, 0xffff0000, v66
	v_lshlrev_b32_e32 v66, 16, v67
	v_and_b32_e32 v67, 0xffff0000, v67
	v_pk_fma_f32 v[64:65], v[64:65], v[152:153], v[66:67]
	v_lshlrev_b32_e32 v66, 16, v68
	v_and_b32_e32 v67, 0xffff0000, v68
	v_pk_fma_f32 v[66:67], v[58:59], v[154:155], v[66:67]
	v_lshlrev_b32_e32 v58, 16, v69
	v_and_b32_e32 v59, 0xffff0000, v69
	v_pk_fma_f32 v[62:63], v[62:63], v[156:157], v[72:73]
	v_pk_fma_f32 v[68:69], v[60:61], v[150:151], v[58:59]
	v_cvt_pk_bf16_f32 v58, v62, v63
	v_cvt_pk_bf16_f32 v59, v64, v65
	v_cvt_pk_bf16_f32 v60, v66, v67
	v_cvt_pk_bf16_f32 v61, v68, v69
	global_store_dwordx4 v[70:71], v[58:61], off offset:2048
	global_load_dwordx4 v[58:61], v[70:71], off offset:2304
	s_waitcnt vmcnt(0)
	v_lshlrev_b32_e32 v62, 16, v58
	v_and_b32_e32 v63, 0xffff0000, v58
	v_lshlrev_b32_e32 v58, 16, v59
	v_and_b32_e32 v59, 0xffff0000, v59
	v_pk_fma_f32 v[56:57], v[56:57], v[146:147], v[58:59]
	v_lshlrev_b32_e32 v58, 16, v60
	v_and_b32_e32 v59, 0xffff0000, v60
	v_pk_fma_f32 v[58:59], v[50:51], v[144:145], v[58:59]
	v_lshlrev_b32_e32 v50, 16, v61
	v_and_b32_e32 v51, 0xffff0000, v61
	v_pk_fma_f32 v[54:55], v[54:55], v[148:149], v[62:63]
	v_pk_fma_f32 v[60:61], v[52:53], v[142:143], v[50:51]
	v_cvt_pk_bf16_f32 v50, v54, v55
	v_cvt_pk_bf16_f32 v51, v56, v57
	v_cvt_pk_bf16_f32 v52, v58, v59
	v_cvt_pk_bf16_f32 v53, v60, v61
	v_lshl_add_u64 v[54:55], v[158:159], 0, s[14:15]
	global_store_dwordx4 v[70:71], v[50:53], off offset:2304
	global_load_dwordx4 v[50:53], v[54:55], off offset:2048
	s_mov_b64 s[14:15], 0xa0000
	s_waitcnt vmcnt(0)
	v_lshlrev_b32_e32 v56, 16, v50
	v_and_b32_e32 v57, 0xffff0000, v50
	v_lshlrev_b32_e32 v50, 16, v51
	v_and_b32_e32 v51, 0xffff0000, v51
	v_pk_fma_f32 v[48:49], v[48:49], v[152:153], v[50:51]
	v_lshlrev_b32_e32 v50, 16, v52
	v_and_b32_e32 v51, 0xffff0000, v52
	v_pk_fma_f32 v[50:51], v[42:43], v[154:155], v[50:51]
	v_lshlrev_b32_e32 v42, 16, v53
	v_and_b32_e32 v43, 0xffff0000, v53
	v_pk_fma_f32 v[46:47], v[46:47], v[156:157], v[56:57]
	v_pk_fma_f32 v[52:53], v[44:45], v[150:151], v[42:43]
	v_cvt_pk_bf16_f32 v42, v46, v47
	v_cvt_pk_bf16_f32 v43, v48, v49
	v_cvt_pk_bf16_f32 v44, v50, v51
	v_cvt_pk_bf16_f32 v45, v52, v53
	global_store_dwordx4 v[54:55], v[42:45], off offset:2048
	global_load_dwordx4 v[42:45], v[54:55], off offset:2304
	s_waitcnt vmcnt(0)
	v_lshlrev_b32_e32 v46, 16, v42
	v_and_b32_e32 v47, 0xffff0000, v42
	v_lshlrev_b32_e32 v42, 16, v43
	v_and_b32_e32 v43, 0xffff0000, v43
	v_pk_fma_f32 v[40:41], v[40:41], v[146:147], v[42:43]
	v_lshlrev_b32_e32 v42, 16, v44
	v_and_b32_e32 v43, 0xffff0000, v44
	v_pk_fma_f32 v[42:43], v[34:35], v[144:145], v[42:43]
	v_lshlrev_b32_e32 v34, 16, v45
	v_and_b32_e32 v35, 0xffff0000, v45
	v_pk_fma_f32 v[38:39], v[38:39], v[148:149], v[46:47]
	v_pk_fma_f32 v[44:45], v[36:37], v[142:143], v[34:35]
	v_cvt_pk_bf16_f32 v34, v38, v39
	v_cvt_pk_bf16_f32 v35, v40, v41
	v_cvt_pk_bf16_f32 v36, v42, v43
	v_cvt_pk_bf16_f32 v37, v44, v45
	v_lshl_add_u64 v[38:39], v[158:159], 0, s[14:15]
	global_store_dwordx4 v[54:55], v[34:37], off offset:2304
	global_load_dwordx4 v[34:37], v[38:39], off offset:2048
	s_mov_b64 s[14:15], 0xb0000
	s_waitcnt vmcnt(0)
	v_lshlrev_b32_e32 v40, 16, v34
	v_and_b32_e32 v41, 0xffff0000, v34
	v_lshlrev_b32_e32 v34, 16, v35
	v_and_b32_e32 v35, 0xffff0000, v35
	v_pk_fma_f32 v[32:33], v[32:33], v[152:153], v[34:35]
	v_lshlrev_b32_e32 v34, 16, v36
	v_and_b32_e32 v35, 0xffff0000, v36
	v_pk_fma_f32 v[34:35], v[26:27], v[154:155], v[34:35]
	v_lshlrev_b32_e32 v26, 16, v37
	v_and_b32_e32 v27, 0xffff0000, v37
	v_pk_fma_f32 v[30:31], v[30:31], v[156:157], v[40:41]
	v_pk_fma_f32 v[36:37], v[28:29], v[150:151], v[26:27]
	v_cvt_pk_bf16_f32 v26, v30, v31
	v_cvt_pk_bf16_f32 v27, v32, v33
	v_cvt_pk_bf16_f32 v28, v34, v35
	v_cvt_pk_bf16_f32 v29, v36, v37
	global_store_dwordx4 v[38:39], v[26:29], off offset:2048
	global_load_dwordx4 v[26:29], v[38:39], off offset:2304
	s_waitcnt vmcnt(0)
	v_lshlrev_b32_e32 v30, 16, v26
	v_and_b32_e32 v31, 0xffff0000, v26
	v_lshlrev_b32_e32 v26, 16, v27
	v_and_b32_e32 v27, 0xffff0000, v27
	v_pk_fma_f32 v[24:25], v[24:25], v[146:147], v[26:27]
	v_lshlrev_b32_e32 v26, 16, v28
	v_and_b32_e32 v27, 0xffff0000, v28
	v_pk_fma_f32 v[26:27], v[18:19], v[144:145], v[26:27]
	v_lshlrev_b32_e32 v18, 16, v29
	v_and_b32_e32 v19, 0xffff0000, v29
	v_pk_fma_f32 v[22:23], v[22:23], v[148:149], v[30:31]
	v_pk_fma_f32 v[28:29], v[20:21], v[142:143], v[18:19]
	v_cvt_pk_bf16_f32 v18, v22, v23
	v_cvt_pk_bf16_f32 v19, v24, v25
	v_cvt_pk_bf16_f32 v20, v26, v27
	v_cvt_pk_bf16_f32 v21, v28, v29
	global_store_dwordx4 v[38:39], v[18:21], off offset:2304
	s_nop 1
	v_lshl_add_u64 v[18:19], v[158:159], 0, s[14:15]
	global_load_dwordx4 v[20:23], v[18:19], off offset:2048
	s_mov_b64 s[14:15], s[6:7]
	s_waitcnt vmcnt(0)
	v_lshlrev_b32_e32 v24, 16, v20
	v_and_b32_e32 v25, 0xffff0000, v20
	v_lshlrev_b32_e32 v20, 16, v21
	v_and_b32_e32 v21, 0xffff0000, v21
	v_pk_fma_f32 v[16:17], v[16:17], v[152:153], v[20:21]
	v_lshlrev_b32_e32 v20, 16, v22
	v_and_b32_e32 v21, 0xffff0000, v22
	v_pk_fma_f32 v[20:21], v[10:11], v[154:155], v[20:21]
	v_lshlrev_b32_e32 v10, 16, v23
	v_and_b32_e32 v11, 0xffff0000, v23
	v_pk_fma_f32 v[14:15], v[14:15], v[156:157], v[24:25]
	v_pk_fma_f32 v[22:23], v[12:13], v[150:151], v[10:11]
	v_cvt_pk_bf16_f32 v10, v14, v15
	v_cvt_pk_bf16_f32 v11, v16, v17
	v_cvt_pk_bf16_f32 v12, v20, v21
	v_cvt_pk_bf16_f32 v13, v22, v23
	global_store_dwordx4 v[18:19], v[10:13], off offset:2048
	global_load_dwordx4 v[10:13], v[18:19], off offset:2304
	s_waitcnt vmcnt(0)
	v_lshlrev_b32_e32 v14, 16, v10
	v_and_b32_e32 v15, 0xffff0000, v10
	v_lshlrev_b32_e32 v10, 16, v11
	v_and_b32_e32 v11, 0xffff0000, v11
	v_pk_fma_f32 v[8:9], v[8:9], v[146:147], v[10:11]
	v_lshlrev_b32_e32 v10, 16, v12
	v_and_b32_e32 v11, 0xffff0000, v12
	v_pk_fma_f32 v[10:11], v[2:3], v[144:145], v[10:11]
	v_lshlrev_b32_e32 v2, 16, v13
	v_and_b32_e32 v3, 0xffff0000, v13
	v_pk_fma_f32 v[6:7], v[6:7], v[148:149], v[14:15]
	v_pk_fma_f32 v[12:13], v[4:5], v[142:143], v[2:3]
	v_cvt_pk_bf16_f32 v2, v6, v7
	v_cvt_pk_bf16_f32 v3, v8, v9
	v_cvt_pk_bf16_f32 v4, v10, v11
	v_cvt_pk_bf16_f32 v5, v12, v13
	global_store_dwordx4 v[18:19], v[2:5], off offset:2304
	s_cbranch_vccz .LBB0_363
	s_waitcnt vmcnt(0)
	s_cmpk_gt_u32 s30, 0xff
	s_cbranch_scc1 .LBB0_378
	s_barrier

.LBB0_400:
	s_add_u32 s16, s14, 0x100
	s_addc_u32 s17, s15, 0
	s_add_i32 s49, 0, 0x10000
	v_add_u32_e32 v154, s49, v164
	ds_read_b128 v[142:145], v154
	ds_read_b128 v[146:149], v154 offset:1024
	ds_read_b128 v[150:153], v154 offset:2048
	ds_read_b128 v[154:157], v154 offset:3072
	s_cmp_eq_u32 s48, 40
	s_cselect_b32 s21, s7, s17
	s_cselect_b32 s20, s6, s16
	s_cselect_b32 s19, s9, s47
	s_cselect_b32 s18, s8, s46
	v_lshl_add_u64 v[162:163], s[14:15], 0, v[138:139]
	s_add_i32 m0, s34, 0xc000
	ds_read_b128 v[158:161], v166
	ds_read_b128 v[168:171], v166 offset:1024
	ds_read_b128 v[172:175], v166 offset:2048
	ds_read_b128 v[190:193], v166 offset:3072
	ds_read_b128 v[194:197], v166 offset:4096
	ds_read_b128 v[198:201], v166 offset:5120
	ds_read_b128 v[202:205], v166 offset:6144
	ds_read_b128 v[206:209], v166 offset:7168
	global_load_lds_dwordx4 v[162:163], off
	v_lshl_add_u64 v[162:163], s[14:15], 0, v[140:141]
	s_add_i32 m0, s34, 0xe000
	s_nop 0
	global_load_lds_dwordx4 v[162:163], off
	s_waitcnt lgkmcnt(8)
	s_barrier
	s_waitcnt lgkmcnt(0)
	s_waitcnt lgkmcnt(0)
	v_mfma_f32_16x16x32_bf16 v[126:129], v[142:145], v[158:161], v[126:129]
	v_mfma_f32_16x16x32_bf16 v[122:125], v[150:153], v[158:161], v[122:125]
	v_mfma_f32_16x16x32_bf16 v[110:113], v[142:145], v[172:175], v[110:113]
	v_mfma_f32_16x16x32_bf16 v[106:109], v[150:153], v[172:175], v[106:109]
	v_mfma_f32_16x16x32_bf16 v[94:97], v[142:145], v[194:197], v[94:97]
	v_mfma_f32_16x16x32_bf16 v[90:93], v[150:153], v[194:197], v[90:93]
	v_mfma_f32_16x16x32_bf16 v[78:81], v[142:145], v[202:205], v[78:81]
	v_mfma_f32_16x16x32_bf16 v[74:77], v[150:153], v[202:205], v[74:77]
	v_mfma_f32_16x16x32_bf16 v[126:129], v[146:149], v[168:171], v[126:129]
	v_mfma_f32_16x16x32_bf16 v[122:125], v[154:157], v[168:171], v[122:125]
	v_mfma_f32_16x16x32_bf16 v[110:113], v[146:149], v[190:193], v[110:113]
	v_mfma_f32_16x16x32_bf16 v[106:109], v[154:157], v[190:193], v[106:109]
	v_mfma_f32_16x16x32_bf16 v[94:97], v[146:149], v[198:201], v[94:97]
	v_mfma_f32_16x16x32_bf16 v[90:93], v[154:157], v[198:201], v[90:93]
	v_mfma_f32_16x16x32_bf16 v[78:81], v[146:149], v[206:209], v[78:81]
	v_mfma_f32_16x16x32_bf16 v[74:77], v[154:157], v[206:209], v[74:77]
	s_barrier
	s_add_i32 s50, 0, 0x14000
	v_add_u32_e32 v162, s50, v164
	s_add_i32 s14, s49, s33
	ds_read_b128 v[210:213], v162
	ds_read_b128 v[214:217], v162 offset:1024
	ds_read_b128 v[218:221], v162 offset:2048
	ds_read_b128 v[222:225], v162 offset:3072
	s_add_u32 s64, s18, 0x80
	s_addc_u32 s65, s19, 0
	s_mov_b32 m0, s14
	s_nop 0
	global_load_lds_dwordx4 v132, s[18:19]
	s_add_i32 m0, s14, 0x2000
	s_nop 0
	global_load_lds_dwordx4 v136, s[18:19]
	s_barrier
	s_waitcnt lgkmcnt(0)
	s_waitcnt lgkmcnt(0)
	v_mfma_f32_16x16x32_bf16 v[118:121], v[210:213], v[158:161], v[118:121]
	v_mfma_f32_16x16x32_bf16 v[114:117], v[218:221], v[158:161], v[114:117]
	v_mfma_f32_16x16x32_bf16 v[102:105], v[210:213], v[172:175], v[102:105]
	v_mfma_f32_16x16x32_bf16 v[98:101], v[218:221], v[172:175], v[98:101]
	v_mfma_f32_16x16x32_bf16 v[86:89], v[210:213], v[194:197], v[86:89]
	v_mfma_f32_16x16x32_bf16 v[82:85], v[218:221], v[194:197], v[82:85]
	v_mfma_f32_16x16x32_bf16 v[70:73], v[210:213], v[202:205], v[70:73]
	v_mfma_f32_16x16x32_bf16 v[66:69], v[218:221], v[202:205], v[66:69]
	v_mfma_f32_16x16x32_bf16 v[118:121], v[214:217], v[168:171], v[118:121]
	v_mfma_f32_16x16x32_bf16 v[114:117], v[222:225], v[168:171], v[114:117]
	v_mfma_f32_16x16x32_bf16 v[102:105], v[214:217], v[190:193], v[102:105]
	v_mfma_f32_16x16x32_bf16 v[98:101], v[222:225], v[190:193], v[98:101]
	v_mfma_f32_16x16x32_bf16 v[86:89], v[214:217], v[198:201], v[86:89]
	v_mfma_f32_16x16x32_bf16 v[82:85], v[222:225], v[198:201], v[82:85]
	v_mfma_f32_16x16x32_bf16 v[70:73], v[214:217], v[206:209], v[70:73]
	v_mfma_f32_16x16x32_bf16 v[66:69], v[222:225], v[206:209], v[66:69]
	s_mov_b32 m0, s34
	s_add_u32 s62, s20, 0x80
	s_addc_u32 s63, s21, 0
	s_barrier
	ds_read_b128 v[158:161], v166 offset:16384
	ds_read_b128 v[168:171], v166 offset:17408
	ds_read_b128 v[172:175], v166 offset:18432
	ds_read_b128 v[190:193], v166 offset:19456
	ds_read_b128 v[194:197], v166 offset:20480
	ds_read_b128 v[198:201], v166 offset:21504
	ds_read_b128 v[202:205], v166 offset:22528
	ds_read_b128 v[206:209], v166 offset:23552
	global_load_lds_dwordx4 v130, s[20:21]
	s_mov_b32 m0, s35
	s_nop 0
	global_load_lds_dwordx4 v134, s[20:21]
	s_barrier
	s_waitcnt lgkmcnt(0)
	s_waitcnt lgkmcnt(0)
	v_mfma_f32_16x16x32_bf16 v[62:65], v[142:145], v[158:161], v[62:65]
	v_mfma_f32_16x16x32_bf16 v[58:61], v[150:153], v[158:161], v[58:61]
	v_mfma_f32_16x16x32_bf16 v[46:49], v[142:145], v[172:175], v[46:49]
	v_mfma_f32_16x16x32_bf16 v[42:45], v[150:153], v[172:175], v[42:45]
	v_mfma_f32_16x16x32_bf16 v[30:33], v[142:145], v[194:197], v[30:33]
	v_mfma_f32_16x16x32_bf16 v[26:29], v[150:153], v[194:197], v[26:29]
	v_mfma_f32_16x16x32_bf16 v[14:17], v[142:145], v[202:205], v[14:17]
	v_mfma_f32_16x16x32_bf16 v[10:13], v[150:153], v[202:205], v[10:13]
	v_mfma_f32_16x16x32_bf16 v[62:65], v[146:149], v[168:171], v[62:65]
	v_mfma_f32_16x16x32_bf16 v[58:61], v[154:157], v[168:171], v[58:61]
	v_mfma_f32_16x16x32_bf16 v[46:49], v[146:149], v[190:193], v[46:49]
	v_mfma_f32_16x16x32_bf16 v[42:45], v[154:157], v[190:193], v[42:45]
	v_mfma_f32_16x16x32_bf16 v[30:33], v[146:149], v[198:201], v[30:33]
	v_mfma_f32_16x16x32_bf16 v[26:29], v[154:157], v[198:201], v[26:29]
	v_mfma_f32_16x16x32_bf16 v[14:17], v[146:149], v[206:209], v[14:17]
	v_mfma_f32_16x16x32_bf16 v[10:13], v[154:157], v[206:209], v[10:13]
	s_barrier
	s_add_u32 s14, s18, 0xb0000
	s_addc_u32 s15, s19, 0
	s_add_i32 s49, s50, s33
	s_mov_b32 m0, s49
	s_nop 0
	global_load_lds_dwordx4 v132, s[14:15]
	s_add_i32 m0, s49, 0x2000
	s_nop 0
	global_load_lds_dwordx4 v136, s[14:15]
	s_waitcnt vmcnt(6)
	s_barrier
	v_mfma_f32_16x16x32_bf16 v[54:57], v[210:213], v[158:161], v[54:57]
	v_mfma_f32_16x16x32_bf16 v[50:53], v[218:221], v[158:161], v[50:53]
	v_mfma_f32_16x16x32_bf16 v[38:41], v[210:213], v[172:175], v[38:41]
	v_mfma_f32_16x16x32_bf16 v[34:37], v[218:221], v[172:175], v[34:37]
	v_mfma_f32_16x16x32_bf16 v[22:25], v[210:213], v[194:197], v[22:25]
	v_mfma_f32_16x16x32_bf16 v[18:21], v[218:221], v[194:197], v[18:21]
	v_mfma_f32_16x16x32_bf16 v[6:9], v[210:213], v[202:205], v[6:9]
	v_mfma_f32_16x16x32_bf16 v[2:5], v[218:221], v[202:205], v[2:5]
	v_mfma_f32_16x16x32_bf16 v[54:57], v[214:217], v[168:171], v[54:57]
	v_mfma_f32_16x16x32_bf16 v[50:53], v[222:225], v[168:171], v[50:53]
	v_mfma_f32_16x16x32_bf16 v[38:41], v[214:217], v[190:193], v[38:41]
	v_mfma_f32_16x16x32_bf16 v[34:37], v[222:225], v[190:193], v[34:37]
	v_mfma_f32_16x16x32_bf16 v[22:25], v[214:217], v[198:201], v[22:25]
	v_mfma_f32_16x16x32_bf16 v[18:21], v[222:225], v[198:201], v[18:21]
	v_mfma_f32_16x16x32_bf16 v[6:9], v[214:217], v[206:209], v[6:9]
	v_mfma_f32_16x16x32_bf16 v[2:5], v[222:225], v[206:209], v[2:5]
	s_add_i32 s49, 0, 0x18000
	v_add_u32_e32 v154, s49, v164
	s_barrier
	ds_read_b128 v[142:145], v154
	ds_read_b128 v[146:149], v154 offset:1024
	ds_read_b128 v[150:153], v154 offset:2048
	ds_read_b128 v[154:157], v154 offset:3072
	s_add_u32 s14, s20, 0xb8000
	s_addc_u32 s15, s21, 0
	s_mov_b32 m0, s36
	ds_read_b128 v[158:161], v166 offset:32768
	ds_read_b128 v[168:171], v166 offset:33792
	ds_read_b128 v[172:175], v166 offset:34816
	ds_read_b128 v[190:193], v166 offset:35840
	ds_read_b128 v[194:197], v166 offset:36864
	ds_read_b128 v[198:201], v166 offset:37888
	ds_read_b128 v[202:205], v166 offset:38912
	ds_read_b128 v[206:209], v166 offset:39936
	global_load_lds_dwordx4 v130, s[14:15]
	s_mov_b32 m0, s37
	s_nop 0
	global_load_lds_dwordx4 v134, s[14:15]
	s_waitcnt lgkmcnt(8)
	s_barrier
	s_waitcnt lgkmcnt(0)
	s_waitcnt lgkmcnt(0)
	v_mfma_f32_16x16x32_bf16 v[126:129], v[142:145], v[158:161], v[126:129]
	v_mfma_f32_16x16x32_bf16 v[122:125], v[150:153], v[158:161], v[122:125]
	v_mfma_f32_16x16x32_bf16 v[110:113], v[142:145], v[172:175], v[110:113]
	v_mfma_f32_16x16x32_bf16 v[106:109], v[150:153], v[172:175], v[106:109]
	v_mfma_f32_16x16x32_bf16 v[94:97], v[142:145], v[194:197], v[94:97]
	v_mfma_f32_16x16x32_bf16 v[90:93], v[150:153], v[194:197], v[90:93]
	v_mfma_f32_16x16x32_bf16 v[78:81], v[142:145], v[202:205], v[78:81]
	v_mfma_f32_16x16x32_bf16 v[74:77], v[150:153], v[202:205], v[74:77]
	v_mfma_f32_16x16x32_bf16 v[126:129], v[146:149], v[168:171], v[126:129]
	v_mfma_f32_16x16x32_bf16 v[122:125], v[154:157], v[168:171], v[122:125]
	v_mfma_f32_16x16x32_bf16 v[110:113], v[146:149], v[190:193], v[110:113]
	v_mfma_f32_16x16x32_bf16 v[106:109], v[154:157], v[190:193], v[106:109]
	v_mfma_f32_16x16x32_bf16 v[94:97], v[146:149], v[198:201], v[94:97]
	v_mfma_f32_16x16x32_bf16 v[90:93], v[154:157], v[198:201], v[90:93]
	v_mfma_f32_16x16x32_bf16 v[78:81], v[146:149], v[206:209], v[78:81]
	v_mfma_f32_16x16x32_bf16 v[74:77], v[154:157], v[206:209], v[74:77]
	s_barrier
	s_add_i32 s20, 0, 0x1c000
	s_add_i32 s14, s49, s33
	v_add_u32_e32 v167, s20, v164
	s_mov_b32 m0, s14
	ds_read_b128 v[210:213], v167
	ds_read_b128 v[214:217], v167 offset:1024
	ds_read_b128 v[218:221], v167 offset:2048
	ds_read_b128 v[222:225], v167 offset:3072
	global_load_lds_dwordx4 v132, s[64:65]
	s_add_i32 m0, s14, 0x2000
	s_nop 0
	global_load_lds_dwordx4 v136, s[64:65]
	s_barrier
	s_waitcnt lgkmcnt(0)
	s_waitcnt lgkmcnt(0)
	v_mfma_f32_16x16x32_bf16 v[118:121], v[210:213], v[158:161], v[118:121]
	v_mfma_f32_16x16x32_bf16 v[114:117], v[218:221], v[158:161], v[114:117]
	v_mfma_f32_16x16x32_bf16 v[102:105], v[210:213], v[172:175], v[102:105]
	v_mfma_f32_16x16x32_bf16 v[98:101], v[218:221], v[172:175], v[98:101]
	v_mfma_f32_16x16x32_bf16 v[86:89], v[210:213], v[194:197], v[86:89]
	v_mfma_f32_16x16x32_bf16 v[82:85], v[218:221], v[194:197], v[82:85]
	v_mfma_f32_16x16x32_bf16 v[70:73], v[210:213], v[202:205], v[70:73]
	v_mfma_f32_16x16x32_bf16 v[66:69], v[218:221], v[202:205], v[66:69]
	v_mfma_f32_16x16x32_bf16 v[118:121], v[214:217], v[168:171], v[118:121]
	v_mfma_f32_16x16x32_bf16 v[114:117], v[222:225], v[168:171], v[114:117]
	v_mfma_f32_16x16x32_bf16 v[102:105], v[214:217], v[190:193], v[102:105]
	v_mfma_f32_16x16x32_bf16 v[98:101], v[222:225], v[190:193], v[98:101]
	v_mfma_f32_16x16x32_bf16 v[86:89], v[214:217], v[198:201], v[86:89]
	v_mfma_f32_16x16x32_bf16 v[82:85], v[222:225], v[198:201], v[82:85]
	v_mfma_f32_16x16x32_bf16 v[70:73], v[214:217], v[206:209], v[70:73]
	v_mfma_f32_16x16x32_bf16 v[66:69], v[222:225], v[206:209], v[66:69]
	s_mov_b32 m0, s38
	s_barrier
	ds_read_b128 v[158:161], v166 offset:49152
	ds_read_b128 v[168:171], v166 offset:50176
	ds_read_b128 v[172:175], v166 offset:51200
	ds_read_b128 v[190:193], v166 offset:52224
	ds_read_b128 v[194:197], v166 offset:53248
	ds_read_b128 v[198:201], v166 offset:54272
	ds_read_b128 v[202:205], v166 offset:55296
	ds_read_b128 v[206:209], v166 offset:56320
	global_load_lds_dwordx4 v130, s[62:63]
	s_mov_b32 m0, s39
	s_nop 0
	global_load_lds_dwordx4 v134, s[62:63]
	s_barrier
	s_waitcnt lgkmcnt(0)
	s_waitcnt lgkmcnt(0)
	v_mfma_f32_16x16x32_bf16 v[62:65], v[142:145], v[158:161], v[62:65]
	v_mfma_f32_16x16x32_bf16 v[58:61], v[150:153], v[158:161], v[58:61]
	v_mfma_f32_16x16x32_bf16 v[46:49], v[142:145], v[172:175], v[46:49]
	v_mfma_f32_16x16x32_bf16 v[42:45], v[150:153], v[172:175], v[42:45]
	v_mfma_f32_16x16x32_bf16 v[30:33], v[142:145], v[194:197], v[30:33]
	v_mfma_f32_16x16x32_bf16 v[26:29], v[150:153], v[194:197], v[26:29]
	v_mfma_f32_16x16x32_bf16 v[14:17], v[142:145], v[202:205], v[14:17]
	v_mfma_f32_16x16x32_bf16 v[10:13], v[150:153], v[202:205], v[10:13]
	v_mfma_f32_16x16x32_bf16 v[62:65], v[146:149], v[168:171], v[62:65]
	v_mfma_f32_16x16x32_bf16 v[58:61], v[154:157], v[168:171], v[58:61]
	v_mfma_f32_16x16x32_bf16 v[46:49], v[146:149], v[190:193], v[46:49]
	v_mfma_f32_16x16x32_bf16 v[42:45], v[154:157], v[190:193], v[42:45]
	v_mfma_f32_16x16x32_bf16 v[30:33], v[146:149], v[198:201], v[30:33]
	v_mfma_f32_16x16x32_bf16 v[26:29], v[154:157], v[198:201], v[26:29]
	v_mfma_f32_16x16x32_bf16 v[14:17], v[146:149], v[206:209], v[14:17]
	v_mfma_f32_16x16x32_bf16 v[10:13], v[154:157], v[206:209], v[10:13]
	s_barrier
	s_add_u32 s14, s18, 0xb0080
	s_addc_u32 s15, s19, 0
	s_add_i32 s18, s20, s33
	s_mov_b32 m0, s18
	s_nop 0
	global_load_lds_dwordx4 v132, s[14:15]
	s_add_i32 m0, s18, 0x2000
	s_nop 0
	global_load_lds_dwordx4 v136, s[14:15]
	s_waitcnt vmcnt(6)
	s_barrier
	v_mfma_f32_16x16x32_bf16 v[54:57], v[210:213], v[158:161], v[54:57]
	v_mfma_f32_16x16x32_bf16 v[50:53], v[218:221], v[158:161], v[50:53]
	v_mfma_f32_16x16x32_bf16 v[38:41], v[210:213], v[172:175], v[38:41]
	v_mfma_f32_16x16x32_bf16 v[34:37], v[218:221], v[172:175], v[34:37]
	v_mfma_f32_16x16x32_bf16 v[22:25], v[210:213], v[194:197], v[22:25]
	v_mfma_f32_16x16x32_bf16 v[18:21], v[218:221], v[194:197], v[18:21]
	v_mfma_f32_16x16x32_bf16 v[6:9], v[210:213], v[202:205], v[6:9]
	v_mfma_f32_16x16x32_bf16 v[2:5], v[218:221], v[202:205], v[2:5]
	v_mfma_f32_16x16x32_bf16 v[54:57], v[214:217], v[168:171], v[54:57]
	v_mfma_f32_16x16x32_bf16 v[50:53], v[222:225], v[168:171], v[50:53]
	v_mfma_f32_16x16x32_bf16 v[38:41], v[214:217], v[190:193], v[38:41]
	v_mfma_f32_16x16x32_bf16 v[34:37], v[222:225], v[190:193], v[34:37]
	v_mfma_f32_16x16x32_bf16 v[22:25], v[214:217], v[198:201], v[22:25]
	v_mfma_f32_16x16x32_bf16 v[18:21], v[222:225], v[198:201], v[18:21]
	v_mfma_f32_16x16x32_bf16 v[6:9], v[214:217], v[206:209], v[6:9]
	v_mfma_f32_16x16x32_bf16 v[2:5], v[222:225], v[206:209], v[2:5]
	s_add_i32 s48, s48, 2
	s_add_u32 s46, s46, 0x100
	s_addc_u32 s47, s47, 0
	s_cmp_gt_u32 s48, 41
	s_mov_b64 s[14:15], s[16:17]
	s_barrier
	s_cbranch_scc0 .LBB0_400
	s_ashr_i32 s14, s44, 5
	v_lshl_or_b32 v176, s45, 8, v165
	s_mul_hi_i32 s15, s14, 0x9000
	s_mul_i32 s14, s14, 0x9000
	s_add_u32 s14, s26, s14
	v_ashrrev_i32_e32 v177, 31, v176
	s_addc_u32 s15, s27, s15
	v_lshlrev_b64 v[158:159], 2, v[176:177]
	v_lshl_add_u64 v[160:161], s[14:15], 0, v[158:159]
	global_load_dwordx4 v[142:145], v[160:161], off offset:16
	global_load_dwordx4 v[146:149], v[160:161], off
	v_lshl_add_u32 v162, s44, 8, v1
	v_ashrrev_i32_e32 v163, 31, v162
	s_mov_b64 s[14:15], 0x80000
	s_and_b64 vcc, exec, s[4:5]
	s_mov_b32 s45, s42
	s_mov_b32 s44, s43
	s_mov_b64 s[16:17], s[8:9]
	s_waitcnt vmcnt(0)
	v_pk_add_f32 v[144:145], v[144:145], 1.0 op_sel_hi:[1,0]
	v_pk_add_f32 v[148:149], v[148:149], 1.0 op_sel_hi:[1,0]
	v_pk_add_f32 v[146:147], v[146:147], 1.0 op_sel_hi:[1,0]
	v_pk_add_f32 v[142:143], v[142:143], 1.0 op_sel_hi:[1,0]
	v_pk_mul_f32 v[150:151], v[148:149], 0.5 op_sel_hi:[1,0]
	v_pk_mul_f32 v[152:153], v[146:147], 0.5 op_sel_hi:[1,0]
	v_pk_mul_f32 v[154:155], v[144:145], 0.5 op_sel_hi:[1,0]
	v_pk_mul_f32 v[156:157], v[142:143], 0.5 op_sel_hi:[1,0]
	global_load_dwordx4 v[146:149], v[160:161], off offset:528
	global_load_dwordx4 v[142:145], v[160:161], off offset:512
	s_waitcnt vmcnt(0)
	v_pk_add_f32 v[148:149], v[148:149], 1.0 op_sel_hi:[1,0]
	v_pk_add_f32 v[144:145], v[144:145], 1.0 op_sel_hi:[1,0]
	v_pk_add_f32 v[160:161], v[142:143], 1.0 op_sel_hi:[1,0]
	v_pk_mul_f32 v[142:143], v[144:145], 0.5 op_sel_hi:[1,0]
	v_pk_mul_f32 v[144:145], v[160:161], 0.5 op_sel_hi:[1,0]
	v_pk_add_f32 v[160:161], v[146:147], 1.0 op_sel_hi:[1,0]
	v_pk_mul_f32 v[146:147], v[148:149], 0.5 op_sel_hi:[1,0]
	v_pk_mul_f32 v[148:149], v[160:161], 0.5 op_sel_hi:[1,0]
	v_lshlrev_b64 v[160:161], 12, v[162:163]
	v_lshl_add_u64 v[168:169], s[2:3], 0, v[160:161]
	v_lshl_add_u64 v[186:187], v[168:169], 0, v[158:159]
	global_load_dwordx4 v[168:171], v[186:187], off offset:16
	global_load_dwordx4 v[172:175], v[186:187], off
	s_waitcnt vmcnt(0)
	v_pk_fma_f32 v[122:123], v[122:123], v[156:157], v[168:169]
	v_pk_fma_f32 v[128:129], v[128:129], v[150:151], v[174:175]
	v_pk_fma_f32 v[126:127], v[126:127], v[152:153], v[172:173]
	v_pk_fma_f32 v[170:171], v[124:125], v[154:155], v[170:171]
	v_cvt_pk_bf16_f32 v124, v126, v127
	v_cvt_pk_bf16_f32 v125, v128, v129
	v_cvt_pk_bf16_f32 v126, v122, v123
	v_lshl_add_u64 v[128:129], s[12:13], 0, v[160:161]
	v_lshlrev_b64 v[122:123], 1, v[176:177]
	v_cvt_pk_bf16_f32 v127, v170, v171
	v_lshl_add_u64 v[128:129], v[128:129], 0, v[122:123]
	global_store_dwordx4 v[128:129], v[124:127], off offset:2048
	global_load_dwordx4 v[124:127], v[186:187], off offset:528
	s_nop 0
	global_load_dwordx4 v[168:171], v[186:187], off offset:512
	s_waitcnt vmcnt(0)
	v_pk_fma_f32 v[126:127], v[116:117], v[146:147], v[126:127]
	v_pk_fma_f32 v[120:121], v[120:121], v[142:143], v[170:171]
	v_pk_fma_f32 v[118:119], v[118:119], v[144:145], v[168:169]
	v_pk_fma_f32 v[116:117], v[114:115], v[148:149], v[124:125]
	v_cvt_pk_bf16_f32 v114, v118, v119
	v_cvt_pk_bf16_f32 v115, v120, v121
	v_cvt_pk_bf16_f32 v116, v116, v117
	v_cvt_pk_bf16_f32 v117, v126, v127
	global_store_dwordx4 v[128:129], v[114:117], off offset:2304
	s_nop 1
	v_or_b32_e32 v114, 16, v162
	v_ashrrev_i32_e32 v115, 31, v114
	v_lshlrev_b64 v[124:125], 12, v[114:115]
	v_lshl_add_u64 v[114:115], s[2:3], 0, v[124:125]
	v_lshl_add_u64 v[126:127], v[114:115], 0, v[158:159]
	global_load_dwordx4 v[114:117], v[126:127], off offset:16
	global_load_dwordx4 v[118:121], v[126:127], off
	s_waitcnt vmcnt(0)
	v_pk_fma_f32 v[116:117], v[108:109], v[154:155], v[116:117]
	v_pk_fma_f32 v[110:111], v[110:111], v[152:153], v[118:119]
	v_pk_fma_f32 v[112:113], v[112:113], v[150:151], v[120:121]
	v_pk_fma_f32 v[108:109], v[106:107], v[156:157], v[114:115]
	v_cvt_pk_bf16_f32 v106, v110, v111
	v_lshl_add_u64 v[110:111], s[12:13], 0, v[124:125]
	v_cvt_pk_bf16_f32 v107, v112, v113
	v_cvt_pk_bf16_f32 v108, v108, v109
	v_cvt_pk_bf16_f32 v109, v116, v117
	v_lshl_add_u64 v[114:115], v[110:111], 0, v[122:123]
	global_store_dwordx4 v[114:115], v[106:109], off offset:2048
	global_load_dwordx4 v[106:109], v[126:127], off offset:528
	s_nop 0
	global_load_dwordx4 v[110:113], v[126:127], off offset:512
	s_waitcnt vmcnt(0)
	v_pk_fma_f32 v[108:109], v[100:101], v[146:147], v[108:109]
	v_pk_fma_f32 v[104:105], v[104:105], v[142:143], v[112:113]
	v_pk_fma_f32 v[102:103], v[102:103], v[144:145], v[110:111]
	v_pk_fma_f32 v[100:101], v[98:99], v[148:149], v[106:107]
	v_cvt_pk_bf16_f32 v98, v102, v103
	v_cvt_pk_bf16_f32 v99, v104, v105
	v_cvt_pk_bf16_f32 v100, v100, v101
	v_cvt_pk_bf16_f32 v101, v108, v109
	global_store_dwordx4 v[114:115], v[98:101], off offset:2304
	s_nop 1
	v_or_b32_e32 v98, 32, v162
	v_ashrrev_i32_e32 v99, 31, v98
	v_lshlrev_b64 v[106:107], 12, v[98:99]
	v_lshl_add_u64 v[98:99], s[2:3], 0, v[106:107]
	v_lshl_add_u64 v[108:109], v[98:99], 0, v[158:159]
	global_load_dwordx4 v[98:101], v[108:109], off offset:16
	global_load_dwordx4 v[102:105], v[108:109], off
	s_waitcnt vmcnt(0)
	v_pk_fma_f32 v[100:101], v[92:93], v[154:155], v[100:101]
	v_pk_fma_f32 v[94:95], v[94:95], v[152:153], v[102:103]
	v_pk_fma_f32 v[96:97], v[96:97], v[150:151], v[104:105]
	v_pk_fma_f32 v[92:93], v[90:91], v[156:157], v[98:99]
	v_cvt_pk_bf16_f32 v90, v94, v95
	v_lshl_add_u64 v[94:95], s[12:13], 0, v[106:107]
	v_cvt_pk_bf16_f32 v91, v96, v97
	v_cvt_pk_bf16_f32 v92, v92, v93
	v_cvt_pk_bf16_f32 v93, v100, v101
	v_lshl_add_u64 v[98:99], v[94:95], 0, v[122:123]
	global_store_dwordx4 v[98:99], v[90:93], off offset:2048
	global_load_dwordx4 v[90:93], v[108:109], off offset:528
	s_nop 0
	global_load_dwordx4 v[94:97], v[108:109], off offset:512
	s_waitcnt vmcnt(0)
	v_pk_fma_f32 v[92:93], v[84:85], v[146:147], v[92:93]
	v_pk_fma_f32 v[88:89], v[88:89], v[142:143], v[96:97]
	v_pk_fma_f32 v[86:87], v[86:87], v[144:145], v[94:95]
	v_pk_fma_f32 v[84:85], v[82:83], v[148:149], v[90:91]
	v_cvt_pk_bf16_f32 v82, v86, v87
	v_cvt_pk_bf16_f32 v83, v88, v89
	v_cvt_pk_bf16_f32 v84, v84, v85
	v_cvt_pk_bf16_f32 v85, v92, v93
	global_store_dwordx4 v[98:99], v[82:85], off offset:2304
	s_nop 1
	v_or_b32_e32 v82, 48, v162
	v_ashrrev_i32_e32 v83, 31, v82
	v_lshlrev_b64 v[90:91], 12, v[82:83]
	v_lshl_add_u64 v[82:83], s[2:3], 0, v[90:91]
	v_lshl_add_u64 v[92:93], v[82:83], 0, v[158:159]
	global_load_dwordx4 v[82:85], v[92:93], off offset:16
	global_load_dwordx4 v[86:89], v[92:93], off
	s_waitcnt vmcnt(0)
	v_pk_fma_f32 v[84:85], v[76:77], v[154:155], v[84:85]
	v_pk_fma_f32 v[78:79], v[78:79], v[152:153], v[86:87]
	v_pk_fma_f32 v[80:81], v[80:81], v[150:151], v[88:89]
	v_pk_fma_f32 v[76:77], v[74:75], v[156:157], v[82:83]
	v_cvt_pk_bf16_f32 v74, v78, v79
	v_lshl_add_u64 v[78:79], s[12:13], 0, v[90:91]
	v_cvt_pk_bf16_f32 v75, v80, v81
	v_cvt_pk_bf16_f32 v76, v76, v77
	v_cvt_pk_bf16_f32 v77, v84, v85
	v_lshl_add_u64 v[82:83], v[78:79], 0, v[122:123]
	global_store_dwordx4 v[82:83], v[74:77], off offset:2048
	global_load_dwordx4 v[74:77], v[92:93], off offset:528
	s_nop 0
	global_load_dwordx4 v[78:81], v[92:93], off offset:512
	s_waitcnt vmcnt(0)
	v_pk_fma_f32 v[76:77], v[68:69], v[146:147], v[76:77]
	v_pk_fma_f32 v[72:73], v[72:73], v[142:143], v[80:81]
	v_pk_fma_f32 v[70:71], v[70:71], v[144:145], v[78:79]
	v_pk_fma_f32 v[68:69], v[66:67], v[148:149], v[74:75]
	v_cvt_pk_bf16_f32 v66, v70, v71
	v_cvt_pk_bf16_f32 v67, v72, v73
	v_cvt_pk_bf16_f32 v68, v68, v69
	v_cvt_pk_bf16_f32 v69, v76, v77
	v_lshl_add_u64 v[74:75], v[160:161], 0, s[14:15]
	global_store_dwordx4 v[82:83], v[66:69], off offset:2304
	s_mov_b64 s[14:15], 0x90000
	s_nop 0
	v_lshl_add_u64 v[66:67], s[2:3], 0, v[74:75]
	v_lshl_add_u64 v[76:77], v[66:67], 0, v[158:159]
	global_load_dwordx4 v[66:69], v[76:77], off offset:16
	global_load_dwordx4 v[70:73], v[76:77], off
	s_waitcnt vmcnt(0)
	v_pk_fma_f32 v[68:69], v[60:61], v[154:155], v[68:69]
	v_pk_fma_f32 v[62:63], v[62:63], v[152:153], v[70:71]
	v_pk_fma_f32 v[64:65], v[64:65], v[150:151], v[72:73]
	v_pk_fma_f32 v[60:61], v[58:59], v[156:157], v[66:67]
	v_cvt_pk_bf16_f32 v58, v62, v63
	v_lshl_add_u64 v[62:63], s[12:13], 0, v[74:75]
	v_cvt_pk_bf16_f32 v59, v64, v65
	v_cvt_pk_bf16_f32 v60, v60, v61
	v_cvt_pk_bf16_f32 v61, v68, v69
	v_lshl_add_u64 v[66:67], v[62:63], 0, v[122:123]
	global_store_dwordx4 v[66:67], v[58:61], off offset:2048
	global_load_dwordx4 v[58:61], v[76:77], off offset:528
	s_nop 0
	global_load_dwordx4 v[62:65], v[76:77], off offset:512
	s_waitcnt vmcnt(0)
	v_pk_fma_f32 v[60:61], v[52:53], v[146:147], v[60:61]
	v_pk_fma_f32 v[56:57], v[56:57], v[142:143], v[64:65]
	v_pk_fma_f32 v[54:55], v[54:55], v[144:145], v[62:63]
	v_pk_fma_f32 v[52:53], v[50:51], v[148:149], v[58:59]
	v_cvt_pk_bf16_f32 v50, v54, v55
	v_cvt_pk_bf16_f32 v51, v56, v57
	v_cvt_pk_bf16_f32 v52, v52, v53
	v_cvt_pk_bf16_f32 v53, v60, v61
	v_lshl_add_u64 v[58:59], v[160:161], 0, s[14:15]
	global_store_dwordx4 v[66:67], v[50:53], off offset:2304
	s_mov_b64 s[14:15], 0xa0000
	s_nop 0
	v_lshl_add_u64 v[50:51], s[2:3], 0, v[58:59]
	v_lshl_add_u64 v[60:61], v[50:51], 0, v[158:159]
	global_load_dwordx4 v[50:53], v[60:61], off offset:16
	global_load_dwordx4 v[54:57], v[60:61], off
	s_waitcnt vmcnt(0)
	v_pk_fma_f32 v[52:53], v[44:45], v[154:155], v[52:53]
	v_pk_fma_f32 v[46:47], v[46:47], v[152:153], v[54:55]
	v_pk_fma_f32 v[48:49], v[48:49], v[150:151], v[56:57]
	v_pk_fma_f32 v[44:45], v[42:43], v[156:157], v[50:51]
	v_cvt_pk_bf16_f32 v42, v46, v47
	v_lshl_add_u64 v[46:47], s[12:13], 0, v[58:59]
	v_cvt_pk_bf16_f32 v43, v48, v49
	v_cvt_pk_bf16_f32 v44, v44, v45
	v_cvt_pk_bf16_f32 v45, v52, v53
	v_lshl_add_u64 v[50:51], v[46:47], 0, v[122:123]
	global_store_dwordx4 v[50:51], v[42:45], off offset:2048
	global_load_dwordx4 v[42:45], v[60:61], off offset:528
	s_nop 0
	global_load_dwordx4 v[46:49], v[60:61], off offset:512
	s_waitcnt vmcnt(0)
	v_pk_fma_f32 v[44:45], v[36:37], v[146:147], v[44:45]
	v_pk_fma_f32 v[40:41], v[40:41], v[142:143], v[48:49]
	v_pk_fma_f32 v[38:39], v[38:39], v[144:145], v[46:47]
	v_pk_fma_f32 v[36:37], v[34:35], v[148:149], v[42:43]
	v_cvt_pk_bf16_f32 v34, v38, v39
	v_cvt_pk_bf16_f32 v35, v40, v41
	v_cvt_pk_bf16_f32 v36, v36, v37
	v_cvt_pk_bf16_f32 v37, v44, v45
	v_lshl_add_u64 v[42:43], v[160:161], 0, s[14:15]
	global_store_dwordx4 v[50:51], v[34:37], off offset:2304
	s_mov_b64 s[14:15], 0xb0000
	s_nop 0
	v_lshl_add_u64 v[34:35], s[2:3], 0, v[42:43]
	v_lshl_add_u64 v[44:45], v[34:35], 0, v[158:159]
	global_load_dwordx4 v[34:37], v[44:45], off offset:16
	global_load_dwordx4 v[38:41], v[44:45], off
	s_waitcnt vmcnt(0)
	v_pk_fma_f32 v[36:37], v[28:29], v[154:155], v[36:37]
	v_pk_fma_f32 v[30:31], v[30:31], v[152:153], v[38:39]
	v_pk_fma_f32 v[32:33], v[32:33], v[150:151], v[40:41]
	v_pk_fma_f32 v[28:29], v[26:27], v[156:157], v[34:35]
	v_cvt_pk_bf16_f32 v26, v30, v31
	v_lshl_add_u64 v[30:31], s[12:13], 0, v[42:43]
	v_cvt_pk_bf16_f32 v27, v32, v33
	v_cvt_pk_bf16_f32 v28, v28, v29
	v_cvt_pk_bf16_f32 v29, v36, v37
	v_lshl_add_u64 v[34:35], v[30:31], 0, v[122:123]
	global_store_dwordx4 v[34:35], v[26:29], off offset:2048
	global_load_dwordx4 v[26:29], v[44:45], off offset:528
	s_nop 0
	global_load_dwordx4 v[30:33], v[44:45], off offset:512
	s_waitcnt vmcnt(0)
	v_pk_fma_f32 v[28:29], v[20:21], v[146:147], v[28:29]
	v_pk_fma_f32 v[24:25], v[24:25], v[142:143], v[32:33]
	v_pk_fma_f32 v[22:23], v[22:23], v[144:145], v[30:31]
	v_pk_fma_f32 v[20:21], v[18:19], v[148:149], v[26:27]
	v_cvt_pk_bf16_f32 v18, v22, v23
	v_cvt_pk_bf16_f32 v19, v24, v25
	v_cvt_pk_bf16_f32 v20, v20, v21
	v_cvt_pk_bf16_f32 v21, v28, v29
	v_lshl_add_u64 v[26:27], v[160:161], 0, s[14:15]
	global_store_dwordx4 v[34:35], v[18:21], off offset:2304
	s_mov_b64 s[14:15], s[6:7]
	s_nop 0
	v_lshl_add_u64 v[18:19], s[2:3], 0, v[26:27]
	v_lshl_add_u64 v[28:29], v[18:19], 0, v[158:159]
	global_load_dwordx4 v[18:21], v[28:29], off offset:16
	global_load_dwordx4 v[22:25], v[28:29], off
	s_waitcnt vmcnt(0)
	v_pk_fma_f32 v[20:21], v[12:13], v[154:155], v[20:21]
	v_pk_fma_f32 v[14:15], v[14:15], v[152:153], v[22:23]
	v_pk_fma_f32 v[16:17], v[16:17], v[150:151], v[24:25]
	v_pk_fma_f32 v[12:13], v[10:11], v[156:157], v[18:19]
	v_cvt_pk_bf16_f32 v10, v14, v15
	v_lshl_add_u64 v[14:15], s[12:13], 0, v[26:27]
	v_cvt_pk_bf16_f32 v11, v16, v17
	v_cvt_pk_bf16_f32 v12, v12, v13
	v_cvt_pk_bf16_f32 v13, v20, v21
	v_lshl_add_u64 v[18:19], v[14:15], 0, v[122:123]
	global_store_dwordx4 v[18:19], v[10:13], off offset:2048
	global_load_dwordx4 v[10:13], v[28:29], off offset:528
	s_nop 0
	global_load_dwordx4 v[14:17], v[28:29], off offset:512
	s_waitcnt vmcnt(0)
	v_pk_fma_f32 v[12:13], v[4:5], v[146:147], v[12:13]
	v_pk_fma_f32 v[8:9], v[8:9], v[142:143], v[16:17]
	v_pk_fma_f32 v[6:7], v[6:7], v[144:145], v[14:15]
	v_pk_fma_f32 v[4:5], v[2:3], v[148:149], v[10:11]
	v_cvt_pk_bf16_f32 v2, v6, v7
	v_cvt_pk_bf16_f32 v3, v8, v9
	v_cvt_pk_bf16_f32 v4, v4, v5
	v_cvt_pk_bf16_f32 v5, v12, v13
	global_store_dwordx4 v[18:19], v[2:5], off offset:2304
	s_cbranch_vccz .LBB0_389
	s_waitcnt vmcnt(0)
	s_cmpk_gt_u32 s30, 0xff
	s_cbranch_scc1 .LBB0_404
	s_barrier

.LBB0_528:
	s_add_u32 s22, s20, 0xfffc0080
	s_addc_u32 s23, s21, -1
	s_add_i32 s55, 0, 0x10000
	v_add_u32_e32 v144, s55, v146
	ds_read_b128 v[150:153], v144
	ds_read_b128 v[154:157], v144 offset:1024
	ds_read_b128 v[158:161], v144 offset:2048
	ds_read_b128 v[162:165], v144 offset:3072
	s_cmp_eq_u32 s54, 12
	s_cselect_b32 s25, s11, s23
	s_cselect_b32 s24, s15, s22
	s_cselect_b32 s23, s13, s53
	s_cselect_b32 s22, s51, s52
	s_add_i32 m0, s41, 0xc000
	ds_read_b128 v[166:169], v148
	ds_read_b128 v[170:173], v148 offset:1024
	ds_read_b128 v[174:177], v148 offset:2048
	ds_read_b128 v[190:193], v148 offset:3072
	ds_read_b128 v[194:197], v148 offset:4096
	ds_read_b128 v[198:201], v148 offset:5120
	ds_read_b128 v[202:205], v148 offset:6144
	ds_read_b128 v[206:209], v148 offset:7168
	global_load_lds_dwordx4 v140, s[20:21]
	v_lshl_add_u64 v[144:145], s[20:21], 0, v[142:143]
	s_add_i32 m0, s41, 0xe000
	s_nop 0
	global_load_lds_dwordx4 v[144:145], off
	s_waitcnt lgkmcnt(8)
	s_barrier
	s_waitcnt lgkmcnt(0)
	s_waitcnt lgkmcnt(0)
	v_mfma_f32_16x16x32_bf16 v[86:89], v[150:153], v[166:169], v[86:89]
	v_mfma_f32_16x16x32_bf16 v[82:85], v[158:161], v[166:169], v[82:85]
	v_mfma_f32_16x16x32_bf16 v[78:81], v[150:153], v[174:177], v[78:81]
	v_mfma_f32_16x16x32_bf16 v[74:77], v[158:161], v[174:177], v[74:77]
	v_mfma_f32_16x16x32_bf16 v[62:65], v[150:153], v[194:197], v[62:65]
	v_mfma_f32_16x16x32_bf16 v[58:61], v[158:161], v[194:197], v[58:61]
	v_mfma_f32_16x16x32_bf16 v[54:57], v[150:153], v[202:205], v[54:57]
	v_mfma_f32_16x16x32_bf16 v[50:53], v[158:161], v[202:205], v[50:53]
	v_mfma_f32_16x16x32_bf16 v[86:89], v[154:157], v[170:173], v[86:89]
	v_mfma_f32_16x16x32_bf16 v[82:85], v[162:165], v[170:173], v[82:85]
	v_mfma_f32_16x16x32_bf16 v[78:81], v[154:157], v[190:193], v[78:81]
	v_mfma_f32_16x16x32_bf16 v[74:77], v[162:165], v[190:193], v[74:77]
	v_mfma_f32_16x16x32_bf16 v[62:65], v[154:157], v[198:201], v[62:65]
	v_mfma_f32_16x16x32_bf16 v[58:61], v[162:165], v[198:201], v[58:61]
	v_mfma_f32_16x16x32_bf16 v[54:57], v[154:157], v[206:209], v[54:57]
	v_mfma_f32_16x16x32_bf16 v[50:53], v[162:165], v[206:209], v[50:53]
	s_barrier
	s_add_i32 s58, 0, 0x14000
	v_add_u32_e32 v144, s58, v146
	s_add_i32 s55, s55, s35
	ds_read_b128 v[210:213], v144
	ds_read_b128 v[214:217], v144 offset:1024
	ds_read_b128 v[218:221], v144 offset:2048
	ds_read_b128 v[222:225], v144 offset:3072
	s_add_u32 s64, s22, 0x80
	s_addc_u32 s65, s23, 0
	s_mov_b32 m0, s55
	s_nop 0
	global_load_lds_dwordx4 v134, s[22:23]
	s_add_i32 m0, s55, 0x2000
	s_nop 0
	global_load_lds_dwordx4 v130, s[22:23]
	s_barrier
	s_waitcnt lgkmcnt(0)
	s_waitcnt lgkmcnt(0)
	v_mfma_f32_16x16x32_bf16 v[126:129], v[210:213], v[166:169], v[126:129]
	v_mfma_f32_16x16x32_bf16 v[122:125], v[218:221], v[166:169], v[122:125]
	v_mfma_f32_16x16x32_bf16 v[118:121], v[210:213], v[174:177], v[118:121]
	v_mfma_f32_16x16x32_bf16 v[114:117], v[218:221], v[174:177], v[114:117]
	v_mfma_f32_16x16x32_bf16 v[110:113], v[210:213], v[194:197], v[110:113]
	v_mfma_f32_16x16x32_bf16 v[106:109], v[218:221], v[194:197], v[106:109]
	v_mfma_f32_16x16x32_bf16 v[102:105], v[210:213], v[202:205], v[102:105]
	v_mfma_f32_16x16x32_bf16 v[98:101], v[218:221], v[202:205], v[98:101]
	v_mfma_f32_16x16x32_bf16 v[126:129], v[214:217], v[170:173], v[126:129]
	v_mfma_f32_16x16x32_bf16 v[122:125], v[222:225], v[170:173], v[122:125]
	v_mfma_f32_16x16x32_bf16 v[118:121], v[214:217], v[190:193], v[118:121]
	v_mfma_f32_16x16x32_bf16 v[114:117], v[222:225], v[190:193], v[114:117]
	v_mfma_f32_16x16x32_bf16 v[110:113], v[214:217], v[198:201], v[110:113]
	v_mfma_f32_16x16x32_bf16 v[106:109], v[222:225], v[198:201], v[106:109]
	v_mfma_f32_16x16x32_bf16 v[102:105], v[214:217], v[206:209], v[102:105]
	v_mfma_f32_16x16x32_bf16 v[98:101], v[222:225], v[206:209], v[98:101]
	s_mov_b32 m0, s41
	s_add_u32 s62, s24, 0x80
	s_addc_u32 s63, s25, 0
	s_barrier
	ds_read_b128 v[166:169], v148 offset:16384
	ds_read_b128 v[170:173], v148 offset:17408
	ds_read_b128 v[174:177], v148 offset:18432
	ds_read_b128 v[190:193], v148 offset:19456
	ds_read_b128 v[194:197], v148 offset:20480
	ds_read_b128 v[198:201], v148 offset:21504
	ds_read_b128 v[202:205], v148 offset:22528
	ds_read_b128 v[206:209], v148 offset:23552
	global_load_lds_dwordx4 v136, s[24:25]
	s_mov_b32 m0, s42
	s_nop 0
	global_load_lds_dwordx4 v132, s[24:25]
	s_barrier
	s_waitcnt lgkmcnt(0)
	s_waitcnt lgkmcnt(0)
	v_mfma_f32_16x16x32_bf16 v[34:37], v[150:153], v[166:169], v[34:37]
	v_mfma_f32_16x16x32_bf16 v[26:29], v[158:161], v[166:169], v[26:29]
	v_mfma_f32_16x16x32_bf16 v[22:25], v[150:153], v[174:177], v[22:25]
	v_mfma_f32_16x16x32_bf16 v[18:21], v[158:161], v[174:177], v[18:21]
	v_mfma_f32_16x16x32_bf16 v[14:17], v[150:153], v[194:197], v[14:17]
	v_mfma_f32_16x16x32_bf16 v[10:13], v[158:161], v[194:197], v[10:13]
	v_mfma_f32_16x16x32_bf16 v[6:9], v[150:153], v[202:205], v[6:9]
	v_mfma_f32_16x16x32_bf16 v[2:5], v[158:161], v[202:205], v[2:5]
	v_mfma_f32_16x16x32_bf16 v[34:37], v[154:157], v[170:173], v[34:37]
	v_mfma_f32_16x16x32_bf16 v[26:29], v[162:165], v[170:173], v[26:29]
	v_mfma_f32_16x16x32_bf16 v[22:25], v[154:157], v[190:193], v[22:25]
	v_mfma_f32_16x16x32_bf16 v[18:21], v[162:165], v[190:193], v[18:21]
	v_mfma_f32_16x16x32_bf16 v[14:17], v[154:157], v[198:201], v[14:17]
	v_mfma_f32_16x16x32_bf16 v[10:13], v[162:165], v[198:201], v[10:13]
	v_mfma_f32_16x16x32_bf16 v[6:9], v[154:157], v[206:209], v[6:9]
	v_mfma_f32_16x16x32_bf16 v[2:5], v[162:165], v[206:209], v[2:5]
	s_barrier
	s_add_u32 s56, s22, 0x40000
	s_addc_u32 s57, s23, 0
	s_add_i32 s55, s58, s35
	s_mov_b32 m0, s55
	s_nop 0
	global_load_lds_dwordx4 v134, s[56:57]
	s_add_i32 m0, s55, 0x2000
	s_nop 0
	global_load_lds_dwordx4 v130, s[56:57]
	s_waitcnt vmcnt(6)
	s_barrier
	v_mfma_f32_16x16x32_bf16 v[94:97], v[210:213], v[166:169], v[94:97]
	v_mfma_f32_16x16x32_bf16 v[90:93], v[218:221], v[166:169], v[90:93]
	v_mfma_f32_16x16x32_bf16 v[70:73], v[210:213], v[174:177], v[70:73]
	v_mfma_f32_16x16x32_bf16 v[66:69], v[218:221], v[174:177], v[66:69]
	v_mfma_f32_16x16x32_bf16 v[46:49], v[210:213], v[194:197], v[46:49]
	v_mfma_f32_16x16x32_bf16 v[42:45], v[218:221], v[194:197], v[42:45]
	v_mfma_f32_16x16x32_bf16 v[38:41], v[210:213], v[202:205], v[38:41]
	v_mfma_f32_16x16x32_bf16 v[30:33], v[218:221], v[202:205], v[30:33]
	v_mfma_f32_16x16x32_bf16 v[94:97], v[214:217], v[170:173], v[94:97]
	v_mfma_f32_16x16x32_bf16 v[90:93], v[222:225], v[170:173], v[90:93]
	v_mfma_f32_16x16x32_bf16 v[70:73], v[214:217], v[190:193], v[70:73]
	v_mfma_f32_16x16x32_bf16 v[66:69], v[222:225], v[190:193], v[66:69]
	v_mfma_f32_16x16x32_bf16 v[46:49], v[214:217], v[198:201], v[46:49]
	v_mfma_f32_16x16x32_bf16 v[42:45], v[222:225], v[198:201], v[42:45]
	v_mfma_f32_16x16x32_bf16 v[38:41], v[214:217], v[206:209], v[38:41]
	v_mfma_f32_16x16x32_bf16 v[30:33], v[222:225], v[206:209], v[30:33]
	s_add_i32 s55, 0, 0x18000
	v_add_u32_e32 v149, s55, v146
	s_barrier
	ds_read_b128 v[150:153], v149
	ds_read_b128 v[154:157], v149 offset:1024
	ds_read_b128 v[158:161], v149 offset:2048
	ds_read_b128 v[162:165], v149 offset:3072
	s_add_u32 s24, s24, 0x40000
	s_addc_u32 s25, s25, 0
	s_mov_b32 m0, s43
	ds_read_b128 v[166:169], v148 offset:32768
	ds_read_b128 v[170:173], v148 offset:33792
	ds_read_b128 v[174:177], v148 offset:34816
	ds_read_b128 v[190:193], v148 offset:35840
	ds_read_b128 v[194:197], v148 offset:36864
	ds_read_b128 v[198:201], v148 offset:37888
	ds_read_b128 v[202:205], v148 offset:38912
	ds_read_b128 v[206:209], v148 offset:39936
	global_load_lds_dwordx4 v136, s[24:25]
	s_mov_b32 m0, s44
	s_nop 0
	global_load_lds_dwordx4 v132, s[24:25]
	s_waitcnt lgkmcnt(8)
	s_barrier
	s_waitcnt lgkmcnt(0)
	s_waitcnt lgkmcnt(0)
	v_mfma_f32_16x16x32_bf16 v[86:89], v[150:153], v[166:169], v[86:89]
	v_mfma_f32_16x16x32_bf16 v[82:85], v[158:161], v[166:169], v[82:85]
	v_mfma_f32_16x16x32_bf16 v[78:81], v[150:153], v[174:177], v[78:81]
	v_mfma_f32_16x16x32_bf16 v[74:77], v[158:161], v[174:177], v[74:77]
	v_mfma_f32_16x16x32_bf16 v[62:65], v[150:153], v[194:197], v[62:65]
	v_mfma_f32_16x16x32_bf16 v[58:61], v[158:161], v[194:197], v[58:61]
	v_mfma_f32_16x16x32_bf16 v[54:57], v[150:153], v[202:205], v[54:57]
	v_mfma_f32_16x16x32_bf16 v[50:53], v[158:161], v[202:205], v[50:53]
	v_mfma_f32_16x16x32_bf16 v[86:89], v[154:157], v[170:173], v[86:89]
	v_mfma_f32_16x16x32_bf16 v[82:85], v[162:165], v[170:173], v[82:85]
	v_mfma_f32_16x16x32_bf16 v[78:81], v[154:157], v[190:193], v[78:81]
	v_mfma_f32_16x16x32_bf16 v[74:77], v[162:165], v[190:193], v[74:77]
	v_mfma_f32_16x16x32_bf16 v[62:65], v[154:157], v[198:201], v[62:65]
	v_mfma_f32_16x16x32_bf16 v[58:61], v[162:165], v[198:201], v[58:61]
	v_mfma_f32_16x16x32_bf16 v[54:57], v[154:157], v[206:209], v[54:57]
	v_mfma_f32_16x16x32_bf16 v[50:53], v[162:165], v[206:209], v[50:53]
	s_barrier
	s_add_i32 s24, 0, 0x1c000
	s_add_i32 s25, s55, s35
	v_add_u32_e32 v149, s24, v146
	s_mov_b32 m0, s25
	ds_read_b128 v[210:213], v149
	ds_read_b128 v[214:217], v149 offset:1024
	ds_read_b128 v[218:221], v149 offset:2048
	ds_read_b128 v[222:225], v149 offset:3072
	global_load_lds_dwordx4 v134, s[64:65]
	s_add_i32 m0, s25, 0x2000
	s_nop 0
	global_load_lds_dwordx4 v130, s[64:65]
	s_barrier
	s_waitcnt lgkmcnt(0)
	s_waitcnt lgkmcnt(0)
	v_mfma_f32_16x16x32_bf16 v[126:129], v[210:213], v[166:169], v[126:129]
	v_mfma_f32_16x16x32_bf16 v[122:125], v[218:221], v[166:169], v[122:125]
	v_mfma_f32_16x16x32_bf16 v[118:121], v[210:213], v[174:177], v[118:121]
	v_mfma_f32_16x16x32_bf16 v[114:117], v[218:221], v[174:177], v[114:117]
	v_mfma_f32_16x16x32_bf16 v[110:113], v[210:213], v[194:197], v[110:113]
	v_mfma_f32_16x16x32_bf16 v[106:109], v[218:221], v[194:197], v[106:109]
	v_mfma_f32_16x16x32_bf16 v[102:105], v[210:213], v[202:205], v[102:105]
	v_mfma_f32_16x16x32_bf16 v[98:101], v[218:221], v[202:205], v[98:101]
	v_mfma_f32_16x16x32_bf16 v[126:129], v[214:217], v[170:173], v[126:129]
	v_mfma_f32_16x16x32_bf16 v[122:125], v[222:225], v[170:173], v[122:125]
	v_mfma_f32_16x16x32_bf16 v[118:121], v[214:217], v[190:193], v[118:121]
	v_mfma_f32_16x16x32_bf16 v[114:117], v[222:225], v[190:193], v[114:117]
	v_mfma_f32_16x16x32_bf16 v[110:113], v[214:217], v[198:201], v[110:113]
	v_mfma_f32_16x16x32_bf16 v[106:109], v[222:225], v[198:201], v[106:109]
	v_mfma_f32_16x16x32_bf16 v[102:105], v[214:217], v[206:209], v[102:105]
	v_mfma_f32_16x16x32_bf16 v[98:101], v[222:225], v[206:209], v[98:101]
	s_mov_b32 m0, s46
	s_barrier
	ds_read_b128 v[166:169], v148 offset:49152
	ds_read_b128 v[170:173], v148 offset:50176
	ds_read_b128 v[174:177], v148 offset:51200
	ds_read_b128 v[190:193], v148 offset:52224
	ds_read_b128 v[194:197], v148 offset:53248
	ds_read_b128 v[198:201], v148 offset:54272
	ds_read_b128 v[202:205], v148 offset:55296
	ds_read_b128 v[206:209], v148 offset:56320
	global_load_lds_dwordx4 v136, s[62:63]
	s_mov_b32 m0, s47
	s_nop 0
	global_load_lds_dwordx4 v132, s[62:63]
	s_barrier
	s_waitcnt lgkmcnt(0)
	s_waitcnt lgkmcnt(0)
	v_mfma_f32_16x16x32_bf16 v[34:37], v[150:153], v[166:169], v[34:37]
	v_mfma_f32_16x16x32_bf16 v[26:29], v[158:161], v[166:169], v[26:29]
	v_mfma_f32_16x16x32_bf16 v[22:25], v[150:153], v[174:177], v[22:25]
	v_mfma_f32_16x16x32_bf16 v[18:21], v[158:161], v[174:177], v[18:21]
	v_mfma_f32_16x16x32_bf16 v[14:17], v[150:153], v[194:197], v[14:17]
	v_mfma_f32_16x16x32_bf16 v[10:13], v[158:161], v[194:197], v[10:13]
	v_mfma_f32_16x16x32_bf16 v[6:9], v[150:153], v[202:205], v[6:9]
	v_mfma_f32_16x16x32_bf16 v[2:5], v[158:161], v[202:205], v[2:5]
	v_mfma_f32_16x16x32_bf16 v[34:37], v[154:157], v[170:173], v[34:37]
	v_mfma_f32_16x16x32_bf16 v[26:29], v[162:165], v[170:173], v[26:29]
	v_mfma_f32_16x16x32_bf16 v[22:25], v[154:157], v[190:193], v[22:25]
	v_mfma_f32_16x16x32_bf16 v[18:21], v[162:165], v[190:193], v[18:21]
	v_mfma_f32_16x16x32_bf16 v[14:17], v[154:157], v[198:201], v[14:17]
	v_mfma_f32_16x16x32_bf16 v[10:13], v[162:165], v[198:201], v[10:13]
	v_mfma_f32_16x16x32_bf16 v[6:9], v[154:157], v[206:209], v[6:9]
	v_mfma_f32_16x16x32_bf16 v[2:5], v[162:165], v[206:209], v[2:5]
	s_barrier
	s_add_u32 s22, s22, 0x40080
	s_addc_u32 s23, s23, 0
	s_add_i32 s24, s24, s35
	s_mov_b32 m0, s24
	s_nop 0
	global_load_lds_dwordx4 v134, s[22:23]
	v_lshl_add_u64 v[144:145], s[22:23], 0, v[130:131]
	s_add_i32 m0, s24, 0x2000
	s_nop 0
	global_load_lds_dwordx4 v[144:145], off
	s_waitcnt vmcnt(6)
	s_barrier
	v_mfma_f32_16x16x32_bf16 v[94:97], v[210:213], v[166:169], v[94:97]
	v_mfma_f32_16x16x32_bf16 v[90:93], v[218:221], v[166:169], v[90:93]
	v_mfma_f32_16x16x32_bf16 v[70:73], v[210:213], v[174:177], v[70:73]
	v_mfma_f32_16x16x32_bf16 v[66:69], v[218:221], v[174:177], v[66:69]
	v_mfma_f32_16x16x32_bf16 v[46:49], v[210:213], v[194:197], v[46:49]
	v_mfma_f32_16x16x32_bf16 v[42:45], v[218:221], v[194:197], v[42:45]
	v_mfma_f32_16x16x32_bf16 v[38:41], v[210:213], v[202:205], v[38:41]
	v_mfma_f32_16x16x32_bf16 v[30:33], v[218:221], v[202:205], v[30:33]
	v_mfma_f32_16x16x32_bf16 v[94:97], v[214:217], v[170:173], v[94:97]
	v_mfma_f32_16x16x32_bf16 v[90:93], v[222:225], v[170:173], v[90:93]
	v_mfma_f32_16x16x32_bf16 v[70:73], v[214:217], v[190:193], v[70:73]
	v_mfma_f32_16x16x32_bf16 v[66:69], v[222:225], v[190:193], v[66:69]
	v_mfma_f32_16x16x32_bf16 v[46:49], v[214:217], v[198:201], v[46:49]
	v_mfma_f32_16x16x32_bf16 v[42:45], v[222:225], v[198:201], v[42:45]
	v_mfma_f32_16x16x32_bf16 v[38:41], v[214:217], v[206:209], v[38:41]
	v_mfma_f32_16x16x32_bf16 v[30:33], v[222:225], v[206:209], v[30:33]
	s_add_i32 s54, s54, 2
	s_add_u32 s20, s20, 0x100
	s_addc_u32 s21, s21, 0
	s_add_u32 s52, s52, 0x100
	s_addc_u32 s53, s53, 0
	s_cmp_gt_u32 s54, 13
	s_barrier
	s_cbranch_scc0 .LBB0_528
	v_lshl_add_u32 v144, s10, 8, v1
	s_cmp_lg_u32 s50, s45
	s_mov_b64 s[10:11], -1
	s_cbranch_scc0 .LBB0_531
	v_lshl_or_b32 v154, s50, 8, v147
	v_readlane_b32 s13, v255, 32
	v_ashrrev_i32_e32 v155, 31, v154
	v_lshlrev_b64 v[154:155], 1, v[154:155]
	v_mad_i64_i32 v[156:157], s[10:11], v144, s13, 0
	v_lshl_add_u64 v[156:157], v[156:157], 1, s[6:7]
	v_lshl_add_u64 v[156:157], v[156:157], 0, v[154:155]
	v_cvt_pk_bf16_f32 v126, v126, v127
	v_cvt_pk_bf16_f32 v127, v128, v129
	v_cvt_pk_bf16_f32 v128, v122, v123
	v_cvt_pk_bf16_f32 v129, v124, v125
	global_store_dwordx4 v[156:157], v[126:129], off offset:256
	v_cvt_pk_bf16_f32 v150, v86, v87
	v_cvt_pk_bf16_f32 v151, v88, v89
	v_or_b32_e32 v126, 16, v144
	v_mad_i64_i32 v[126:127], s[10:11], v126, s13, 0
	v_lshl_add_u64 v[126:127], v[126:127], 1, s[6:7]
	v_cvt_pk_bf16_f32 v152, v82, v83
	v_cvt_pk_bf16_f32 v153, v84, v85
	v_lshl_add_u64 v[126:127], v[126:127], 0, v[154:155]
	v_cvt_pk_bf16_f32 v118, v118, v119
	v_cvt_pk_bf16_f32 v119, v120, v121
	v_cvt_pk_bf16_f32 v120, v114, v115
	v_cvt_pk_bf16_f32 v121, v116, v117
	global_store_dwordx4 v[156:157], v[150:153], off
	global_store_dwordx4 v[126:127], v[118:121], off offset:256
	v_cvt_pk_bf16_f32 v122, v78, v79
	v_cvt_pk_bf16_f32 v123, v80, v81
	v_or_b32_e32 v118, 32, v144
	v_mad_i64_i32 v[118:119], s[10:11], v118, s13, 0
	v_lshl_add_u64 v[118:119], v[118:119], 1, s[6:7]
	v_cvt_pk_bf16_f32 v124, v74, v75
	v_cvt_pk_bf16_f32 v125, v76, v77
	v_lshl_add_u64 v[118:119], v[118:119], 0, v[154:155]
	v_cvt_pk_bf16_f32 v110, v110, v111
	v_cvt_pk_bf16_f32 v111, v112, v113
	v_cvt_pk_bf16_f32 v112, v106, v107
	v_cvt_pk_bf16_f32 v113, v108, v109
	global_store_dwordx4 v[126:127], v[122:125], off
	global_store_dwordx4 v[118:119], v[110:113], off offset:256
	v_cvt_pk_bf16_f32 v114, v62, v63
	v_cvt_pk_bf16_f32 v115, v64, v65
	v_or_b32_e32 v110, 48, v144
	v_mad_i64_i32 v[110:111], s[10:11], v110, s13, 0
	v_lshl_add_u64 v[110:111], v[110:111], 1, s[6:7]
	v_cvt_pk_bf16_f32 v116, v58, v59
	v_cvt_pk_bf16_f32 v117, v60, v61
	v_lshl_add_u64 v[110:111], v[110:111], 0, v[154:155]
	v_cvt_pk_bf16_f32 v102, v102, v103
	v_cvt_pk_bf16_f32 v103, v104, v105
	v_cvt_pk_bf16_f32 v104, v98, v99
	v_cvt_pk_bf16_f32 v105, v100, v101
	global_store_dwordx4 v[118:119], v[114:117], off
	global_store_dwordx4 v[110:111], v[102:105], off offset:256
	v_cvt_pk_bf16_f32 v106, v54, v55
	v_cvt_pk_bf16_f32 v107, v56, v57
	v_add_u32_e32 v102, 0x80, v144
	v_mad_i64_i32 v[102:103], s[10:11], v102, s13, 0
	v_lshl_add_u64 v[102:103], v[102:103], 1, s[6:7]
	v_cvt_pk_bf16_f32 v108, v50, v51
	v_cvt_pk_bf16_f32 v109, v52, v53
	v_lshl_add_u64 v[102:103], v[102:103], 0, v[154:155]
	v_cvt_pk_bf16_f32 v94, v94, v95
	v_cvt_pk_bf16_f32 v95, v96, v97
	v_cvt_pk_bf16_f32 v96, v90, v91
	v_cvt_pk_bf16_f32 v97, v92, v93
	global_store_dwordx4 v[110:111], v[106:109], off
	global_store_dwordx4 v[102:103], v[94:97], off offset:256
	v_cvt_pk_bf16_f32 v98, v34, v35
	v_cvt_pk_bf16_f32 v99, v36, v37
	v_add_u32_e32 v94, 0x90, v144
	v_mad_i64_i32 v[94:95], s[10:11], v94, s13, 0
	v_lshl_add_u64 v[94:95], v[94:95], 1, s[6:7]
	v_cvt_pk_bf16_f32 v100, v26, v27
	v_cvt_pk_bf16_f32 v101, v28, v29
	v_lshl_add_u64 v[94:95], v[94:95], 0, v[154:155]
	v_cvt_pk_bf16_f32 v70, v70, v71
	v_cvt_pk_bf16_f32 v71, v72, v73
	v_cvt_pk_bf16_f32 v72, v66, v67
	v_cvt_pk_bf16_f32 v73, v68, v69
	global_store_dwordx4 v[102:103], v[98:101], off
	global_store_dwordx4 v[94:95], v[70:73], off offset:256
	v_cvt_pk_bf16_f32 v90, v22, v23
	v_cvt_pk_bf16_f32 v91, v24, v25
	v_add_u32_e32 v70, 0xa0, v144
	v_mad_i64_i32 v[70:71], s[10:11], v70, s13, 0
	v_lshl_add_u64 v[70:71], v[70:71], 1, s[6:7]
	v_cvt_pk_bf16_f32 v92, v18, v19
	v_cvt_pk_bf16_f32 v93, v20, v21
	v_lshl_add_u64 v[70:71], v[70:71], 0, v[154:155]
	v_cvt_pk_bf16_f32 v46, v46, v47
	v_cvt_pk_bf16_f32 v47, v48, v49
	v_cvt_pk_bf16_f32 v48, v42, v43
	v_cvt_pk_bf16_f32 v49, v44, v45
	global_store_dwordx4 v[94:95], v[90:93], off
	global_store_dwordx4 v[70:71], v[46:49], off offset:256
	v_cvt_pk_bf16_f32 v66, v14, v15
	v_cvt_pk_bf16_f32 v67, v16, v17
	v_add_u32_e32 v46, 0xb0, v144
	v_mad_i64_i32 v[46:47], s[10:11], v46, s13, 0
	v_lshl_add_u64 v[46:47], v[46:47], 1, s[6:7]
	v_cvt_pk_bf16_f32 v68, v10, v11
	v_cvt_pk_bf16_f32 v69, v12, v13
	v_cvt_pk_bf16_f32 v42, v6, v7
	v_cvt_pk_bf16_f32 v43, v8, v9
	v_cvt_pk_bf16_f32 v44, v2, v3
	v_cvt_pk_bf16_f32 v45, v4, v5
	v_lshl_add_u64 v[46:47], v[46:47], 0, v[154:155]
	v_cvt_pk_bf16_f32 v38, v38, v39
	v_cvt_pk_bf16_f32 v39, v40, v41
	v_cvt_pk_bf16_f32 v40, v30, v31
	v_cvt_pk_bf16_f32 v41, v32, v33
	global_store_dwordx4 v[70:71], v[66:69], off
	global_store_dwordx4 v[46:47], v[42:45], off
	global_store_dwordx4 v[46:47], v[38:41], off offset:256
	s_mov_b64 s[10:11], 0

.LBB0_1408:
	s_add_u32 s16, s14, s6
	s_addc_u32 s17, s15, s7
	s_add_u32 s16, s16, 0x100
	s_addc_u32 s17, s17, 0
	s_add_u32 s48, s45, s6
	s_addc_u32 s49, s46, s7
	s_add_i32 s50, 0, 0x10000
	v_add_u32_e32 v158, s50, v164
	ds_read_b128 v[146:149], v158
	ds_read_b128 v[150:153], v158 offset:1024
	ds_read_b128 v[154:157], v158 offset:2048
	ds_read_b128 v[158:161], v158 offset:3072
	s_cmpk_eq_i32 s6, 0xf00
	s_cselect_b32 s19, s11, s17
	s_cselect_b32 s18, s10, s16
	s_cselect_b32 s17, s3, s49
	s_cselect_b32 s16, s44, s48
	v_lshl_add_u64 v[162:163], v[142:143], 0, s[6:7]
	s_add_i32 m0, s30, 0xc000
	ds_read_b128 v[168:171], v166
	ds_read_b128 v[172:175], v166 offset:1024
	ds_read_b128 v[186:189], v166 offset:2048
	ds_read_b128 v[190:193], v166 offset:3072
	ds_read_b128 v[194:197], v166 offset:4096
	ds_read_b128 v[198:201], v166 offset:5120
	ds_read_b128 v[202:205], v166 offset:6144
	ds_read_b128 v[206:209], v166 offset:7168
	global_load_lds_dwordx4 v[162:163], off
	v_lshl_add_u64 v[162:163], v[144:145], 0, s[6:7]
	s_add_i32 m0, s30, 0xe000
	s_nop 0
	global_load_lds_dwordx4 v[162:163], off
	s_waitcnt lgkmcnt(8)
	s_barrier
	s_waitcnt lgkmcnt(0)
	s_waitcnt lgkmcnt(0)
	v_mfma_f32_16x16x32_bf16 v[126:129], v[146:149], v[168:171], v[126:129]
	v_mfma_f32_16x16x32_bf16 v[122:125], v[154:157], v[168:171], v[122:125]
	v_mfma_f32_16x16x32_bf16 v[110:113], v[146:149], v[186:189], v[110:113]
	v_mfma_f32_16x16x32_bf16 v[106:109], v[154:157], v[186:189], v[106:109]
	v_mfma_f32_16x16x32_bf16 v[94:97], v[146:149], v[194:197], v[94:97]
	v_mfma_f32_16x16x32_bf16 v[90:93], v[154:157], v[194:197], v[90:93]
	v_mfma_f32_16x16x32_bf16 v[78:81], v[146:149], v[202:205], v[78:81]
	v_mfma_f32_16x16x32_bf16 v[74:77], v[154:157], v[202:205], v[74:77]
	v_mfma_f32_16x16x32_bf16 v[126:129], v[150:153], v[172:175], v[126:129]
	v_mfma_f32_16x16x32_bf16 v[122:125], v[158:161], v[172:175], v[122:125]
	v_mfma_f32_16x16x32_bf16 v[110:113], v[150:153], v[190:193], v[110:113]
	v_mfma_f32_16x16x32_bf16 v[106:109], v[158:161], v[190:193], v[106:109]
	v_mfma_f32_16x16x32_bf16 v[94:97], v[150:153], v[198:201], v[94:97]
	v_mfma_f32_16x16x32_bf16 v[90:93], v[158:161], v[198:201], v[90:93]
	v_mfma_f32_16x16x32_bf16 v[78:81], v[150:153], v[206:209], v[78:81]
	v_mfma_f32_16x16x32_bf16 v[74:77], v[158:161], v[206:209], v[74:77]
	s_barrier
	s_add_i32 s51, 0, 0x14000
	v_add_u32_e32 v162, s51, v164
	s_add_i32 s48, s50, s29
	ds_read_b128 v[210:213], v162
	ds_read_b128 v[214:217], v162 offset:1024
	ds_read_b128 v[218:221], v162 offset:2048
	ds_read_b128 v[222:225], v162 offset:3072
	s_add_u32 s64, s16, 0x80
	s_addc_u32 s65, s17, 0
	s_mov_b32 m0, s48
	s_nop 0
	global_load_lds_dwordx4 v132, s[16:17]
	s_add_i32 m0, s48, 0x2000
	s_nop 0
	global_load_lds_dwordx4 v136, s[16:17]
	s_barrier
	s_waitcnt lgkmcnt(0)
	s_waitcnt lgkmcnt(0)
	v_mfma_f32_16x16x32_bf16 v[118:121], v[210:213], v[168:171], v[118:121]
	v_mfma_f32_16x16x32_bf16 v[114:117], v[218:221], v[168:171], v[114:117]
	v_mfma_f32_16x16x32_bf16 v[102:105], v[210:213], v[186:189], v[102:105]
	v_mfma_f32_16x16x32_bf16 v[98:101], v[218:221], v[186:189], v[98:101]
	v_mfma_f32_16x16x32_bf16 v[86:89], v[210:213], v[194:197], v[86:89]
	v_mfma_f32_16x16x32_bf16 v[82:85], v[218:221], v[194:197], v[82:85]
	v_mfma_f32_16x16x32_bf16 v[70:73], v[210:213], v[202:205], v[70:73]
	v_mfma_f32_16x16x32_bf16 v[66:69], v[218:221], v[202:205], v[66:69]
	v_mfma_f32_16x16x32_bf16 v[118:121], v[214:217], v[172:175], v[118:121]
	v_mfma_f32_16x16x32_bf16 v[114:117], v[222:225], v[172:175], v[114:117]
	v_mfma_f32_16x16x32_bf16 v[102:105], v[214:217], v[190:193], v[102:105]
	v_mfma_f32_16x16x32_bf16 v[98:101], v[222:225], v[190:193], v[98:101]
	v_mfma_f32_16x16x32_bf16 v[86:89], v[214:217], v[198:201], v[86:89]
	v_mfma_f32_16x16x32_bf16 v[82:85], v[222:225], v[198:201], v[82:85]
	v_mfma_f32_16x16x32_bf16 v[70:73], v[214:217], v[206:209], v[70:73]
	v_mfma_f32_16x16x32_bf16 v[66:69], v[222:225], v[206:209], v[66:69]
	s_mov_b32 m0, s30
	s_add_u32 s62, s18, 0x80
	s_addc_u32 s63, s19, 0
	s_barrier
	ds_read_b128 v[168:171], v166 offset:16384
	ds_read_b128 v[172:175], v166 offset:17408
	ds_read_b128 v[186:189], v166 offset:18432
	ds_read_b128 v[190:193], v166 offset:19456
	ds_read_b128 v[194:197], v166 offset:20480
	ds_read_b128 v[198:201], v166 offset:21504
	ds_read_b128 v[202:205], v166 offset:22528
	ds_read_b128 v[206:209], v166 offset:23552
	global_load_lds_dwordx4 v130, s[18:19]
	s_mov_b32 m0, s31
	s_nop 0
	global_load_lds_dwordx4 v134, s[18:19]
	s_barrier
	s_waitcnt lgkmcnt(0)
	s_waitcnt lgkmcnt(0)
	v_mfma_f32_16x16x32_bf16 v[62:65], v[146:149], v[168:171], v[62:65]
	v_mfma_f32_16x16x32_bf16 v[58:61], v[154:157], v[168:171], v[58:61]
	v_mfma_f32_16x16x32_bf16 v[46:49], v[146:149], v[186:189], v[46:49]
	v_mfma_f32_16x16x32_bf16 v[42:45], v[154:157], v[186:189], v[42:45]
	v_mfma_f32_16x16x32_bf16 v[30:33], v[146:149], v[194:197], v[30:33]
	v_mfma_f32_16x16x32_bf16 v[26:29], v[154:157], v[194:197], v[26:29]
	v_mfma_f32_16x16x32_bf16 v[14:17], v[146:149], v[202:205], v[14:17]
	v_mfma_f32_16x16x32_bf16 v[10:13], v[154:157], v[202:205], v[10:13]
	v_mfma_f32_16x16x32_bf16 v[62:65], v[150:153], v[172:175], v[62:65]
	v_mfma_f32_16x16x32_bf16 v[58:61], v[158:161], v[172:175], v[58:61]
	v_mfma_f32_16x16x32_bf16 v[46:49], v[150:153], v[190:193], v[46:49]
	v_mfma_f32_16x16x32_bf16 v[42:45], v[158:161], v[190:193], v[42:45]
	v_mfma_f32_16x16x32_bf16 v[30:33], v[150:153], v[198:201], v[30:33]
	v_mfma_f32_16x16x32_bf16 v[26:29], v[158:161], v[198:201], v[26:29]
	v_mfma_f32_16x16x32_bf16 v[14:17], v[150:153], v[206:209], v[14:17]
	v_mfma_f32_16x16x32_bf16 v[10:13], v[158:161], v[206:209], v[10:13]
	s_barrier
	s_add_u32 s48, s16, 0x80000
	s_addc_u32 s49, s17, 0
	s_add_i32 s50, s51, s29
	s_mov_b32 m0, s50
	s_nop 0
	global_load_lds_dwordx4 v132, s[48:49]
	s_add_i32 m0, s50, 0x2000
	s_nop 0
	global_load_lds_dwordx4 v136, s[48:49]
	s_waitcnt vmcnt(6)
	s_barrier
	v_mfma_f32_16x16x32_bf16 v[54:57], v[210:213], v[168:171], v[54:57]
	v_mfma_f32_16x16x32_bf16 v[50:53], v[218:221], v[168:171], v[50:53]
	v_mfma_f32_16x16x32_bf16 v[38:41], v[210:213], v[186:189], v[38:41]
	v_mfma_f32_16x16x32_bf16 v[34:37], v[218:221], v[186:189], v[34:37]
	v_mfma_f32_16x16x32_bf16 v[22:25], v[210:213], v[194:197], v[22:25]
	v_mfma_f32_16x16x32_bf16 v[18:21], v[218:221], v[194:197], v[18:21]
	v_mfma_f32_16x16x32_bf16 v[6:9], v[210:213], v[202:205], v[6:9]
	v_mfma_f32_16x16x32_bf16 v[2:5], v[218:221], v[202:205], v[2:5]
	v_mfma_f32_16x16x32_bf16 v[54:57], v[214:217], v[172:175], v[54:57]
	v_mfma_f32_16x16x32_bf16 v[50:53], v[222:225], v[172:175], v[50:53]
	v_mfma_f32_16x16x32_bf16 v[38:41], v[214:217], v[190:193], v[38:41]
	v_mfma_f32_16x16x32_bf16 v[34:37], v[222:225], v[190:193], v[34:37]
	v_mfma_f32_16x16x32_bf16 v[22:25], v[214:217], v[198:201], v[22:25]
	v_mfma_f32_16x16x32_bf16 v[18:21], v[222:225], v[198:201], v[18:21]
	v_mfma_f32_16x16x32_bf16 v[6:9], v[214:217], v[206:209], v[6:9]
	v_mfma_f32_16x16x32_bf16 v[2:5], v[222:225], v[206:209], v[2:5]
	s_add_i32 s48, 0, 0x18000
	v_add_u32_e32 v158, s48, v164
	s_barrier
	ds_read_b128 v[146:149], v158
	ds_read_b128 v[150:153], v158 offset:1024
	ds_read_b128 v[154:157], v158 offset:2048
	ds_read_b128 v[158:161], v158 offset:3072
	s_add_u32 s18, s18, s80
	s_addc_u32 s19, s19, 0
	s_mov_b32 m0, s34
	ds_read_b128 v[168:171], v166 offset:32768
	ds_read_b128 v[172:175], v166 offset:33792
	ds_read_b128 v[186:189], v166 offset:34816
	ds_read_b128 v[190:193], v166 offset:35840
	ds_read_b128 v[194:197], v166 offset:36864
	ds_read_b128 v[198:201], v166 offset:37888
	ds_read_b128 v[202:205], v166 offset:38912
	ds_read_b128 v[206:209], v166 offset:39936
	global_load_lds_dwordx4 v130, s[18:19]
	s_mov_b32 m0, s35
	s_nop 0
	global_load_lds_dwordx4 v134, s[18:19]
	s_waitcnt lgkmcnt(8)
	s_barrier
	s_waitcnt lgkmcnt(0)
	s_waitcnt lgkmcnt(0)
	v_mfma_f32_16x16x32_bf16 v[126:129], v[146:149], v[168:171], v[126:129]
	v_mfma_f32_16x16x32_bf16 v[122:125], v[154:157], v[168:171], v[122:125]
	v_mfma_f32_16x16x32_bf16 v[110:113], v[146:149], v[186:189], v[110:113]
	v_mfma_f32_16x16x32_bf16 v[106:109], v[154:157], v[186:189], v[106:109]
	v_mfma_f32_16x16x32_bf16 v[94:97], v[146:149], v[194:197], v[94:97]
	v_mfma_f32_16x16x32_bf16 v[90:93], v[154:157], v[194:197], v[90:93]
	v_mfma_f32_16x16x32_bf16 v[78:81], v[146:149], v[202:205], v[78:81]
	v_mfma_f32_16x16x32_bf16 v[74:77], v[154:157], v[202:205], v[74:77]
	v_mfma_f32_16x16x32_bf16 v[126:129], v[150:153], v[172:175], v[126:129]
	v_mfma_f32_16x16x32_bf16 v[122:125], v[158:161], v[172:175], v[122:125]
	v_mfma_f32_16x16x32_bf16 v[110:113], v[150:153], v[190:193], v[110:113]
	v_mfma_f32_16x16x32_bf16 v[106:109], v[158:161], v[190:193], v[106:109]
	v_mfma_f32_16x16x32_bf16 v[94:97], v[150:153], v[198:201], v[94:97]
	v_mfma_f32_16x16x32_bf16 v[90:93], v[158:161], v[198:201], v[90:93]
	v_mfma_f32_16x16x32_bf16 v[78:81], v[150:153], v[206:209], v[78:81]
	v_mfma_f32_16x16x32_bf16 v[74:77], v[158:161], v[206:209], v[74:77]
	s_barrier
	s_add_i32 s18, 0, 0x1c000
	s_add_i32 s19, s48, s29
	v_add_u32_e32 v167, s18, v164
	s_mov_b32 m0, s19
	ds_read_b128 v[210:213], v167
	ds_read_b128 v[214:217], v167 offset:1024
	ds_read_b128 v[218:221], v167 offset:2048
	ds_read_b128 v[222:225], v167 offset:3072
	global_load_lds_dwordx4 v132, s[64:65]
	s_add_i32 m0, s19, 0x2000
	s_nop 0
	global_load_lds_dwordx4 v136, s[64:65]
	s_barrier
	s_waitcnt lgkmcnt(0)
	s_waitcnt lgkmcnt(0)
	v_mfma_f32_16x16x32_bf16 v[118:121], v[210:213], v[168:171], v[118:121]
	v_mfma_f32_16x16x32_bf16 v[114:117], v[218:221], v[168:171], v[114:117]
	v_mfma_f32_16x16x32_bf16 v[102:105], v[210:213], v[186:189], v[102:105]
	v_mfma_f32_16x16x32_bf16 v[98:101], v[218:221], v[186:189], v[98:101]
	v_mfma_f32_16x16x32_bf16 v[86:89], v[210:213], v[194:197], v[86:89]
	v_mfma_f32_16x16x32_bf16 v[82:85], v[218:221], v[194:197], v[82:85]
	v_mfma_f32_16x16x32_bf16 v[70:73], v[210:213], v[202:205], v[70:73]
	v_mfma_f32_16x16x32_bf16 v[66:69], v[218:221], v[202:205], v[66:69]
	v_mfma_f32_16x16x32_bf16 v[118:121], v[214:217], v[172:175], v[118:121]
	v_mfma_f32_16x16x32_bf16 v[114:117], v[222:225], v[172:175], v[114:117]
	v_mfma_f32_16x16x32_bf16 v[102:105], v[214:217], v[190:193], v[102:105]
	v_mfma_f32_16x16x32_bf16 v[98:101], v[222:225], v[190:193], v[98:101]
	v_mfma_f32_16x16x32_bf16 v[86:89], v[214:217], v[198:201], v[86:89]
	v_mfma_f32_16x16x32_bf16 v[82:85], v[222:225], v[198:201], v[82:85]
	v_mfma_f32_16x16x32_bf16 v[70:73], v[214:217], v[206:209], v[70:73]
	v_mfma_f32_16x16x32_bf16 v[66:69], v[222:225], v[206:209], v[66:69]
	s_mov_b32 m0, s38
	s_barrier
	ds_read_b128 v[168:171], v166 offset:49152
	ds_read_b128 v[172:175], v166 offset:50176
	ds_read_b128 v[186:189], v166 offset:51200
	ds_read_b128 v[190:193], v166 offset:52224
	ds_read_b128 v[194:197], v166 offset:53248
	ds_read_b128 v[198:201], v166 offset:54272
	ds_read_b128 v[202:205], v166 offset:55296
	ds_read_b128 v[206:209], v166 offset:56320
	global_load_lds_dwordx4 v130, s[62:63]
	s_mov_b32 m0, s39
	s_nop 0
	global_load_lds_dwordx4 v134, s[62:63]
	s_barrier
	s_waitcnt lgkmcnt(0)
	s_waitcnt lgkmcnt(0)
	v_mfma_f32_16x16x32_bf16 v[62:65], v[146:149], v[168:171], v[62:65]
	v_mfma_f32_16x16x32_bf16 v[58:61], v[154:157], v[168:171], v[58:61]
	v_mfma_f32_16x16x32_bf16 v[46:49], v[146:149], v[186:189], v[46:49]
	v_mfma_f32_16x16x32_bf16 v[42:45], v[154:157], v[186:189], v[42:45]
	v_mfma_f32_16x16x32_bf16 v[30:33], v[146:149], v[194:197], v[30:33]
	v_mfma_f32_16x16x32_bf16 v[26:29], v[154:157], v[194:197], v[26:29]
	v_mfma_f32_16x16x32_bf16 v[14:17], v[146:149], v[202:205], v[14:17]
	v_mfma_f32_16x16x32_bf16 v[10:13], v[154:157], v[202:205], v[10:13]
	v_mfma_f32_16x16x32_bf16 v[62:65], v[150:153], v[172:175], v[62:65]
	v_mfma_f32_16x16x32_bf16 v[58:61], v[158:161], v[172:175], v[58:61]
	v_mfma_f32_16x16x32_bf16 v[46:49], v[150:153], v[190:193], v[46:49]
	v_mfma_f32_16x16x32_bf16 v[42:45], v[158:161], v[190:193], v[42:45]
	v_mfma_f32_16x16x32_bf16 v[30:33], v[150:153], v[198:201], v[30:33]
	v_mfma_f32_16x16x32_bf16 v[26:29], v[158:161], v[198:201], v[26:29]
	v_mfma_f32_16x16x32_bf16 v[14:17], v[150:153], v[206:209], v[14:17]
	v_mfma_f32_16x16x32_bf16 v[10:13], v[158:161], v[206:209], v[10:13]
	s_barrier
	s_add_u32 s16, s16, 0x80080
	s_addc_u32 s17, s17, 0
	s_add_i32 s18, s18, s29
	s_mov_b32 m0, s18
	s_nop 0
	global_load_lds_dwordx4 v132, s[16:17]
	s_add_i32 m0, s18, 0x2000
	s_nop 0
	global_load_lds_dwordx4 v136, s[16:17]
	s_waitcnt vmcnt(6)
	s_barrier
	v_mfma_f32_16x16x32_bf16 v[54:57], v[210:213], v[168:171], v[54:57]
	v_mfma_f32_16x16x32_bf16 v[50:53], v[218:221], v[168:171], v[50:53]
	v_mfma_f32_16x16x32_bf16 v[38:41], v[210:213], v[186:189], v[38:41]
	v_mfma_f32_16x16x32_bf16 v[34:37], v[218:221], v[186:189], v[34:37]
	v_mfma_f32_16x16x32_bf16 v[22:25], v[210:213], v[194:197], v[22:25]
	v_mfma_f32_16x16x32_bf16 v[18:21], v[218:221], v[194:197], v[18:21]
	v_mfma_f32_16x16x32_bf16 v[6:9], v[210:213], v[202:205], v[6:9]
	v_mfma_f32_16x16x32_bf16 v[2:5], v[218:221], v[202:205], v[2:5]
	v_mfma_f32_16x16x32_bf16 v[54:57], v[214:217], v[172:175], v[54:57]
	v_mfma_f32_16x16x32_bf16 v[50:53], v[222:225], v[172:175], v[50:53]
	v_mfma_f32_16x16x32_bf16 v[38:41], v[214:217], v[190:193], v[38:41]
	v_mfma_f32_16x16x32_bf16 v[34:37], v[222:225], v[190:193], v[34:37]
	v_mfma_f32_16x16x32_bf16 v[22:25], v[214:217], v[198:201], v[22:25]
	v_mfma_f32_16x16x32_bf16 v[18:21], v[222:225], v[198:201], v[18:21]
	v_mfma_f32_16x16x32_bf16 v[6:9], v[214:217], v[206:209], v[6:9]
	v_mfma_f32_16x16x32_bf16 v[2:5], v[222:225], v[206:209], v[2:5]
	s_add_i32 s47, s47, 2
	s_add_u32 s6, s6, 0x100
	s_addc_u32 s7, s7, 0
	s_cmp_gt_u32 s47, 29
	s_barrier
	s_cbranch_scc0 .LBB0_1408
	s_ashr_i32 s3, s33, 5
	s_mul_hi_i32 s7, s3, 0x9000
	s_mul_i32 s3, s3, 0x9000
	v_lshl_or_b32 v168, s43, 8, v165
	s_add_u32 s6, s36, s3
	s_addc_u32 s7, s37, s7
	v_ashrrev_i32_e32 v169, 31, v168
	v_lshl_add_u64 v[162:163], v[168:169], 2, s[6:7]
	global_load_dwordx4 v[142:145], v[162:163], off offset:16
	global_load_dwordx4 v[146:149], v[162:163], off
	s_mov_b64 s[6:7], 0x80000
	s_and_b64 vcc, exec, s[4:5]
	s_mov_b32 s43, s2
	s_mov_b64 s[16:17], s[12:13]
	s_mov_b64 s[14:15], s[10:11]
	s_waitcnt vmcnt(0)
	v_pk_add_f32 v[150:151], v[144:145], 1.0 op_sel_hi:[1,0]
	v_pk_add_f32 v[154:155], v[142:143], 1.0 op_sel_hi:[1,0]
	global_load_dwordx4 v[158:161], v[162:163], off offset:528
	global_load_dwordx4 v[142:145], v[162:163], off offset:512
	v_lshl_add_u32 v162, s33, 8, v1
	v_ashrrev_i32_e32 v163, 31, v162
	v_pk_add_f32 v[156:157], v[146:147], 1.0 op_sel_hi:[1,0]
	v_pk_add_f32 v[152:153], v[148:149], 1.0 op_sel_hi:[1,0]
	s_mov_b32 s33, s42
	s_waitcnt vmcnt(0)
	v_pk_add_f32 v[146:147], v[144:145], 1.0 op_sel_hi:[1,0]
	v_pk_add_f32 v[144:145], v[158:159], 1.0 op_sel_hi:[1,0]
	v_lshlrev_b64 v[158:159], 12, v[162:163]
	v_pk_add_f32 v[148:149], v[142:143], 1.0 op_sel_hi:[1,0]
	v_pk_add_f32 v[142:143], v[160:161], 1.0 op_sel_hi:[1,0]
	v_lshl_add_u64 v[158:159], s[8:9], 0, v[158:159]
	v_lshlrev_b64 v[160:161], 1, v[168:169]
	v_lshl_add_u64 v[158:159], v[158:159], 0, v[160:161]
	global_load_dwordx4 v[168:171], v[158:159], off offset:2048
	s_waitcnt vmcnt(0)
	v_lshlrev_b32_e32 v172, 16, v168
	v_and_b32_e32 v173, 0xffff0000, v168
	v_lshlrev_b32_e32 v168, 16, v169
	v_and_b32_e32 v169, 0xffff0000, v169
	v_pk_fma_f32 v[128:129], v[128:129], v[152:153], v[168:169]
	v_lshlrev_b32_e32 v168, 16, v170
	v_and_b32_e32 v169, 0xffff0000, v170
	v_pk_fma_f32 v[168:169], v[122:123], v[154:155], v[168:169]
	v_lshlrev_b32_e32 v122, 16, v171
	v_and_b32_e32 v123, 0xffff0000, v171
	v_pk_fma_f32 v[126:127], v[126:127], v[156:157], v[172:173]
	v_pk_fma_f32 v[170:171], v[124:125], v[150:151], v[122:123]
	v_cvt_pk_bf16_f32 v122, v126, v127
	v_cvt_pk_bf16_f32 v123, v128, v129
	v_cvt_pk_bf16_f32 v124, v168, v169
	v_cvt_pk_bf16_f32 v125, v170, v171
	global_store_dwordx4 v[158:159], v[122:125], off offset:2048
	global_load_dwordx4 v[122:125], v[158:159], off offset:2304
	s_waitcnt vmcnt(0)
	v_lshlrev_b32_e32 v126, 16, v122
	v_and_b32_e32 v127, 0xffff0000, v122
	v_lshlrev_b32_e32 v122, 16, v123
	v_and_b32_e32 v123, 0xffff0000, v123
	v_pk_fma_f32 v[120:121], v[120:121], v[146:147], v[122:123]
	v_lshlrev_b32_e32 v122, 16, v124
	v_and_b32_e32 v123, 0xffff0000, v124
	v_pk_fma_f32 v[122:123], v[114:115], v[144:145], v[122:123]
	v_lshlrev_b32_e32 v114, 16, v125
	v_and_b32_e32 v115, 0xffff0000, v125
	v_pk_fma_f32 v[118:119], v[118:119], v[148:149], v[126:127]
	v_pk_fma_f32 v[124:125], v[116:117], v[142:143], v[114:115]
	v_cvt_pk_bf16_f32 v114, v118, v119
	v_cvt_pk_bf16_f32 v115, v120, v121
	v_cvt_pk_bf16_f32 v116, v122, v123
	v_cvt_pk_bf16_f32 v117, v124, v125
	global_store_dwordx4 v[158:159], v[114:117], off offset:2304
	s_nop 1
	v_or_b32_e32 v114, 16, v162
	v_ashrrev_i32_e32 v115, 31, v114
	v_lshlrev_b64 v[114:115], 12, v[114:115]
	v_lshl_add_u64 v[114:115], s[8:9], 0, v[114:115]
	v_lshl_add_u64 v[118:119], v[114:115], 0, v[160:161]
	global_load_dwordx4 v[114:117], v[118:119], off offset:2048
	s_waitcnt vmcnt(0)
	v_lshlrev_b32_e32 v120, 16, v114
	v_and_b32_e32 v121, 0xffff0000, v114
	v_lshlrev_b32_e32 v114, 16, v115
	v_and_b32_e32 v115, 0xffff0000, v115
	v_pk_fma_f32 v[112:113], v[112:113], v[152:153], v[114:115]
	v_lshlrev_b32_e32 v114, 16, v116
	v_and_b32_e32 v115, 0xffff0000, v116
	v_pk_fma_f32 v[114:115], v[106:107], v[154:155], v[114:115]
	v_lshlrev_b32_e32 v106, 16, v117
	v_and_b32_e32 v107, 0xffff0000, v117
	v_pk_fma_f32 v[110:111], v[110:111], v[156:157], v[120:121]
	v_pk_fma_f32 v[116:117], v[108:109], v[150:151], v[106:107]
	v_cvt_pk_bf16_f32 v106, v110, v111
	v_cvt_pk_bf16_f32 v107, v112, v113
	v_cvt_pk_bf16_f32 v108, v114, v115
	v_cvt_pk_bf16_f32 v109, v116, v117
	global_store_dwordx4 v[118:119], v[106:109], off offset:2048
	global_load_dwordx4 v[106:109], v[118:119], off offset:2304
	s_waitcnt vmcnt(0)
	v_lshlrev_b32_e32 v110, 16, v106
	v_and_b32_e32 v111, 0xffff0000, v106
	v_lshlrev_b32_e32 v106, 16, v107
	v_and_b32_e32 v107, 0xffff0000, v107
	v_pk_fma_f32 v[104:105], v[104:105], v[146:147], v[106:107]
	v_lshlrev_b32_e32 v106, 16, v108
	v_and_b32_e32 v107, 0xffff0000, v108
	v_pk_fma_f32 v[106:107], v[98:99], v[144:145], v[106:107]
	v_lshlrev_b32_e32 v98, 16, v109
	v_and_b32_e32 v99, 0xffff0000, v109
	v_pk_fma_f32 v[102:103], v[102:103], v[148:149], v[110:111]
	v_pk_fma_f32 v[108:109], v[100:101], v[142:143], v[98:99]
	v_cvt_pk_bf16_f32 v98, v102, v103
	v_cvt_pk_bf16_f32 v99, v104, v105
	v_cvt_pk_bf16_f32 v100, v106, v107
	v_cvt_pk_bf16_f32 v101, v108, v109
	global_store_dwordx4 v[118:119], v[98:101], off offset:2304
	s_nop 1
	v_or_b32_e32 v98, 32, v162
	v_ashrrev_i32_e32 v99, 31, v98
	v_lshlrev_b64 v[98:99], 12, v[98:99]
	v_lshl_add_u64 v[98:99], s[8:9], 0, v[98:99]
	v_lshl_add_u64 v[102:103], v[98:99], 0, v[160:161]
	global_load_dwordx4 v[98:101], v[102:103], off offset:2048
	s_waitcnt vmcnt(0)
	v_lshlrev_b32_e32 v104, 16, v98
	v_and_b32_e32 v105, 0xffff0000, v98
	v_lshlrev_b32_e32 v98, 16, v99
	v_and_b32_e32 v99, 0xffff0000, v99
	v_pk_fma_f32 v[96:97], v[96:97], v[152:153], v[98:99]
	v_lshlrev_b32_e32 v98, 16, v100
	v_and_b32_e32 v99, 0xffff0000, v100
	v_pk_fma_f32 v[98:99], v[90:91], v[154:155], v[98:99]
	v_lshlrev_b32_e32 v90, 16, v101
	v_and_b32_e32 v91, 0xffff0000, v101
	v_pk_fma_f32 v[94:95], v[94:95], v[156:157], v[104:105]
	v_pk_fma_f32 v[100:101], v[92:93], v[150:151], v[90:91]
	v_cvt_pk_bf16_f32 v90, v94, v95
	v_cvt_pk_bf16_f32 v91, v96, v97
	v_cvt_pk_bf16_f32 v92, v98, v99
	v_cvt_pk_bf16_f32 v93, v100, v101
	global_store_dwordx4 v[102:103], v[90:93], off offset:2048
	global_load_dwordx4 v[90:93], v[102:103], off offset:2304
	s_waitcnt vmcnt(0)
	v_lshlrev_b32_e32 v94, 16, v90
	v_and_b32_e32 v95, 0xffff0000, v90
	v_lshlrev_b32_e32 v90, 16, v91
	v_and_b32_e32 v91, 0xffff0000, v91
	v_pk_fma_f32 v[88:89], v[88:89], v[146:147], v[90:91]
	v_lshlrev_b32_e32 v90, 16, v92
	v_and_b32_e32 v91, 0xffff0000, v92
	v_pk_fma_f32 v[90:91], v[82:83], v[144:145], v[90:91]
	v_lshlrev_b32_e32 v82, 16, v93
	v_and_b32_e32 v83, 0xffff0000, v93
	v_pk_fma_f32 v[86:87], v[86:87], v[148:149], v[94:95]
	v_pk_fma_f32 v[92:93], v[84:85], v[142:143], v[82:83]
	v_cvt_pk_bf16_f32 v82, v86, v87
	v_cvt_pk_bf16_f32 v83, v88, v89
	v_cvt_pk_bf16_f32 v84, v90, v91
	v_cvt_pk_bf16_f32 v85, v92, v93
	global_store_dwordx4 v[102:103], v[82:85], off offset:2304
	s_nop 1
	v_or_b32_e32 v82, 48, v162
	v_ashrrev_i32_e32 v83, 31, v82
	v_lshlrev_b64 v[82:83], 12, v[82:83]
	v_lshl_add_u64 v[82:83], s[8:9], 0, v[82:83]
	v_lshl_add_u64 v[82:83], v[82:83], 0, v[160:161]
	global_load_dwordx4 v[84:87], v[82:83], off offset:2048
	s_waitcnt vmcnt(0)
	v_lshlrev_b32_e32 v88, 16, v84
	v_and_b32_e32 v89, 0xffff0000, v84
	v_lshlrev_b32_e32 v84, 16, v85
	v_and_b32_e32 v85, 0xffff0000, v85
	v_pk_fma_f32 v[80:81], v[80:81], v[152:153], v[84:85]
	v_lshlrev_b32_e32 v84, 16, v86
	v_and_b32_e32 v85, 0xffff0000, v86
	v_pk_fma_f32 v[84:85], v[74:75], v[154:155], v[84:85]
	v_lshlrev_b32_e32 v74, 16, v87
	v_and_b32_e32 v75, 0xffff0000, v87
	v_pk_fma_f32 v[78:79], v[78:79], v[156:157], v[88:89]
	v_pk_fma_f32 v[86:87], v[76:77], v[150:151], v[74:75]
	v_cvt_pk_bf16_f32 v74, v78, v79
	v_cvt_pk_bf16_f32 v75, v80, v81
	v_cvt_pk_bf16_f32 v76, v84, v85
	v_cvt_pk_bf16_f32 v77, v86, v87
	global_store_dwordx4 v[82:83], v[74:77], off offset:2048
	global_load_dwordx4 v[74:77], v[82:83], off offset:2304
	s_waitcnt vmcnt(0)
	v_lshlrev_b32_e32 v78, 16, v74
	v_and_b32_e32 v79, 0xffff0000, v74
	v_lshlrev_b32_e32 v74, 16, v75
	v_and_b32_e32 v75, 0xffff0000, v75
	v_pk_fma_f32 v[72:73], v[72:73], v[146:147], v[74:75]
	v_lshlrev_b32_e32 v74, 16, v76
	v_and_b32_e32 v75, 0xffff0000, v76
	v_pk_fma_f32 v[74:75], v[66:67], v[144:145], v[74:75]
	v_lshlrev_b32_e32 v66, 16, v77
	v_and_b32_e32 v67, 0xffff0000, v77
	v_pk_fma_f32 v[70:71], v[70:71], v[148:149], v[78:79]
	v_pk_fma_f32 v[76:77], v[68:69], v[142:143], v[66:67]
	v_cvt_pk_bf16_f32 v66, v70, v71
	v_cvt_pk_bf16_f32 v67, v72, v73
	v_cvt_pk_bf16_f32 v68, v74, v75
	v_cvt_pk_bf16_f32 v69, v76, v77
	v_lshl_add_u64 v[70:71], v[158:159], 0, s[6:7]
	global_store_dwordx4 v[82:83], v[66:69], off offset:2304
	global_load_dwordx4 v[66:69], v[70:71], off offset:2048
	s_mov_b64 s[6:7], 0x90000
	s_waitcnt vmcnt(0)
	v_lshlrev_b32_e32 v72, 16, v66
	v_and_b32_e32 v73, 0xffff0000, v66
	v_lshlrev_b32_e32 v66, 16, v67
	v_and_b32_e32 v67, 0xffff0000, v67
	v_pk_fma_f32 v[64:65], v[64:65], v[152:153], v[66:67]
	v_lshlrev_b32_e32 v66, 16, v68
	v_and_b32_e32 v67, 0xffff0000, v68
	v_pk_fma_f32 v[66:67], v[58:59], v[154:155], v[66:67]
	v_lshlrev_b32_e32 v58, 16, v69
	v_and_b32_e32 v59, 0xffff0000, v69
	v_pk_fma_f32 v[62:63], v[62:63], v[156:157], v[72:73]
	v_pk_fma_f32 v[68:69], v[60:61], v[150:151], v[58:59]
	v_cvt_pk_bf16_f32 v58, v62, v63
	v_cvt_pk_bf16_f32 v59, v64, v65
	v_cvt_pk_bf16_f32 v60, v66, v67
	v_cvt_pk_bf16_f32 v61, v68, v69
	global_store_dwordx4 v[70:71], v[58:61], off offset:2048
	global_load_dwordx4 v[58:61], v[70:71], off offset:2304
	s_waitcnt vmcnt(0)
	v_lshlrev_b32_e32 v62, 16, v58
	v_and_b32_e32 v63, 0xffff0000, v58
	v_lshlrev_b32_e32 v58, 16, v59
	v_and_b32_e32 v59, 0xffff0000, v59
	v_pk_fma_f32 v[56:57], v[56:57], v[146:147], v[58:59]
	v_lshlrev_b32_e32 v58, 16, v60
	v_and_b32_e32 v59, 0xffff0000, v60
	v_pk_fma_f32 v[58:59], v[50:51], v[144:145], v[58:59]
	v_lshlrev_b32_e32 v50, 16, v61
	v_and_b32_e32 v51, 0xffff0000, v61
	v_pk_fma_f32 v[54:55], v[54:55], v[148:149], v[62:63]
	v_pk_fma_f32 v[60:61], v[52:53], v[142:143], v[50:51]
	v_cvt_pk_bf16_f32 v50, v54, v55
	v_cvt_pk_bf16_f32 v51, v56, v57
	v_cvt_pk_bf16_f32 v52, v58, v59
	v_cvt_pk_bf16_f32 v53, v60, v61
	v_lshl_add_u64 v[54:55], v[158:159], 0, s[6:7]
	global_store_dwordx4 v[70:71], v[50:53], off offset:2304
	global_load_dwordx4 v[50:53], v[54:55], off offset:2048
	s_mov_b64 s[6:7], 0xa0000
	s_waitcnt vmcnt(0)
	v_lshlrev_b32_e32 v56, 16, v50
	v_and_b32_e32 v57, 0xffff0000, v50
	v_lshlrev_b32_e32 v50, 16, v51
	v_and_b32_e32 v51, 0xffff0000, v51
	v_pk_fma_f32 v[48:49], v[48:49], v[152:153], v[50:51]
	v_lshlrev_b32_e32 v50, 16, v52
	v_and_b32_e32 v51, 0xffff0000, v52
	v_pk_fma_f32 v[50:51], v[42:43], v[154:155], v[50:51]
	v_lshlrev_b32_e32 v42, 16, v53
	v_and_b32_e32 v43, 0xffff0000, v53
	v_pk_fma_f32 v[46:47], v[46:47], v[156:157], v[56:57]
	v_pk_fma_f32 v[52:53], v[44:45], v[150:151], v[42:43]
	v_cvt_pk_bf16_f32 v42, v46, v47
	v_cvt_pk_bf16_f32 v43, v48, v49
	v_cvt_pk_bf16_f32 v44, v50, v51
	v_cvt_pk_bf16_f32 v45, v52, v53
	global_store_dwordx4 v[54:55], v[42:45], off offset:2048
	global_load_dwordx4 v[42:45], v[54:55], off offset:2304
	s_waitcnt vmcnt(0)
	v_lshlrev_b32_e32 v46, 16, v42
	v_and_b32_e32 v47, 0xffff0000, v42
	v_lshlrev_b32_e32 v42, 16, v43
	v_and_b32_e32 v43, 0xffff0000, v43
	v_pk_fma_f32 v[40:41], v[40:41], v[146:147], v[42:43]
	v_lshlrev_b32_e32 v42, 16, v44
	v_and_b32_e32 v43, 0xffff0000, v44
	v_pk_fma_f32 v[42:43], v[34:35], v[144:145], v[42:43]
	v_lshlrev_b32_e32 v34, 16, v45
	v_and_b32_e32 v35, 0xffff0000, v45
	v_pk_fma_f32 v[38:39], v[38:39], v[148:149], v[46:47]
	v_pk_fma_f32 v[44:45], v[36:37], v[142:143], v[34:35]
	v_cvt_pk_bf16_f32 v34, v38, v39
	v_cvt_pk_bf16_f32 v35, v40, v41
	v_cvt_pk_bf16_f32 v36, v42, v43
	v_cvt_pk_bf16_f32 v37, v44, v45
	v_lshl_add_u64 v[38:39], v[158:159], 0, s[6:7]
	global_store_dwordx4 v[54:55], v[34:37], off offset:2304
	global_load_dwordx4 v[34:37], v[38:39], off offset:2048
	s_mov_b64 s[6:7], 0xb0000
	s_waitcnt vmcnt(0)
	v_lshlrev_b32_e32 v40, 16, v34
	v_and_b32_e32 v41, 0xffff0000, v34
	v_lshlrev_b32_e32 v34, 16, v35
	v_and_b32_e32 v35, 0xffff0000, v35
	v_pk_fma_f32 v[32:33], v[32:33], v[152:153], v[34:35]
	v_lshlrev_b32_e32 v34, 16, v36
	v_and_b32_e32 v35, 0xffff0000, v36
	v_pk_fma_f32 v[34:35], v[26:27], v[154:155], v[34:35]
	v_lshlrev_b32_e32 v26, 16, v37
	v_and_b32_e32 v27, 0xffff0000, v37
	v_pk_fma_f32 v[30:31], v[30:31], v[156:157], v[40:41]
	v_pk_fma_f32 v[36:37], v[28:29], v[150:151], v[26:27]
	v_cvt_pk_bf16_f32 v26, v30, v31
	v_cvt_pk_bf16_f32 v27, v32, v33
	v_cvt_pk_bf16_f32 v28, v34, v35
	v_cvt_pk_bf16_f32 v29, v36, v37
	global_store_dwordx4 v[38:39], v[26:29], off offset:2048
	global_load_dwordx4 v[26:29], v[38:39], off offset:2304
	s_waitcnt vmcnt(0)
	v_lshlrev_b32_e32 v30, 16, v26
	v_and_b32_e32 v31, 0xffff0000, v26
	v_lshlrev_b32_e32 v26, 16, v27
	v_and_b32_e32 v27, 0xffff0000, v27
	v_pk_fma_f32 v[24:25], v[24:25], v[146:147], v[26:27]
	v_lshlrev_b32_e32 v26, 16, v28
	v_and_b32_e32 v27, 0xffff0000, v28
	v_pk_fma_f32 v[26:27], v[18:19], v[144:145], v[26:27]
	v_lshlrev_b32_e32 v18, 16, v29
	v_and_b32_e32 v19, 0xffff0000, v29
	v_pk_fma_f32 v[22:23], v[22:23], v[148:149], v[30:31]
	v_pk_fma_f32 v[28:29], v[20:21], v[142:143], v[18:19]
	v_cvt_pk_bf16_f32 v18, v22, v23
	v_cvt_pk_bf16_f32 v19, v24, v25
	v_cvt_pk_bf16_f32 v20, v26, v27
	v_cvt_pk_bf16_f32 v21, v28, v29
	global_store_dwordx4 v[38:39], v[18:21], off offset:2304
	s_nop 1
	v_lshl_add_u64 v[18:19], v[158:159], 0, s[6:7]
	global_load_dwordx4 v[20:23], v[18:19], off offset:2048
	s_waitcnt vmcnt(0)
	v_lshlrev_b32_e32 v24, 16, v20
	v_and_b32_e32 v25, 0xffff0000, v20
	v_lshlrev_b32_e32 v20, 16, v21
	v_and_b32_e32 v21, 0xffff0000, v21
	v_pk_fma_f32 v[16:17], v[16:17], v[152:153], v[20:21]
	v_lshlrev_b32_e32 v20, 16, v22
	v_and_b32_e32 v21, 0xffff0000, v22
	v_pk_fma_f32 v[20:21], v[10:11], v[154:155], v[20:21]
	v_lshlrev_b32_e32 v10, 16, v23
	v_and_b32_e32 v11, 0xffff0000, v23
	v_pk_fma_f32 v[14:15], v[14:15], v[156:157], v[24:25]
	v_pk_fma_f32 v[22:23], v[12:13], v[150:151], v[10:11]
	v_cvt_pk_bf16_f32 v10, v14, v15
	v_cvt_pk_bf16_f32 v11, v16, v17
	v_cvt_pk_bf16_f32 v12, v20, v21
	v_cvt_pk_bf16_f32 v13, v22, v23
	global_store_dwordx4 v[18:19], v[10:13], off offset:2048
	global_load_dwordx4 v[10:13], v[18:19], off offset:2304
	s_waitcnt vmcnt(0)
	v_lshlrev_b32_e32 v14, 16, v10
	v_and_b32_e32 v15, 0xffff0000, v10
	v_lshlrev_b32_e32 v10, 16, v11
	v_and_b32_e32 v11, 0xffff0000, v11
	v_pk_fma_f32 v[8:9], v[8:9], v[146:147], v[10:11]
	v_lshlrev_b32_e32 v10, 16, v12
	v_and_b32_e32 v11, 0xffff0000, v12
	v_pk_fma_f32 v[10:11], v[2:3], v[144:145], v[10:11]
	v_lshlrev_b32_e32 v2, 16, v13
	v_and_b32_e32 v3, 0xffff0000, v13
	v_pk_fma_f32 v[6:7], v[6:7], v[148:149], v[14:15]
	v_pk_fma_f32 v[12:13], v[4:5], v[142:143], v[2:3]
	v_cvt_pk_bf16_f32 v2, v6, v7
	v_cvt_pk_bf16_f32 v3, v8, v9
	v_cvt_pk_bf16_f32 v4, v10, v11
	v_cvt_pk_bf16_f32 v5, v12, v13
	global_store_dwordx4 v[18:19], v[2:5], off offset:2304
	s_cbranch_vccz .LBB0_1399
	s_waitcnt vmcnt(0)
	s_cmpk_gt_u32 s22, 0xff
	s_cbranch_scc1 .LBB0_1412
	s_barrier
